# pairing + peel + epilogue edits, K-loop barriers left at original positions (no early barrier)
# baseline (speedup 1.0000x reference)
;     __device__ bool next(int i, Unit& u) const { if (i >= 2) return false; const int x = c & 7, j = c >> 3; u.pm = 32 * i + 4 * x + (j & 3); u.pn = j >> 2; return true; }
; #define PG8_STAGE(bufoff, gbase, voff) do { _Pragma("unroll") for (int _i = 0; _i < 2; ++_i) \
;         __builtin_amdgcn_global_load_lds((const unsigned*)((const char*)(gbase) + (voff)[_i]), (LAS unsigned*)(lds + (bufoff) + ldsw + _i * 8192), 16, 0, 0); } while (0)
; #define PG8_LDA(dst, b, h) do { _Pragma("unroll") for (int m = 0; m < 4; ++m) _Pragma("unroll") for (int k = 0; k < 2; ++k) dst[m][k] = *(const LAS bf16x8*)(lds + PG8_SA(b, h) + aoff + m * 2048 + k * 1024); } while (0)
; #define PG8_LDB(dst, b, h) do { _Pragma("unroll") for (int n = 0; n < 2; ++n) _Pragma("unroll") for (int k = 0; k < 2; ++k) dst[n][k] = *(const LAS bf16x8*)(lds + PG8_SB(b, h) + boff + n * 2048 + k * 1024); } while (0)
; #define PG8_WAIT_V(n) asm volatile("s_waitcnt vmcnt(" #n ")" ::: "memory")
; #define PG8_WAIT_L(n) asm volatile("s_waitcnt lgkmcnt(" #n ")" ::: "memory")
; #define PG8_BAR __builtin_amdgcn_s_barrier()
; template <class Epi, class Sched, bool ALIGN_EPI = true>
; __device__ __forceinline__ void gemm_phase(LAS unsigned char* lds, const Gemm g, const Sched& S, const Epi& E) {
;     ...
;         const bool has_next = S.next(ui + 1, nxt);
;         const char* nA = has_next ? (const char*)g.A + ((size_t)nxt.pm * BM * g.lda + (size_t)nxt.pn * g.a_pn_off) * 2 : cA; const char* nB = has_next ? (const char*)g.Bt + (size_t)nxt.pn * BM * g.ldb * 2 : cB;
;         for (int t = 0; t < nt; t += 2) {
;             const bool last = (t == nt - 2);
;             const char* a1 = cA + (size_t)(t + 1) * kstep;
;             const char* a2 = last ? nA : cA + (size_t)(t + 2) * kstep; const char* b2 = last ? nB : cB + (size_t)(t + 2) * kstep;
;             const char* a3 = a2 + kstep; const char* b3 = b2 + kstep;
;             PG8_LDB(B0, 0, 0); PG8_LDB(B1, 0, 1); PG8_SCHED; PG8_LDA(At, 0, 0); PG8_STAGE(PG8_SA(1, 1), a1 + hA, voffA);
;             PG8_WAIT_V(8); PG8_WAIT_L(0); PG8_BAR; PG8_MMA(0, 0, At, B0); PG8_MMA(0, 1, At, B1); PG8_BAR; PG8_SCHED;
;             PG8_LDA(At, 0, 1); PG8_STAGE(PG8_SB(0, 0), b2, voffB); PG8_STAGE(PG8_SB(0, 1), b2 + hB, voffB); PG8_STAGE(PG8_SA(0, 0), a2, voffA);
;             PG8_WAIT_V(8); PG8_WAIT_L(0); PG8_BAR; PG8_MMA(1, 0, At, B0); PG8_MMA(1, 1, At, B1); PG8_BAR; PG8_SCHED;
.LBB0_76:
	s_ashr_i32 s15, s14, 31
	s_lshl_b64 s[18:19], s[14:15], 20
	s_add_u32 s38, s46, s18
	s_addc_u32 s39, s47, s19
	s_and_b64 s[18:19], s[4:5], exec
	s_cselect_b32 s15, s39, s7
	s_cselect_b32 s17, s38, s6
	s_ashr_i32 s13, s12, 31
	s_lshl_b64 s[18:19], s[12:13], 20
	s_add_u32 s40, s53, s18
	s_addc_u32 s41, s58, s19
	s_and_b64 s[18:19], s[4:5], exec
	s_cselect_b32 s13, s41, s43
	s_cselect_b32 s18, s40, s42
	s_add_u32 s6, s6, 0x80080
	s_addc_u32 s7, s7, 0
	s_add_u32 s19, s42, 0x100
	s_addc_u32 s24, s43, 0
	s_mov_b32 s25, -2
	s_add_u32 s26, s6, 0xfff80080
	s_addc_u32 s27, s7, -1
	s_add_i32 s30, 0, 0x10000
	s_cmp_eq_u32 s25, 28
	s_cselect_b32 s45, s15, s27
	s_cselect_b32 s44, s17, s26
	s_cselect_b32 s43, s13, s24
	s_cselect_b32 s42, s18, s19
	s_add_i32 s31, 0, 0x14000
	v_add_u32_e32 v144, s30, v166
	v_add_u32_e32 v156, s31, v166
	ds_read_b128 v[132:135], v144
	ds_read_b128 v[136:139], v144 offset:1024
	ds_read_b128 v[140:143], v144 offset:2048
	ds_read_b128 v[144:147], v144 offset:3072
	ds_read_b128 v[170:173], v156
	ds_read_b128 v[174:177], v156 offset:1024
	ds_read_b128 v[178:181], v156 offset:2048
	ds_read_b128 v[182:185], v156 offset:3072
	v_lshl_add_u64 v[156:157], s[6:7], 0, v[152:153]
	s_add_i32 m0, s60, 0xc000
	ds_read_b128 v[186:189], v168
	ds_read_b128 v[190:193], v168 offset:1024
	ds_read_b128 v[194:197], v168 offset:2048
	ds_read_b128 v[204:207], v168 offset:3072
	ds_read_b128 v[208:211], v168 offset:4096
	ds_read_b128 v[212:215], v168 offset:5120
	ds_read_b128 v[216:219], v168 offset:6144
	ds_read_b128 v[220:223], v168 offset:7168
	global_load_lds_dwordx4 v[156:157], off
	v_lshl_add_u64 v[156:157], s[6:7], 0, v[154:155]
	s_add_i32 m0, s60, 0xe000
	s_nop 0
	global_load_lds_dwordx4 v[156:157], off
	s_waitcnt vmcnt(8)
	s_waitcnt lgkmcnt(0)
	s_barrier
	s_setprio 1
	s_waitcnt lgkmcnt(0)
	v_mfma_f32_16x16x32_bf16 v[128:131], v[132:135], v[186:189], 0
	v_mfma_f32_16x16x32_bf16 v[128:131], v[136:139], v[190:193], v[128:131]
	v_mfma_f32_16x16x32_bf16 v[124:127], v[140:143], v[186:189], 0
	v_mfma_f32_16x16x32_bf16 v[124:127], v[144:147], v[190:193], v[124:127]
	v_mfma_f32_16x16x32_bf16 v[116:119], v[132:135], v[194:197], 0
	v_mfma_f32_16x16x32_bf16 v[116:119], v[136:139], v[204:207], v[116:119]
	v_mfma_f32_16x16x32_bf16 v[112:115], v[140:143], v[194:197], 0
	v_mfma_f32_16x16x32_bf16 v[112:115], v[144:147], v[204:207], v[112:115]
	v_mfma_f32_16x16x32_bf16 v[104:107], v[132:135], v[208:211], 0
	v_mfma_f32_16x16x32_bf16 v[104:107], v[136:139], v[212:215], v[104:107]
	v_mfma_f32_16x16x32_bf16 v[96:99], v[140:143], v[208:211], 0
	v_mfma_f32_16x16x32_bf16 v[96:99], v[144:147], v[212:215], v[96:99]
	v_mfma_f32_16x16x32_bf16 v[88:91], v[132:135], v[216:219], 0
	v_mfma_f32_16x16x32_bf16 v[88:91], v[136:139], v[220:223], v[88:91]
	v_mfma_f32_16x16x32_bf16 v[80:83], v[140:143], v[216:219], 0
	v_mfma_f32_16x16x32_bf16 v[80:83], v[144:147], v[220:223], v[80:83]
	s_setprio 0
	s_setprio 1
	v_mfma_f32_16x16x32_bf16 v[120:123], v[170:173], v[186:189], 0
	v_mfma_f32_16x16x32_bf16 v[120:123], v[174:177], v[190:193], v[120:123]
	v_mfma_f32_16x16x32_bf16 v[108:111], v[178:181], v[186:189], 0
	v_mfma_f32_16x16x32_bf16 v[108:111], v[182:185], v[190:193], v[108:111]
	v_mfma_f32_16x16x32_bf16 v[100:103], v[170:173], v[194:197], 0
	v_mfma_f32_16x16x32_bf16 v[100:103], v[174:177], v[204:207], v[100:103]
	v_mfma_f32_16x16x32_bf16 v[92:95], v[178:181], v[194:197], 0
	v_mfma_f32_16x16x32_bf16 v[92:95], v[182:185], v[204:207], v[92:95]
	v_mfma_f32_16x16x32_bf16 v[84:87], v[170:173], v[208:211], 0
	v_mfma_f32_16x16x32_bf16 v[84:87], v[174:177], v[212:215], v[84:87]
	v_mfma_f32_16x16x32_bf16 v[76:79], v[178:181], v[208:211], 0
	v_mfma_f32_16x16x32_bf16 v[76:79], v[182:185], v[212:215], v[76:79]
	v_mfma_f32_16x16x32_bf16 v[72:75], v[170:173], v[216:219], 0
	v_mfma_f32_16x16x32_bf16 v[72:75], v[174:177], v[220:223], v[72:75]
	v_mfma_f32_16x16x32_bf16 v[68:71], v[178:181], v[216:219], 0
	v_mfma_f32_16x16x32_bf16 v[68:71], v[182:185], v[220:223], v[68:71]
	s_setprio 0
	s_barrier
	s_add_i32 s26, s30, s59
	v_lshl_add_u64 v[156:157], s[42:43], 0, v[2:3]
	s_mov_b32 m0, s26
	ds_read_b128 v[186:189], v168 offset:16384
	ds_read_b128 v[190:193], v168 offset:17408
	ds_read_b128 v[194:197], v168 offset:18432
	ds_read_b128 v[204:207], v168 offset:19456
	ds_read_b128 v[208:211], v168 offset:20480
	ds_read_b128 v[212:215], v168 offset:21504
	ds_read_b128 v[216:219], v168 offset:22528
	ds_read_b128 v[220:223], v168 offset:23552
	global_load_lds_dwordx4 v[156:157], off
	s_add_i32 m0, s26, 0x2000
	s_add_u32 s26, s42, 0x80000
	v_lshl_add_u64 v[164:165], s[42:43], 0, v[0:1]
	s_addc_u32 s27, s43, 0
	s_add_i32 s30, s31, s59
	global_load_lds_dwordx4 v[164:165], off
	v_lshl_add_u64 v[224:225], s[26:27], 0, v[2:3]
	s_mov_b32 m0, s30
	v_lshl_add_u64 v[226:227], s[44:45], 0, v[148:149]
	global_load_lds_dwordx4 v[224:225], off
	v_lshl_add_u64 v[224:225], s[26:27], 0, v[0:1]
	s_add_i32 m0, s30, 0x2000
	s_nop 0
	global_load_lds_dwordx4 v[224:225], off
	v_lshl_add_u64 v[224:225], s[44:45], 0, v[150:151]
	s_mov_b32 m0, s60
	s_nop 0
	global_load_lds_dwordx4 v[224:225], off
	s_mov_b32 m0, s61
	s_nop 0
	global_load_lds_dwordx4 v[226:227], off
	s_waitcnt vmcnt(8)
	s_waitcnt lgkmcnt(0)
	s_barrier
; #define PG8_STAGE(bufoff, gbase, voff) do { _Pragma("unroll") for (int _i = 0; _i < 2; ++_i) \
;         __builtin_amdgcn_global_load_lds((const unsigned*)((const char*)(gbase) + (voff)[_i]), (LAS unsigned*)(lds + (bufoff) + ldsw + _i * 8192), 16, 0, 0); } while (0)
; #define PG8_LDA(dst, b, h) do { _Pragma("unroll") for (int m = 0; m < 4; ++m) _Pragma("unroll") for (int k = 0; k < 2; ++k) dst[m][k] = *(const LAS bf16x8*)(lds + PG8_SA(b, h) + aoff + m * 2048 + k * 1024); } while (0)
; #define PG8_LDB(dst, b, h) do { _Pragma("unroll") for (int n = 0; n < 2; ++n) _Pragma("unroll") for (int k = 0; k < 2; ++k) dst[n][k] = *(const LAS bf16x8*)(lds + PG8_SB(b, h) + boff + n * 2048 + k * 1024); } while (0)
; #define PG8_MMA(ai, bj, At, Bt) do { __builtin_amdgcn_s_setprio(1); _Pragma("unroll") for (int m = 0; m < 4; ++m) _Pragma("unroll") for (int n = 0; n < 2; ++n) _Pragma("unroll") for (int k = 0; k < 2; ++k) \
;         acc[ai][bj][m][n] = __builtin_amdgcn_mfma_f32_16x16x32_bf16(Bt[n][k], At[m][k], acc[ai][bj][m][n], 0, 0, 0); __builtin_amdgcn_s_setprio(0); } while (0)
; #define PG8_WAIT_V(n) asm volatile("s_waitcnt vmcnt(" #n ")" ::: "memory")
; #define PG8_WAIT_L(n) asm volatile("s_waitcnt lgkmcnt(" #n ")" ::: "memory")
; #define PG8_BAR __builtin_amdgcn_s_barrier()
; #define PG8_SCHED __builtin_amdgcn_sched_barrier(0)
; template <class Epi, class Sched, bool ALIGN_EPI = true>
; __device__ __forceinline__ void gemm_phase(LAS unsigned char* lds, const Gemm g, const Sched& S, const Epi& E) {
;     ...
;             PG8_WAIT_V(8); PG8_WAIT_L(0); PG8_BAR; PG8_MMA(1, 0, At, B0); PG8_MMA(1, 1, At, B1); PG8_BAR; PG8_SCHED;
;             PG8_LDB(B0, 1, 0); PG8_LDB(B1, 1, 1); PG8_SCHED; PG8_LDA(At, 1, 0); PG8_STAGE(PG8_SA(0, 1), a2 + hA, voffA);
;             PG8_WAIT_V(8); PG8_WAIT_L(0); PG8_BAR; PG8_MMA(0, 0, At, B0); PG8_MMA(0, 1, At, B1); PG8_BAR; PG8_SCHED;
;             PG8_LDA(At, 1, 1); PG8_STAGE(PG8_SB(1, 0), b3, voffB); PG8_STAGE(PG8_SB(1, 1), b3 + hB, voffB); PG8_STAGE(PG8_SA(1, 0), a3, voffA);
;             PG8_WAIT_V(8); PG8_WAIT_L(0); PG8_BAR; PG8_MMA(1, 0, At, B0); PG8_MMA(1, 1, At, B1); PG8_BAR; PG8_SCHED;
	s_setprio 1
	s_waitcnt lgkmcnt(0)
	v_mfma_f32_16x16x32_bf16 v[64:67], v[132:135], v[186:189], 0
	v_mfma_f32_16x16x32_bf16 v[64:67], v[136:139], v[190:193], v[64:67]
	v_mfma_f32_16x16x32_bf16 v[60:63], v[140:143], v[186:189], 0
	v_mfma_f32_16x16x32_bf16 v[60:63], v[144:147], v[190:193], v[60:63]
	v_mfma_f32_16x16x32_bf16 v[56:59], v[132:135], v[194:197], 0
	v_mfma_f32_16x16x32_bf16 v[56:59], v[136:139], v[204:207], v[56:59]
	v_mfma_f32_16x16x32_bf16 v[48:51], v[140:143], v[194:197], 0
	v_mfma_f32_16x16x32_bf16 v[48:51], v[144:147], v[204:207], v[48:51]
	v_mfma_f32_16x16x32_bf16 v[40:43], v[132:135], v[208:211], 0
	v_mfma_f32_16x16x32_bf16 v[40:43], v[136:139], v[212:215], v[40:43]
	v_mfma_f32_16x16x32_bf16 v[32:35], v[140:143], v[208:211], 0
	v_mfma_f32_16x16x32_bf16 v[32:35], v[144:147], v[212:215], v[32:35]
	v_mfma_f32_16x16x32_bf16 v[24:27], v[132:135], v[216:219], 0
	v_mfma_f32_16x16x32_bf16 v[24:27], v[136:139], v[220:223], v[24:27]
	v_mfma_f32_16x16x32_bf16 v[16:19], v[140:143], v[216:219], 0
	v_mfma_f32_16x16x32_bf16 v[16:19], v[144:147], v[220:223], v[16:19]
	s_setprio 0
	s_setprio 1
	v_mfma_f32_16x16x32_bf16 v[52:55], v[170:173], v[186:189], 0
	v_mfma_f32_16x16x32_bf16 v[52:55], v[174:177], v[190:193], v[52:55]
	v_mfma_f32_16x16x32_bf16 v[44:47], v[178:181], v[186:189], 0
	v_mfma_f32_16x16x32_bf16 v[44:47], v[182:185], v[190:193], v[44:47]
	v_mfma_f32_16x16x32_bf16 v[36:39], v[170:173], v[194:197], 0
	v_mfma_f32_16x16x32_bf16 v[36:39], v[174:177], v[204:207], v[36:39]
	v_mfma_f32_16x16x32_bf16 v[28:31], v[178:181], v[194:197], 0
	v_mfma_f32_16x16x32_bf16 v[28:31], v[182:185], v[204:207], v[28:31]
	v_mfma_f32_16x16x32_bf16 v[20:23], v[170:173], v[208:211], 0
	v_mfma_f32_16x16x32_bf16 v[20:23], v[174:177], v[212:215], v[20:23]
	v_mfma_f32_16x16x32_bf16 v[12:15], v[178:181], v[208:211], 0
	v_mfma_f32_16x16x32_bf16 v[12:15], v[182:185], v[212:215], v[12:15]
	v_mfma_f32_16x16x32_bf16 v[8:11], v[170:173], v[216:219], 0
	v_mfma_f32_16x16x32_bf16 v[8:11], v[174:177], v[220:223], v[8:11]
	v_mfma_f32_16x16x32_bf16 v[4:7], v[178:181], v[216:219], 0
	v_mfma_f32_16x16x32_bf16 v[4:7], v[182:185], v[220:223], v[4:7]
	s_setprio 0
	s_barrier
	s_add_i32 s30, 0, 0x18000
	s_add_i32 s31, 0, 0x1c000
	v_add_u32_e32 v144, s30, v166
	v_add_u32_e32 v160, s31, v166
	ds_read_b128 v[132:135], v144
	ds_read_b128 v[136:139], v144 offset:1024
	ds_read_b128 v[140:143], v144 offset:2048
	ds_read_b128 v[144:147], v144 offset:3072
	ds_read_b128 v[170:173], v160
	ds_read_b128 v[174:177], v160 offset:1024
	ds_read_b128 v[178:181], v160 offset:2048
	ds_read_b128 v[182:185], v160 offset:3072
	s_add_u32 s26, s44, 0x80000
	s_addc_u32 s27, s45, 0
	s_mov_b32 m0, s62
	v_lshl_add_u64 v[228:229], s[26:27], 0, v[150:151]
	ds_read_b128 v[186:189], v168 offset:32768
	ds_read_b128 v[190:193], v168 offset:33792
	ds_read_b128 v[194:197], v168 offset:34816
	ds_read_b128 v[204:207], v168 offset:35840
	ds_read_b128 v[208:211], v168 offset:36864
	ds_read_b128 v[212:215], v168 offset:37888
	ds_read_b128 v[216:219], v168 offset:38912
	ds_read_b128 v[220:223], v168 offset:39936
	global_load_lds_dwordx4 v[228:229], off
	v_lshl_add_u64 v[228:229], s[26:27], 0, v[148:149]
	s_mov_b32 m0, s63
	s_nop 0
	global_load_lds_dwordx4 v[228:229], off
	s_waitcnt vmcnt(8)
	s_waitcnt lgkmcnt(0)
	s_barrier
	s_setprio 1
	s_waitcnt lgkmcnt(0)
	v_mfma_f32_16x16x32_bf16 v[128:131], v[132:135], v[186:189], v[128:131]
	v_mfma_f32_16x16x32_bf16 v[128:131], v[136:139], v[190:193], v[128:131]
	v_mfma_f32_16x16x32_bf16 v[124:127], v[140:143], v[186:189], v[124:127]
	v_mfma_f32_16x16x32_bf16 v[124:127], v[144:147], v[190:193], v[124:127]
	v_mfma_f32_16x16x32_bf16 v[116:119], v[132:135], v[194:197], v[116:119]
	v_mfma_f32_16x16x32_bf16 v[116:119], v[136:139], v[204:207], v[116:119]
	v_mfma_f32_16x16x32_bf16 v[112:115], v[140:143], v[194:197], v[112:115]
	v_mfma_f32_16x16x32_bf16 v[112:115], v[144:147], v[204:207], v[112:115]
	v_mfma_f32_16x16x32_bf16 v[104:107], v[132:135], v[208:211], v[104:107]
	v_mfma_f32_16x16x32_bf16 v[104:107], v[136:139], v[212:215], v[104:107]
	v_mfma_f32_16x16x32_bf16 v[96:99], v[140:143], v[208:211], v[96:99]
	v_mfma_f32_16x16x32_bf16 v[96:99], v[144:147], v[212:215], v[96:99]
	v_mfma_f32_16x16x32_bf16 v[88:91], v[132:135], v[216:219], v[88:91]
	v_mfma_f32_16x16x32_bf16 v[88:91], v[136:139], v[220:223], v[88:91]
	v_mfma_f32_16x16x32_bf16 v[80:83], v[140:143], v[216:219], v[80:83]
	v_mfma_f32_16x16x32_bf16 v[80:83], v[144:147], v[220:223], v[80:83]
	s_setprio 0
	s_setprio 1
	v_mfma_f32_16x16x32_bf16 v[120:123], v[170:173], v[186:189], v[120:123]
	v_mfma_f32_16x16x32_bf16 v[120:123], v[174:177], v[190:193], v[120:123]
	v_mfma_f32_16x16x32_bf16 v[108:111], v[178:181], v[186:189], v[108:111]
	v_mfma_f32_16x16x32_bf16 v[108:111], v[182:185], v[190:193], v[108:111]
	v_mfma_f32_16x16x32_bf16 v[100:103], v[170:173], v[194:197], v[100:103]
	v_mfma_f32_16x16x32_bf16 v[100:103], v[174:177], v[204:207], v[100:103]
	v_mfma_f32_16x16x32_bf16 v[92:95], v[178:181], v[194:197], v[92:95]
	v_mfma_f32_16x16x32_bf16 v[92:95], v[182:185], v[204:207], v[92:95]
	v_mfma_f32_16x16x32_bf16 v[84:87], v[170:173], v[208:211], v[84:87]
	v_mfma_f32_16x16x32_bf16 v[84:87], v[174:177], v[212:215], v[84:87]
	v_mfma_f32_16x16x32_bf16 v[76:79], v[178:181], v[208:211], v[76:79]
	v_mfma_f32_16x16x32_bf16 v[76:79], v[182:185], v[212:215], v[76:79]
	v_mfma_f32_16x16x32_bf16 v[72:75], v[170:173], v[216:219], v[72:75]
	v_mfma_f32_16x16x32_bf16 v[72:75], v[174:177], v[220:223], v[72:75]
	v_mfma_f32_16x16x32_bf16 v[68:71], v[178:181], v[216:219], v[68:71]
	v_mfma_f32_16x16x32_bf16 v[68:71], v[182:185], v[220:223], v[68:71]
	s_setprio 0
	s_barrier
; #define PG8_STAGE(bufoff, gbase, voff) do { _Pragma("unroll") for (int _i = 0; _i < 2; ++_i) \
;         __builtin_amdgcn_global_load_lds((const unsigned*)((const char*)(gbase) + (voff)[_i]), (LAS unsigned*)(lds + (bufoff) + ldsw + _i * 8192), 16, 0, 0); } while (0)
; #define PG8_LDA(dst, b, h) do { _Pragma("unroll") for (int m = 0; m < 4; ++m) _Pragma("unroll") for (int k = 0; k < 2; ++k) dst[m][k] = *(const LAS bf16x8*)(lds + PG8_SA(b, h) + aoff + m * 2048 + k * 1024); } while (0)
; #define PG8_LDB(dst, b, h) do { _Pragma("unroll") for (int n = 0; n < 2; ++n) _Pragma("unroll") for (int k = 0; k < 2; ++k) dst[n][k] = *(const LAS bf16x8*)(lds + PG8_SB(b, h) + boff + n * 2048 + k * 1024); } while (0)
; #define PG8_MMA(ai, bj, At, Bt) do { __builtin_amdgcn_s_setprio(1); _Pragma("unroll") for (int m = 0; m < 4; ++m) _Pragma("unroll") for (int n = 0; n < 2; ++n) _Pragma("unroll") for (int k = 0; k < 2; ++k) \
;         acc[ai][bj][m][n] = __builtin_amdgcn_mfma_f32_16x16x32_bf16(Bt[n][k], At[m][k], acc[ai][bj][m][n], 0, 0, 0); __builtin_amdgcn_s_setprio(0); } while (0)
; #define PG8_WAIT_V(n) asm volatile("s_waitcnt vmcnt(" #n ")" ::: "memory")
; #define PG8_WAIT_L(n) asm volatile("s_waitcnt lgkmcnt(" #n ")" ::: "memory")
; template <class Epi, class Sched, bool ALIGN_EPI = true>
; __device__ __forceinline__ void gemm_phase(LAS unsigned char* lds, const Gemm g, const Sched& S, const Epi& E) {
;     ...
;         for (int t = 0; t < nt; t += 2) {
;             const bool last = (t == nt - 2);
;             const char* a1 = cA + (size_t)(t + 1) * kstep;
;             const char* a2 = last ? nA : cA + (size_t)(t + 2) * kstep; const char* b2 = last ? nB : cB + (size_t)(t + 2) * kstep;
;             const char* a3 = a2 + kstep; const char* b3 = b2 + kstep;
;             PG8_LDB(B0, 0, 0); PG8_LDB(B1, 0, 1); PG8_SCHED; PG8_LDA(At, 0, 0); PG8_STAGE(PG8_SA(1, 1), a1 + hA, voffA);
;             PG8_WAIT_V(8); PG8_WAIT_L(0); PG8_BAR; PG8_MMA(0, 0, At, B0); PG8_MMA(0, 1, At, B1); PG8_BAR; PG8_SCHED;
;     ...
;             PG8_WAIT_V(8); PG8_WAIT_L(0); PG8_BAR; PG8_MMA(0, 0, At, B0); PG8_MMA(0, 1, At, B1); PG8_BAR; PG8_SCHED;
;             PG8_LDA(At, 1, 1); PG8_STAGE(PG8_SB(1, 0), b3, voffB); PG8_STAGE(PG8_SB(1, 1), b3 + hB, voffB); PG8_STAGE(PG8_SA(1, 0), a3, voffA);
;             PG8_WAIT_V(8); PG8_WAIT_L(0); PG8_BAR; PG8_MMA(1, 0, At, B0); PG8_MMA(1, 1, At, B1); PG8_BAR; PG8_SCHED;
	s_add_i32 s26, s30, s59
	v_lshl_add_u64 v[156:157], v[156:157], 0, s[86:87]
	s_mov_b32 m0, s26
	ds_read_b128 v[186:189], v168 offset:49152
	ds_read_b128 v[190:193], v168 offset:50176
	ds_read_b128 v[194:197], v168 offset:51200
	ds_read_b128 v[204:207], v168 offset:52224
	ds_read_b128 v[208:211], v168 offset:53248
	ds_read_b128 v[212:215], v168 offset:54272
	ds_read_b128 v[216:219], v168 offset:55296
	ds_read_b128 v[220:223], v168 offset:56320
	global_load_lds_dwordx4 v[156:157], off
	s_add_i32 m0, s26, 0x2000
	s_add_u32 s26, s42, 0x80080
	v_lshl_add_u64 v[156:157], v[164:165], 0, s[86:87]
	s_addc_u32 s27, s43, 0
	s_add_i32 s30, s31, s59
	global_load_lds_dwordx4 v[156:157], off
	v_lshl_add_u64 v[156:157], s[26:27], 0, v[2:3]
	s_mov_b32 m0, s30
	s_nop 0
	global_load_lds_dwordx4 v[156:157], off
	v_lshl_add_u64 v[156:157], s[26:27], 0, v[0:1]
	s_add_i32 m0, s30, 0x2000
	s_nop 0
	global_load_lds_dwordx4 v[156:157], off
	v_lshl_add_u64 v[156:157], v[224:225], 0, s[86:87]
	s_mov_b32 m0, s64
	s_nop 0
	global_load_lds_dwordx4 v[156:157], off
	v_lshl_add_u64 v[156:157], v[226:227], 0, s[86:87]
	s_mov_b32 m0, s65
	s_nop 0
	global_load_lds_dwordx4 v[156:157], off
	s_waitcnt vmcnt(8)
	s_waitcnt lgkmcnt(0)
	s_barrier
	s_setprio 1
	s_waitcnt lgkmcnt(0)
	v_mfma_f32_16x16x32_bf16 v[64:67], v[132:135], v[186:189], v[64:67]
	v_mfma_f32_16x16x32_bf16 v[64:67], v[136:139], v[190:193], v[64:67]
	v_mfma_f32_16x16x32_bf16 v[60:63], v[140:143], v[186:189], v[60:63]
	v_mfma_f32_16x16x32_bf16 v[60:63], v[144:147], v[190:193], v[60:63]
	v_mfma_f32_16x16x32_bf16 v[56:59], v[132:135], v[194:197], v[56:59]
	v_mfma_f32_16x16x32_bf16 v[56:59], v[136:139], v[204:207], v[56:59]
	v_mfma_f32_16x16x32_bf16 v[48:51], v[140:143], v[194:197], v[48:51]
	v_mfma_f32_16x16x32_bf16 v[48:51], v[144:147], v[204:207], v[48:51]
	v_mfma_f32_16x16x32_bf16 v[40:43], v[132:135], v[208:211], v[40:43]
	v_mfma_f32_16x16x32_bf16 v[40:43], v[136:139], v[212:215], v[40:43]
	v_mfma_f32_16x16x32_bf16 v[32:35], v[140:143], v[208:211], v[32:35]
	v_mfma_f32_16x16x32_bf16 v[32:35], v[144:147], v[212:215], v[32:35]
	v_mfma_f32_16x16x32_bf16 v[24:27], v[132:135], v[216:219], v[24:27]
	v_mfma_f32_16x16x32_bf16 v[24:27], v[136:139], v[220:223], v[24:27]
	v_mfma_f32_16x16x32_bf16 v[16:19], v[140:143], v[216:219], v[16:19]
	v_mfma_f32_16x16x32_bf16 v[16:19], v[144:147], v[220:223], v[16:19]
	s_setprio 0
	s_setprio 1
	v_mfma_f32_16x16x32_bf16 v[52:55], v[170:173], v[186:189], v[52:55]
	v_mfma_f32_16x16x32_bf16 v[52:55], v[174:177], v[190:193], v[52:55]
	v_mfma_f32_16x16x32_bf16 v[44:47], v[178:181], v[186:189], v[44:47]
	v_mfma_f32_16x16x32_bf16 v[44:47], v[182:185], v[190:193], v[44:47]
	v_mfma_f32_16x16x32_bf16 v[36:39], v[170:173], v[194:197], v[36:39]
	v_mfma_f32_16x16x32_bf16 v[36:39], v[174:177], v[204:207], v[36:39]
	v_mfma_f32_16x16x32_bf16 v[28:31], v[178:181], v[194:197], v[28:31]
	v_mfma_f32_16x16x32_bf16 v[28:31], v[182:185], v[204:207], v[28:31]
	v_mfma_f32_16x16x32_bf16 v[20:23], v[170:173], v[208:211], v[20:23]
	v_mfma_f32_16x16x32_bf16 v[20:23], v[174:177], v[212:215], v[20:23]
	v_mfma_f32_16x16x32_bf16 v[12:15], v[178:181], v[208:211], v[12:15]
	v_mfma_f32_16x16x32_bf16 v[12:15], v[182:185], v[212:215], v[12:15]
	v_mfma_f32_16x16x32_bf16 v[8:11], v[170:173], v[216:219], v[8:11]
	v_mfma_f32_16x16x32_bf16 v[8:11], v[174:177], v[220:223], v[8:11]
	v_mfma_f32_16x16x32_bf16 v[4:7], v[178:181], v[216:219], v[4:7]
	v_mfma_f32_16x16x32_bf16 v[4:7], v[182:185], v[220:223], v[4:7]
	s_setprio 0
	s_barrier
	s_add_i32 s25, s25, 2
	s_add_u32 s6, s6, 0x100
	s_addc_u32 s7, s7, 0
	s_add_u32 s19, s19, 0x100
	s_addc_u32 s24, s24, 0
	s_cmp_gt_u32 s25, 29
	s_cbranch_scc1 .Lpeel_exit_77
.LBB0_77:
	s_add_u32 s26, s6, 0xfff80080
	s_addc_u32 s27, s7, -1
	s_add_i32 s30, 0, 0x10000
	s_cmp_eq_u32 s25, 28
	s_cselect_b32 s45, s15, s27
	s_cselect_b32 s44, s17, s26
	s_cselect_b32 s43, s13, s24
	s_cselect_b32 s42, s18, s19
	s_add_i32 s31, 0, 0x14000
	v_add_u32_e32 v144, s30, v166
	v_add_u32_e32 v156, s31, v166
	ds_read_b128 v[132:135], v144
	ds_read_b128 v[136:139], v144 offset:1024
	ds_read_b128 v[140:143], v144 offset:2048
	ds_read_b128 v[144:147], v144 offset:3072
	ds_read_b128 v[170:173], v156
	ds_read_b128 v[174:177], v156 offset:1024
	ds_read_b128 v[178:181], v156 offset:2048
	ds_read_b128 v[182:185], v156 offset:3072
	v_lshl_add_u64 v[156:157], s[6:7], 0, v[152:153]
	s_add_i32 m0, s60, 0xc000
	ds_read_b128 v[186:189], v168
	ds_read_b128 v[190:193], v168 offset:1024
	ds_read_b128 v[194:197], v168 offset:2048
	ds_read_b128 v[204:207], v168 offset:3072
	ds_read_b128 v[208:211], v168 offset:4096
	ds_read_b128 v[212:215], v168 offset:5120
	ds_read_b128 v[216:219], v168 offset:6144
	ds_read_b128 v[220:223], v168 offset:7168
	global_load_lds_dwordx4 v[156:157], off
	v_lshl_add_u64 v[156:157], s[6:7], 0, v[154:155]
	s_add_i32 m0, s60, 0xe000
	s_nop 0
	global_load_lds_dwordx4 v[156:157], off
	s_waitcnt vmcnt(8)
	s_waitcnt lgkmcnt(0)
	s_barrier
; #define PG8_STAGE(bufoff, gbase, voff) do { _Pragma("unroll") for (int _i = 0; _i < 2; ++_i) \
;         __builtin_amdgcn_global_load_lds((const unsigned*)((const char*)(gbase) + (voff)[_i]), (LAS unsigned*)(lds + (bufoff) + ldsw + _i * 8192), 16, 0, 0); } while (0)
; #define PG8_LDA(dst, b, h) do { _Pragma("unroll") for (int m = 0; m < 4; ++m) _Pragma("unroll") for (int k = 0; k < 2; ++k) dst[m][k] = *(const LAS bf16x8*)(lds + PG8_SA(b, h) + aoff + m * 2048 + k * 1024); } while (0)
; #define PG8_LDB(dst, b, h) do { _Pragma("unroll") for (int n = 0; n < 2; ++n) _Pragma("unroll") for (int k = 0; k < 2; ++k) dst[n][k] = *(const LAS bf16x8*)(lds + PG8_SB(b, h) + boff + n * 2048 + k * 1024); } while (0)
; #define PG8_MMA(ai, bj, At, Bt) do { __builtin_amdgcn_s_setprio(1); _Pragma("unroll") for (int m = 0; m < 4; ++m) _Pragma("unroll") for (int n = 0; n < 2; ++n) _Pragma("unroll") for (int k = 0; k < 2; ++k) \
;         acc[ai][bj][m][n] = __builtin_amdgcn_mfma_f32_16x16x32_bf16(Bt[n][k], At[m][k], acc[ai][bj][m][n], 0, 0, 0); __builtin_amdgcn_s_setprio(0); } while (0)
; #define PG8_WAIT_V(n) asm volatile("s_waitcnt vmcnt(" #n ")" ::: "memory")
; #define PG8_WAIT_L(n) asm volatile("s_waitcnt lgkmcnt(" #n ")" ::: "memory")
; #define PG8_BAR __builtin_amdgcn_s_barrier()
; #define PG8_SCHED __builtin_amdgcn_sched_barrier(0)
; template <class Epi, class Sched, bool ALIGN_EPI = true>
; __device__ __forceinline__ void gemm_phase(LAS unsigned char* lds, const Gemm g, const Sched& S, const Epi& E) {
;     ...
;             PG8_WAIT_V(8); PG8_WAIT_L(0); PG8_BAR; PG8_MMA(0, 0, At, B0); PG8_MMA(0, 1, At, B1); PG8_BAR; PG8_SCHED;
;             PG8_LDA(At, 0, 1); PG8_STAGE(PG8_SB(0, 0), b2, voffB); PG8_STAGE(PG8_SB(0, 1), b2 + hB, voffB); PG8_STAGE(PG8_SA(0, 0), a2, voffA);
;             PG8_WAIT_V(8); PG8_WAIT_L(0); PG8_BAR; PG8_MMA(1, 0, At, B0); PG8_MMA(1, 1, At, B1); PG8_BAR; PG8_SCHED;
;             PG8_LDB(B0, 1, 0); PG8_LDB(B1, 1, 1); PG8_SCHED; PG8_LDA(At, 1, 0); PG8_STAGE(PG8_SA(0, 1), a2 + hA, voffA);
;             PG8_WAIT_V(8); PG8_WAIT_L(0); PG8_BAR; PG8_MMA(0, 0, At, B0); PG8_MMA(0, 1, At, B1); PG8_BAR; PG8_SCHED;
	s_setprio 1
	s_waitcnt lgkmcnt(0)
	v_mfma_f32_16x16x32_bf16 v[128:131], v[132:135], v[186:189], v[128:131]
	v_mfma_f32_16x16x32_bf16 v[128:131], v[136:139], v[190:193], v[128:131]
	v_mfma_f32_16x16x32_bf16 v[124:127], v[140:143], v[186:189], v[124:127]
	v_mfma_f32_16x16x32_bf16 v[124:127], v[144:147], v[190:193], v[124:127]
	v_mfma_f32_16x16x32_bf16 v[116:119], v[132:135], v[194:197], v[116:119]
	v_mfma_f32_16x16x32_bf16 v[116:119], v[136:139], v[204:207], v[116:119]
	v_mfma_f32_16x16x32_bf16 v[112:115], v[140:143], v[194:197], v[112:115]
	v_mfma_f32_16x16x32_bf16 v[112:115], v[144:147], v[204:207], v[112:115]
	v_mfma_f32_16x16x32_bf16 v[104:107], v[132:135], v[208:211], v[104:107]
	v_mfma_f32_16x16x32_bf16 v[104:107], v[136:139], v[212:215], v[104:107]
	v_mfma_f32_16x16x32_bf16 v[96:99], v[140:143], v[208:211], v[96:99]
	v_mfma_f32_16x16x32_bf16 v[96:99], v[144:147], v[212:215], v[96:99]
	v_mfma_f32_16x16x32_bf16 v[88:91], v[132:135], v[216:219], v[88:91]
	v_mfma_f32_16x16x32_bf16 v[88:91], v[136:139], v[220:223], v[88:91]
	v_mfma_f32_16x16x32_bf16 v[80:83], v[140:143], v[216:219], v[80:83]
	v_mfma_f32_16x16x32_bf16 v[80:83], v[144:147], v[220:223], v[80:83]
	s_setprio 0
	s_setprio 1
	v_mfma_f32_16x16x32_bf16 v[120:123], v[170:173], v[186:189], v[120:123]
	v_mfma_f32_16x16x32_bf16 v[120:123], v[174:177], v[190:193], v[120:123]
	v_mfma_f32_16x16x32_bf16 v[108:111], v[178:181], v[186:189], v[108:111]
	v_mfma_f32_16x16x32_bf16 v[108:111], v[182:185], v[190:193], v[108:111]
	v_mfma_f32_16x16x32_bf16 v[100:103], v[170:173], v[194:197], v[100:103]
	v_mfma_f32_16x16x32_bf16 v[100:103], v[174:177], v[204:207], v[100:103]
	v_mfma_f32_16x16x32_bf16 v[92:95], v[178:181], v[194:197], v[92:95]
	v_mfma_f32_16x16x32_bf16 v[92:95], v[182:185], v[204:207], v[92:95]
	v_mfma_f32_16x16x32_bf16 v[84:87], v[170:173], v[208:211], v[84:87]
	v_mfma_f32_16x16x32_bf16 v[84:87], v[174:177], v[212:215], v[84:87]
	v_mfma_f32_16x16x32_bf16 v[76:79], v[178:181], v[208:211], v[76:79]
	v_mfma_f32_16x16x32_bf16 v[76:79], v[182:185], v[212:215], v[76:79]
	v_mfma_f32_16x16x32_bf16 v[72:75], v[170:173], v[216:219], v[72:75]
	v_mfma_f32_16x16x32_bf16 v[72:75], v[174:177], v[220:223], v[72:75]
	v_mfma_f32_16x16x32_bf16 v[68:71], v[178:181], v[216:219], v[68:71]
	v_mfma_f32_16x16x32_bf16 v[68:71], v[182:185], v[220:223], v[68:71]
	s_setprio 0
	s_barrier
	s_add_i32 s26, s30, s59
	v_lshl_add_u64 v[156:157], s[42:43], 0, v[2:3]
	s_mov_b32 m0, s26
	ds_read_b128 v[186:189], v168 offset:16384
	ds_read_b128 v[190:193], v168 offset:17408
	ds_read_b128 v[194:197], v168 offset:18432
	ds_read_b128 v[204:207], v168 offset:19456
	ds_read_b128 v[208:211], v168 offset:20480
	ds_read_b128 v[212:215], v168 offset:21504
	ds_read_b128 v[216:219], v168 offset:22528
	ds_read_b128 v[220:223], v168 offset:23552
	global_load_lds_dwordx4 v[156:157], off
	s_add_i32 m0, s26, 0x2000
	s_add_u32 s26, s42, 0x80000
	v_lshl_add_u64 v[164:165], s[42:43], 0, v[0:1]
	s_addc_u32 s27, s43, 0
	s_add_i32 s30, s31, s59
	global_load_lds_dwordx4 v[164:165], off
	v_lshl_add_u64 v[224:225], s[26:27], 0, v[2:3]
	s_mov_b32 m0, s30
	v_lshl_add_u64 v[226:227], s[44:45], 0, v[148:149]
	global_load_lds_dwordx4 v[224:225], off
	v_lshl_add_u64 v[224:225], s[26:27], 0, v[0:1]
	s_add_i32 m0, s30, 0x2000
	s_nop 0
	global_load_lds_dwordx4 v[224:225], off
	v_lshl_add_u64 v[224:225], s[44:45], 0, v[150:151]
	s_mov_b32 m0, s60
	s_nop 0
	global_load_lds_dwordx4 v[224:225], off
	s_mov_b32 m0, s61
	s_nop 0
	global_load_lds_dwordx4 v[226:227], off
	s_waitcnt vmcnt(8)
	s_waitcnt lgkmcnt(0)
	s_barrier
	s_setprio 1
	s_waitcnt lgkmcnt(0)
	v_mfma_f32_16x16x32_bf16 v[64:67], v[132:135], v[186:189], v[64:67]
	v_mfma_f32_16x16x32_bf16 v[64:67], v[136:139], v[190:193], v[64:67]
	v_mfma_f32_16x16x32_bf16 v[60:63], v[140:143], v[186:189], v[60:63]
	v_mfma_f32_16x16x32_bf16 v[60:63], v[144:147], v[190:193], v[60:63]
	v_mfma_f32_16x16x32_bf16 v[56:59], v[132:135], v[194:197], v[56:59]
	v_mfma_f32_16x16x32_bf16 v[56:59], v[136:139], v[204:207], v[56:59]
	v_mfma_f32_16x16x32_bf16 v[48:51], v[140:143], v[194:197], v[48:51]
	v_mfma_f32_16x16x32_bf16 v[48:51], v[144:147], v[204:207], v[48:51]
	v_mfma_f32_16x16x32_bf16 v[40:43], v[132:135], v[208:211], v[40:43]
	v_mfma_f32_16x16x32_bf16 v[40:43], v[136:139], v[212:215], v[40:43]
	v_mfma_f32_16x16x32_bf16 v[32:35], v[140:143], v[208:211], v[32:35]
	v_mfma_f32_16x16x32_bf16 v[32:35], v[144:147], v[212:215], v[32:35]
	v_mfma_f32_16x16x32_bf16 v[24:27], v[132:135], v[216:219], v[24:27]
	v_mfma_f32_16x16x32_bf16 v[24:27], v[136:139], v[220:223], v[24:27]
	v_mfma_f32_16x16x32_bf16 v[16:19], v[140:143], v[216:219], v[16:19]
	v_mfma_f32_16x16x32_bf16 v[16:19], v[144:147], v[220:223], v[16:19]
	s_setprio 0
	s_setprio 1
	v_mfma_f32_16x16x32_bf16 v[52:55], v[170:173], v[186:189], v[52:55]
	v_mfma_f32_16x16x32_bf16 v[52:55], v[174:177], v[190:193], v[52:55]
	v_mfma_f32_16x16x32_bf16 v[44:47], v[178:181], v[186:189], v[44:47]
	v_mfma_f32_16x16x32_bf16 v[44:47], v[182:185], v[190:193], v[44:47]
	v_mfma_f32_16x16x32_bf16 v[36:39], v[170:173], v[194:197], v[36:39]
	v_mfma_f32_16x16x32_bf16 v[36:39], v[174:177], v[204:207], v[36:39]
	v_mfma_f32_16x16x32_bf16 v[28:31], v[178:181], v[194:197], v[28:31]
	v_mfma_f32_16x16x32_bf16 v[28:31], v[182:185], v[204:207], v[28:31]
	v_mfma_f32_16x16x32_bf16 v[20:23], v[170:173], v[208:211], v[20:23]
	v_mfma_f32_16x16x32_bf16 v[20:23], v[174:177], v[212:215], v[20:23]
	v_mfma_f32_16x16x32_bf16 v[12:15], v[178:181], v[208:211], v[12:15]
	v_mfma_f32_16x16x32_bf16 v[12:15], v[182:185], v[212:215], v[12:15]
	v_mfma_f32_16x16x32_bf16 v[8:11], v[170:173], v[216:219], v[8:11]
	v_mfma_f32_16x16x32_bf16 v[8:11], v[174:177], v[220:223], v[8:11]
	v_mfma_f32_16x16x32_bf16 v[4:7], v[178:181], v[216:219], v[4:7]
	v_mfma_f32_16x16x32_bf16 v[4:7], v[182:185], v[220:223], v[4:7]
	s_setprio 0
	s_barrier
; #define PG8_STAGE(bufoff, gbase, voff) do { _Pragma("unroll") for (int _i = 0; _i < 2; ++_i) \
;         __builtin_amdgcn_global_load_lds((const unsigned*)((const char*)(gbase) + (voff)[_i]), (LAS unsigned*)(lds + (bufoff) + ldsw + _i * 8192), 16, 0, 0); } while (0)
; #define PG8_LDA(dst, b, h) do { _Pragma("unroll") for (int m = 0; m < 4; ++m) _Pragma("unroll") for (int k = 0; k < 2; ++k) dst[m][k] = *(const LAS bf16x8*)(lds + PG8_SA(b, h) + aoff + m * 2048 + k * 1024); } while (0)
; #define PG8_LDB(dst, b, h) do { _Pragma("unroll") for (int n = 0; n < 2; ++n) _Pragma("unroll") for (int k = 0; k < 2; ++k) dst[n][k] = *(const LAS bf16x8*)(lds + PG8_SB(b, h) + boff + n * 2048 + k * 1024); } while (0)
; #define PG8_MMA(ai, bj, At, Bt) do { __builtin_amdgcn_s_setprio(1); _Pragma("unroll") for (int m = 0; m < 4; ++m) _Pragma("unroll") for (int n = 0; n < 2; ++n) _Pragma("unroll") for (int k = 0; k < 2; ++k) \
;         acc[ai][bj][m][n] = __builtin_amdgcn_mfma_f32_16x16x32_bf16(Bt[n][k], At[m][k], acc[ai][bj][m][n], 0, 0, 0); __builtin_amdgcn_s_setprio(0); } while (0)
; #define PG8_WAIT_V(n) asm volatile("s_waitcnt vmcnt(" #n ")" ::: "memory")
; #define PG8_WAIT_L(n) asm volatile("s_waitcnt lgkmcnt(" #n ")" ::: "memory")
; #define PG8_BAR __builtin_amdgcn_s_barrier()
; #define PG8_SCHED __builtin_amdgcn_sched_barrier(0)
; template <class Epi, class Sched, bool ALIGN_EPI = true>
; __device__ __forceinline__ void gemm_phase(LAS unsigned char* lds, const Gemm g, const Sched& S, const Epi& E) {
;     ...
;             PG8_LDB(B0, 1, 0); PG8_LDB(B1, 1, 1); PG8_SCHED; PG8_LDA(At, 1, 0); PG8_STAGE(PG8_SA(0, 1), a2 + hA, voffA);
;             PG8_WAIT_V(8); PG8_WAIT_L(0); PG8_BAR; PG8_MMA(0, 0, At, B0); PG8_MMA(0, 1, At, B1); PG8_BAR; PG8_SCHED;
	s_add_i32 s30, 0, 0x18000
	s_add_i32 s31, 0, 0x1c000
	v_add_u32_e32 v144, s30, v166
	v_add_u32_e32 v160, s31, v166
	ds_read_b128 v[132:135], v144
	ds_read_b128 v[136:139], v144 offset:1024
	ds_read_b128 v[140:143], v144 offset:2048
	ds_read_b128 v[144:147], v144 offset:3072
	ds_read_b128 v[170:173], v160
	ds_read_b128 v[174:177], v160 offset:1024
	ds_read_b128 v[178:181], v160 offset:2048
	ds_read_b128 v[182:185], v160 offset:3072
	s_add_u32 s26, s44, 0x80000
	s_addc_u32 s27, s45, 0
	s_mov_b32 m0, s62
	v_lshl_add_u64 v[228:229], s[26:27], 0, v[150:151]
	ds_read_b128 v[186:189], v168 offset:32768
	ds_read_b128 v[190:193], v168 offset:33792
	ds_read_b128 v[194:197], v168 offset:34816
	ds_read_b128 v[204:207], v168 offset:35840
	ds_read_b128 v[208:211], v168 offset:36864
	ds_read_b128 v[212:215], v168 offset:37888
	ds_read_b128 v[216:219], v168 offset:38912
	ds_read_b128 v[220:223], v168 offset:39936
	global_load_lds_dwordx4 v[228:229], off
	v_lshl_add_u64 v[228:229], s[26:27], 0, v[148:149]
	s_mov_b32 m0, s63
	s_nop 0
	global_load_lds_dwordx4 v[228:229], off
	s_waitcnt vmcnt(8)
	s_waitcnt lgkmcnt(0)
	s_barrier
	s_setprio 1
	s_waitcnt lgkmcnt(0)
	v_mfma_f32_16x16x32_bf16 v[128:131], v[132:135], v[186:189], v[128:131]
	v_mfma_f32_16x16x32_bf16 v[128:131], v[136:139], v[190:193], v[128:131]
	v_mfma_f32_16x16x32_bf16 v[124:127], v[140:143], v[186:189], v[124:127]
	v_mfma_f32_16x16x32_bf16 v[124:127], v[144:147], v[190:193], v[124:127]
	v_mfma_f32_16x16x32_bf16 v[116:119], v[132:135], v[194:197], v[116:119]
	v_mfma_f32_16x16x32_bf16 v[116:119], v[136:139], v[204:207], v[116:119]
	v_mfma_f32_16x16x32_bf16 v[112:115], v[140:143], v[194:197], v[112:115]
	v_mfma_f32_16x16x32_bf16 v[112:115], v[144:147], v[204:207], v[112:115]
	v_mfma_f32_16x16x32_bf16 v[104:107], v[132:135], v[208:211], v[104:107]
	v_mfma_f32_16x16x32_bf16 v[104:107], v[136:139], v[212:215], v[104:107]
	v_mfma_f32_16x16x32_bf16 v[96:99], v[140:143], v[208:211], v[96:99]
	v_mfma_f32_16x16x32_bf16 v[96:99], v[144:147], v[212:215], v[96:99]
	v_mfma_f32_16x16x32_bf16 v[88:91], v[132:135], v[216:219], v[88:91]
	v_mfma_f32_16x16x32_bf16 v[88:91], v[136:139], v[220:223], v[88:91]
	v_mfma_f32_16x16x32_bf16 v[80:83], v[140:143], v[216:219], v[80:83]
	v_mfma_f32_16x16x32_bf16 v[80:83], v[144:147], v[220:223], v[80:83]
	s_setprio 0
	s_setprio 1
	v_mfma_f32_16x16x32_bf16 v[120:123], v[170:173], v[186:189], v[120:123]
	v_mfma_f32_16x16x32_bf16 v[120:123], v[174:177], v[190:193], v[120:123]
	v_mfma_f32_16x16x32_bf16 v[108:111], v[178:181], v[186:189], v[108:111]
	v_mfma_f32_16x16x32_bf16 v[108:111], v[182:185], v[190:193], v[108:111]
	v_mfma_f32_16x16x32_bf16 v[100:103], v[170:173], v[194:197], v[100:103]
	v_mfma_f32_16x16x32_bf16 v[100:103], v[174:177], v[204:207], v[100:103]
	v_mfma_f32_16x16x32_bf16 v[92:95], v[178:181], v[194:197], v[92:95]
	v_mfma_f32_16x16x32_bf16 v[92:95], v[182:185], v[204:207], v[92:95]
	v_mfma_f32_16x16x32_bf16 v[84:87], v[170:173], v[208:211], v[84:87]
	v_mfma_f32_16x16x32_bf16 v[84:87], v[174:177], v[212:215], v[84:87]
	v_mfma_f32_16x16x32_bf16 v[76:79], v[178:181], v[208:211], v[76:79]
	v_mfma_f32_16x16x32_bf16 v[76:79], v[182:185], v[212:215], v[76:79]
	v_mfma_f32_16x16x32_bf16 v[72:75], v[170:173], v[216:219], v[72:75]
	v_mfma_f32_16x16x32_bf16 v[72:75], v[174:177], v[220:223], v[72:75]
	v_mfma_f32_16x16x32_bf16 v[68:71], v[178:181], v[216:219], v[68:71]
	v_mfma_f32_16x16x32_bf16 v[68:71], v[182:185], v[220:223], v[68:71]
	s_setprio 0
	s_barrier
; #define PG8_STAGE(bufoff, gbase, voff) do { _Pragma("unroll") for (int _i = 0; _i < 2; ++_i) \
;         __builtin_amdgcn_global_load_lds((const unsigned*)((const char*)(gbase) + (voff)[_i]), (LAS unsigned*)(lds + (bufoff) + ldsw + _i * 8192), 16, 0, 0); } while (0)
; #define PG8_LDA(dst, b, h) do { _Pragma("unroll") for (int m = 0; m < 4; ++m) _Pragma("unroll") for (int k = 0; k < 2; ++k) dst[m][k] = *(const LAS bf16x8*)(lds + PG8_SA(b, h) + aoff + m * 2048 + k * 1024); } while (0)
; #define PG8_MMA(ai, bj, At, Bt) do { __builtin_amdgcn_s_setprio(1); _Pragma("unroll") for (int m = 0; m < 4; ++m) _Pragma("unroll") for (int n = 0; n < 2; ++n) _Pragma("unroll") for (int k = 0; k < 2; ++k) \
;         acc[ai][bj][m][n] = __builtin_amdgcn_mfma_f32_16x16x32_bf16(Bt[n][k], At[m][k], acc[ai][bj][m][n], 0, 0, 0); __builtin_amdgcn_s_setprio(0); } while (0)
; #define PG8_WAIT_V(n) asm volatile("s_waitcnt vmcnt(" #n ")" ::: "memory")
; #define PG8_WAIT_L(n) asm volatile("s_waitcnt lgkmcnt(" #n ")" ::: "memory")
; #define PG8_BAR __builtin_amdgcn_s_barrier()
; #define PG8_SCHED __builtin_amdgcn_sched_barrier(0)
; template <class Epi, class Sched, bool ALIGN_EPI = true>
; __device__ __forceinline__ void gemm_phase(LAS unsigned char* lds, const Gemm g, const Sched& S, const Epi& E) {
;     ...
;             PG8_LDA(At, 1, 1); PG8_STAGE(PG8_SB(1, 0), b3, voffB); PG8_STAGE(PG8_SB(1, 1), b3 + hB, voffB); PG8_STAGE(PG8_SA(1, 0), a3, voffA);
;             PG8_WAIT_V(8); PG8_WAIT_L(0); PG8_BAR; PG8_MMA(1, 0, At, B0); PG8_MMA(1, 1, At, B1); PG8_BAR; PG8_SCHED;
;         }
	s_add_i32 s26, s30, s59
	v_lshl_add_u64 v[156:157], v[156:157], 0, s[86:87]
	s_mov_b32 m0, s26
	ds_read_b128 v[186:189], v168 offset:49152
	ds_read_b128 v[190:193], v168 offset:50176
	ds_read_b128 v[194:197], v168 offset:51200
	ds_read_b128 v[204:207], v168 offset:52224
	ds_read_b128 v[208:211], v168 offset:53248
	ds_read_b128 v[212:215], v168 offset:54272
	ds_read_b128 v[216:219], v168 offset:55296
	ds_read_b128 v[220:223], v168 offset:56320
	global_load_lds_dwordx4 v[156:157], off
	s_add_i32 m0, s26, 0x2000
	s_add_u32 s26, s42, 0x80080
	v_lshl_add_u64 v[156:157], v[164:165], 0, s[86:87]
	s_addc_u32 s27, s43, 0
	s_add_i32 s30, s31, s59
	global_load_lds_dwordx4 v[156:157], off
	v_lshl_add_u64 v[156:157], s[26:27], 0, v[2:3]
	s_mov_b32 m0, s30
	s_nop 0
	global_load_lds_dwordx4 v[156:157], off
	v_lshl_add_u64 v[156:157], s[26:27], 0, v[0:1]
	s_add_i32 m0, s30, 0x2000
	s_nop 0
	global_load_lds_dwordx4 v[156:157], off
	v_lshl_add_u64 v[156:157], v[224:225], 0, s[86:87]
	s_mov_b32 m0, s64
	s_nop 0
	global_load_lds_dwordx4 v[156:157], off
	v_lshl_add_u64 v[156:157], v[226:227], 0, s[86:87]
	s_mov_b32 m0, s65
	s_nop 0
	global_load_lds_dwordx4 v[156:157], off
	s_waitcnt vmcnt(8)
	s_waitcnt lgkmcnt(0)
	s_barrier
	s_setprio 1
	s_waitcnt lgkmcnt(0)
	v_mfma_f32_16x16x32_bf16 v[64:67], v[132:135], v[186:189], v[64:67]
	v_mfma_f32_16x16x32_bf16 v[64:67], v[136:139], v[190:193], v[64:67]
	v_mfma_f32_16x16x32_bf16 v[60:63], v[140:143], v[186:189], v[60:63]
	v_mfma_f32_16x16x32_bf16 v[60:63], v[144:147], v[190:193], v[60:63]
	v_mfma_f32_16x16x32_bf16 v[56:59], v[132:135], v[194:197], v[56:59]
	v_mfma_f32_16x16x32_bf16 v[56:59], v[136:139], v[204:207], v[56:59]
	v_mfma_f32_16x16x32_bf16 v[48:51], v[140:143], v[194:197], v[48:51]
	v_mfma_f32_16x16x32_bf16 v[48:51], v[144:147], v[204:207], v[48:51]
	v_mfma_f32_16x16x32_bf16 v[40:43], v[132:135], v[208:211], v[40:43]
	v_mfma_f32_16x16x32_bf16 v[40:43], v[136:139], v[212:215], v[40:43]
	v_mfma_f32_16x16x32_bf16 v[32:35], v[140:143], v[208:211], v[32:35]
	v_mfma_f32_16x16x32_bf16 v[32:35], v[144:147], v[212:215], v[32:35]
	v_mfma_f32_16x16x32_bf16 v[24:27], v[132:135], v[216:219], v[24:27]
	v_mfma_f32_16x16x32_bf16 v[24:27], v[136:139], v[220:223], v[24:27]
	v_mfma_f32_16x16x32_bf16 v[16:19], v[140:143], v[216:219], v[16:19]
	v_mfma_f32_16x16x32_bf16 v[16:19], v[144:147], v[220:223], v[16:19]
	s_setprio 0
	s_setprio 1
	v_mfma_f32_16x16x32_bf16 v[52:55], v[170:173], v[186:189], v[52:55]
	v_mfma_f32_16x16x32_bf16 v[52:55], v[174:177], v[190:193], v[52:55]
	v_mfma_f32_16x16x32_bf16 v[44:47], v[178:181], v[186:189], v[44:47]
	v_mfma_f32_16x16x32_bf16 v[44:47], v[182:185], v[190:193], v[44:47]
	v_mfma_f32_16x16x32_bf16 v[36:39], v[170:173], v[194:197], v[36:39]
	v_mfma_f32_16x16x32_bf16 v[36:39], v[174:177], v[204:207], v[36:39]
	v_mfma_f32_16x16x32_bf16 v[28:31], v[178:181], v[194:197], v[28:31]
	v_mfma_f32_16x16x32_bf16 v[28:31], v[182:185], v[204:207], v[28:31]
	v_mfma_f32_16x16x32_bf16 v[20:23], v[170:173], v[208:211], v[20:23]
	v_mfma_f32_16x16x32_bf16 v[20:23], v[174:177], v[212:215], v[20:23]
	v_mfma_f32_16x16x32_bf16 v[12:15], v[178:181], v[208:211], v[12:15]
	v_mfma_f32_16x16x32_bf16 v[12:15], v[182:185], v[212:215], v[12:15]
	v_mfma_f32_16x16x32_bf16 v[8:11], v[170:173], v[216:219], v[8:11]
	v_mfma_f32_16x16x32_bf16 v[8:11], v[174:177], v[220:223], v[8:11]
	v_mfma_f32_16x16x32_bf16 v[4:7], v[178:181], v[216:219], v[4:7]
	v_mfma_f32_16x16x32_bf16 v[4:7], v[182:185], v[220:223], v[4:7]
	s_setprio 0
	s_barrier
	s_add_i32 s25, s25, 2
	s_add_u32 s6, s6, 0x100
	s_addc_u32 s7, s7, 0
	s_add_u32 s19, s19, 0x100
	s_addc_u32 s24, s24, 0
	s_cmp_gt_u32 s25, 29
	s_cbranch_scc0 .LBB0_77

;     __device__ bool next(int i, Unit& u) const { if (i >= 2) return false; const int x = c & 7, j = c >> 3; u.pm = 32 * i + 4 * x + (j & 3); u.pn = j >> 2; return true; }
; #define PG8_STAGE(bufoff, gbase, voff) do { _Pragma("unroll") for (int _i = 0; _i < 2; ++_i) \
;         __builtin_amdgcn_global_load_lds((const unsigned*)((const char*)(gbase) + (voff)[_i]), (LAS unsigned*)(lds + (bufoff) + ldsw + _i * 8192), 16, 0, 0); } while (0)
; #define PG8_LDA(dst, b, h) do { _Pragma("unroll") for (int m = 0; m < 4; ++m) _Pragma("unroll") for (int k = 0; k < 2; ++k) dst[m][k] = *(const LAS bf16x8*)(lds + PG8_SA(b, h) + aoff + m * 2048 + k * 1024); } while (0)
; #define PG8_LDB(dst, b, h) do { _Pragma("unroll") for (int n = 0; n < 2; ++n) _Pragma("unroll") for (int k = 0; k < 2; ++k) dst[n][k] = *(const LAS bf16x8*)(lds + PG8_SB(b, h) + boff + n * 2048 + k * 1024); } while (0)
; #define PG8_WAIT_V(n) asm volatile("s_waitcnt vmcnt(" #n ")" ::: "memory")
; #define PG8_WAIT_L(n) asm volatile("s_waitcnt lgkmcnt(" #n ")" ::: "memory")
; #define PG8_BAR __builtin_amdgcn_s_barrier()
; template <class Epi, class Sched, bool ALIGN_EPI = true>
; __device__ __forceinline__ void gemm_phase(LAS unsigned char* lds, const Gemm g, const Sched& S, const Epi& E) {
;     ...
;         const bool has_next = S.next(ui + 1, nxt);
;         const char* nA = has_next ? (const char*)g.A + ((size_t)nxt.pm * BM * g.lda + (size_t)nxt.pn * g.a_pn_off) * 2 : cA; const char* nB = has_next ? (const char*)g.Bt + (size_t)nxt.pn * BM * g.ldb * 2 : cB;
;         for (int t = 0; t < nt; t += 2) {
;             const bool last = (t == nt - 2);
;             const char* a1 = cA + (size_t)(t + 1) * kstep;
;             const char* a2 = last ? nA : cA + (size_t)(t + 2) * kstep; const char* b2 = last ? nB : cB + (size_t)(t + 2) * kstep;
;             const char* a3 = a2 + kstep; const char* b3 = b2 + kstep;
;             PG8_LDB(B0, 0, 0); PG8_LDB(B1, 0, 1); PG8_SCHED; PG8_LDA(At, 0, 0); PG8_STAGE(PG8_SA(1, 1), a1 + hA, voffA);
;             PG8_WAIT_V(8); PG8_WAIT_L(0); PG8_BAR; PG8_MMA(0, 0, At, B0); PG8_MMA(0, 1, At, B1); PG8_BAR; PG8_SCHED;
;             PG8_LDA(At, 0, 1); PG8_STAGE(PG8_SB(0, 0), b2, voffB); PG8_STAGE(PG8_SB(0, 1), b2 + hB, voffB); PG8_STAGE(PG8_SA(0, 0), a2, voffA);
;             PG8_WAIT_V(8); PG8_WAIT_L(0); PG8_BAR; PG8_MMA(1, 0, At, B0); PG8_MMA(1, 1, At, B1); PG8_BAR; PG8_SCHED;
.LBB0_217:
	s_ashr_i32 s11, s10, 31
	s_lshl_b64 s[12:13], s[10:11], 20
	s_add_u32 s12, s46, s12
	s_addc_u32 s13, s47, s13
	s_and_b64 s[14:15], s[4:5], exec
	s_cselect_b32 s11, s13, s39
	s_cselect_b32 s18, s12, s38
	s_ashr_i32 s9, s8, 31
	s_lshl_b64 s[14:15], s[8:9], 20
	s_add_u32 s14, s44, s14
	s_addc_u32 s15, s45, s15
	s_and_b64 s[24:25], s[4:5], exec
	s_cselect_b32 s9, s15, s41
	s_cselect_b32 s19, s14, s40
	s_add_u32 s38, s38, 0x80080
	s_addc_u32 s39, s39, 0
	s_add_u32 s24, s40, 0x100
	s_addc_u32 s25, s41, 0
	s_mov_b32 s26, -2
	s_add_u32 s27, s38, 0xfff80080
	s_addc_u32 s30, s39, -1
	s_add_i32 s31, 0, 0x10000
	s_cmp_eq_u32 s26, 28
	s_cselect_b32 s43, s11, s30
	s_cselect_b32 s42, s18, s27
	v_add_u32_e32 v156, s31, v145
	s_cselect_b32 s41, s9, s25
	s_cselect_b32 s40, s19, s24
	s_add_i32 s27, 0, 0x14000
	ds_read_b128 v[140:143], v156
	ds_read_b128 v[148:151], v156 offset:1024
	ds_read_b128 v[152:155], v156 offset:2048
	ds_read_b128 v[164:167], v156 offset:3072
	v_add_u32_e32 v156, s27, v145
	ds_read_b128 v[168:171], v156
	ds_read_b128 v[172:175], v156 offset:1024
	ds_read_b128 v[176:179], v156 offset:2048
	ds_read_b128 v[180:183], v156 offset:3072
	v_lshl_add_u64 v[156:157], s[38:39], 0, v[136:137]
	s_add_i32 m0, s58, 0xc000
	ds_read_b128 v[184:187], v147
	ds_read_b128 v[188:191], v147 offset:1024
	ds_read_b128 v[192:195], v147 offset:2048
	ds_read_b128 v[204:207], v147 offset:3072
	ds_read_b128 v[208:211], v147 offset:4096
	ds_read_b128 v[212:215], v147 offset:5120
	ds_read_b128 v[216:219], v147 offset:6144
	ds_read_b128 v[220:223], v147 offset:7168
	global_load_lds_dwordx4 v[156:157], off
	v_lshl_add_u64 v[156:157], s[38:39], 0, v[138:139]
	s_add_i32 m0, s58, 0xe000
	s_nop 0
	global_load_lds_dwordx4 v[156:157], off
	s_waitcnt vmcnt(8)
	s_waitcnt lgkmcnt(0)
	s_barrier
	s_setprio 1
	s_waitcnt lgkmcnt(0)
	v_mfma_f32_16x16x32_bf16 v[128:131], v[140:143], v[184:187], 0
	v_mfma_f32_16x16x32_bf16 v[128:131], v[148:151], v[188:191], v[128:131]
	v_mfma_f32_16x16x32_bf16 v[124:127], v[152:155], v[184:187], 0
	v_mfma_f32_16x16x32_bf16 v[124:127], v[164:167], v[188:191], v[124:127]
	v_mfma_f32_16x16x32_bf16 v[120:123], v[140:143], v[192:195], 0
	v_mfma_f32_16x16x32_bf16 v[120:123], v[148:151], v[204:207], v[120:123]
	v_mfma_f32_16x16x32_bf16 v[112:115], v[152:155], v[192:195], 0
	v_mfma_f32_16x16x32_bf16 v[112:115], v[164:167], v[204:207], v[112:115]
	v_mfma_f32_16x16x32_bf16 v[104:107], v[140:143], v[208:211], 0
	v_mfma_f32_16x16x32_bf16 v[104:107], v[148:151], v[212:215], v[104:107]
	v_mfma_f32_16x16x32_bf16 v[96:99], v[152:155], v[208:211], 0
	v_mfma_f32_16x16x32_bf16 v[96:99], v[164:167], v[212:215], v[96:99]
	v_mfma_f32_16x16x32_bf16 v[88:91], v[140:143], v[216:219], 0
	v_mfma_f32_16x16x32_bf16 v[88:91], v[148:151], v[220:223], v[88:91]
	v_mfma_f32_16x16x32_bf16 v[80:83], v[152:155], v[216:219], 0
	v_mfma_f32_16x16x32_bf16 v[80:83], v[164:167], v[220:223], v[80:83]
	s_setprio 0
	s_setprio 1
	v_mfma_f32_16x16x32_bf16 v[116:119], v[168:171], v[184:187], 0
	v_mfma_f32_16x16x32_bf16 v[116:119], v[172:175], v[188:191], v[116:119]
	v_mfma_f32_16x16x32_bf16 v[108:111], v[176:179], v[184:187], 0
	v_mfma_f32_16x16x32_bf16 v[108:111], v[180:183], v[188:191], v[108:111]
	v_mfma_f32_16x16x32_bf16 v[100:103], v[168:171], v[192:195], 0
	v_mfma_f32_16x16x32_bf16 v[100:103], v[172:175], v[204:207], v[100:103]
	v_mfma_f32_16x16x32_bf16 v[92:95], v[176:179], v[192:195], 0
	v_mfma_f32_16x16x32_bf16 v[92:95], v[180:183], v[204:207], v[92:95]
	v_mfma_f32_16x16x32_bf16 v[84:87], v[168:171], v[208:211], 0
	v_mfma_f32_16x16x32_bf16 v[84:87], v[172:175], v[212:215], v[84:87]
	v_mfma_f32_16x16x32_bf16 v[76:79], v[176:179], v[208:211], 0
	v_mfma_f32_16x16x32_bf16 v[76:79], v[180:183], v[212:215], v[76:79]
	v_mfma_f32_16x16x32_bf16 v[72:75], v[168:171], v[216:219], 0
	v_mfma_f32_16x16x32_bf16 v[72:75], v[172:175], v[220:223], v[72:75]
	v_mfma_f32_16x16x32_bf16 v[68:71], v[176:179], v[216:219], 0
	v_mfma_f32_16x16x32_bf16 v[68:71], v[180:183], v[220:223], v[68:71]
	s_setprio 0
	s_barrier
	s_add_i32 s30, s31, s53
	v_lshl_add_u64 v[156:157], s[40:41], 0, v[2:3]
	s_mov_b32 m0, s30
	ds_read_b128 v[184:187], v147 offset:16384
	ds_read_b128 v[188:191], v147 offset:17408
	ds_read_b128 v[192:195], v147 offset:18432
	ds_read_b128 v[204:207], v147 offset:19456
	ds_read_b128 v[208:211], v147 offset:20480
	ds_read_b128 v[212:215], v147 offset:21504
	ds_read_b128 v[216:219], v147 offset:22528
	ds_read_b128 v[220:223], v147 offset:23552
	global_load_lds_dwordx4 v[156:157], off
	s_add_i32 m0, s30, 0x2000
	s_add_u32 s30, s40, 0x80000
	v_lshl_add_u64 v[196:197], s[40:41], 0, v[0:1]
	s_addc_u32 s31, s41, 0
	s_add_i32 s27, s27, s53
	global_load_lds_dwordx4 v[196:197], off
	v_lshl_add_u64 v[224:225], s[30:31], 0, v[2:3]
	s_mov_b32 m0, s27
	v_lshl_add_u64 v[226:227], s[42:43], 0, v[132:133]
	global_load_lds_dwordx4 v[224:225], off
	v_lshl_add_u64 v[224:225], s[30:31], 0, v[0:1]
	s_add_i32 m0, s27, 0x2000
	s_nop 0
	global_load_lds_dwordx4 v[224:225], off
	v_lshl_add_u64 v[224:225], s[42:43], 0, v[134:135]
	s_mov_b32 m0, s58
	s_nop 0
	global_load_lds_dwordx4 v[224:225], off
	s_mov_b32 m0, s59
	s_nop 0
	global_load_lds_dwordx4 v[226:227], off
	s_waitcnt vmcnt(8)
	s_waitcnt lgkmcnt(0)
	s_barrier
; #define PG8_STAGE(bufoff, gbase, voff) do { _Pragma("unroll") for (int _i = 0; _i < 2; ++_i) \
;         __builtin_amdgcn_global_load_lds((const unsigned*)((const char*)(gbase) + (voff)[_i]), (LAS unsigned*)(lds + (bufoff) + ldsw + _i * 8192), 16, 0, 0); } while (0)
; #define PG8_LDA(dst, b, h) do { _Pragma("unroll") for (int m = 0; m < 4; ++m) _Pragma("unroll") for (int k = 0; k < 2; ++k) dst[m][k] = *(const LAS bf16x8*)(lds + PG8_SA(b, h) + aoff + m * 2048 + k * 1024); } while (0)
; #define PG8_LDB(dst, b, h) do { _Pragma("unroll") for (int n = 0; n < 2; ++n) _Pragma("unroll") for (int k = 0; k < 2; ++k) dst[n][k] = *(const LAS bf16x8*)(lds + PG8_SB(b, h) + boff + n * 2048 + k * 1024); } while (0)
; #define PG8_MMA(ai, bj, At, Bt) do { __builtin_amdgcn_s_setprio(1); _Pragma("unroll") for (int m = 0; m < 4; ++m) _Pragma("unroll") for (int n = 0; n < 2; ++n) _Pragma("unroll") for (int k = 0; k < 2; ++k) \
;         acc[ai][bj][m][n] = __builtin_amdgcn_mfma_f32_16x16x32_bf16(Bt[n][k], At[m][k], acc[ai][bj][m][n], 0, 0, 0); __builtin_amdgcn_s_setprio(0); } while (0)
; #define PG8_WAIT_V(n) asm volatile("s_waitcnt vmcnt(" #n ")" ::: "memory")
; #define PG8_WAIT_L(n) asm volatile("s_waitcnt lgkmcnt(" #n ")" ::: "memory")
; #define PG8_BAR __builtin_amdgcn_s_barrier()
; #define PG8_SCHED __builtin_amdgcn_sched_barrier(0)
; template <class Epi, class Sched, bool ALIGN_EPI = true>
; __device__ __forceinline__ void gemm_phase(LAS unsigned char* lds, const Gemm g, const Sched& S, const Epi& E) {
;     ...
;             PG8_WAIT_V(8); PG8_WAIT_L(0); PG8_BAR; PG8_MMA(1, 0, At, B0); PG8_MMA(1, 1, At, B1); PG8_BAR; PG8_SCHED;
;             PG8_LDB(B0, 1, 0); PG8_LDB(B1, 1, 1); PG8_SCHED; PG8_LDA(At, 1, 0); PG8_STAGE(PG8_SA(0, 1), a2 + hA, voffA);
;             PG8_WAIT_V(8); PG8_WAIT_L(0); PG8_BAR; PG8_MMA(0, 0, At, B0); PG8_MMA(0, 1, At, B1); PG8_BAR; PG8_SCHED;
	s_setprio 1
	s_waitcnt lgkmcnt(0)
	v_mfma_f32_16x16x32_bf16 v[64:67], v[140:143], v[184:187], 0
	v_mfma_f32_16x16x32_bf16 v[64:67], v[148:151], v[188:191], v[64:67]
	v_mfma_f32_16x16x32_bf16 v[60:63], v[152:155], v[184:187], 0
	v_mfma_f32_16x16x32_bf16 v[60:63], v[164:167], v[188:191], v[60:63]
	v_mfma_f32_16x16x32_bf16 v[56:59], v[140:143], v[192:195], 0
	v_mfma_f32_16x16x32_bf16 v[56:59], v[148:151], v[204:207], v[56:59]
	v_mfma_f32_16x16x32_bf16 v[48:51], v[152:155], v[192:195], 0
	v_mfma_f32_16x16x32_bf16 v[48:51], v[164:167], v[204:207], v[48:51]
	v_mfma_f32_16x16x32_bf16 v[40:43], v[140:143], v[208:211], 0
	v_mfma_f32_16x16x32_bf16 v[40:43], v[148:151], v[212:215], v[40:43]
	v_mfma_f32_16x16x32_bf16 v[32:35], v[152:155], v[208:211], 0
	v_mfma_f32_16x16x32_bf16 v[32:35], v[164:167], v[212:215], v[32:35]
	v_mfma_f32_16x16x32_bf16 v[24:27], v[140:143], v[216:219], 0
	v_mfma_f32_16x16x32_bf16 v[24:27], v[148:151], v[220:223], v[24:27]
	v_mfma_f32_16x16x32_bf16 v[16:19], v[152:155], v[216:219], 0
	v_mfma_f32_16x16x32_bf16 v[16:19], v[164:167], v[220:223], v[16:19]
	s_setprio 0
	s_setprio 1
	v_mfma_f32_16x16x32_bf16 v[52:55], v[168:171], v[184:187], 0
	v_mfma_f32_16x16x32_bf16 v[52:55], v[172:175], v[188:191], v[52:55]
	v_mfma_f32_16x16x32_bf16 v[44:47], v[176:179], v[184:187], 0
	v_mfma_f32_16x16x32_bf16 v[44:47], v[180:183], v[188:191], v[44:47]
	v_mfma_f32_16x16x32_bf16 v[36:39], v[168:171], v[192:195], 0
	v_mfma_f32_16x16x32_bf16 v[36:39], v[172:175], v[204:207], v[36:39]
	v_mfma_f32_16x16x32_bf16 v[28:31], v[176:179], v[192:195], 0
	v_mfma_f32_16x16x32_bf16 v[28:31], v[180:183], v[204:207], v[28:31]
	v_mfma_f32_16x16x32_bf16 v[20:23], v[168:171], v[208:211], 0
	v_mfma_f32_16x16x32_bf16 v[20:23], v[172:175], v[212:215], v[20:23]
	v_mfma_f32_16x16x32_bf16 v[12:15], v[176:179], v[208:211], 0
	v_mfma_f32_16x16x32_bf16 v[12:15], v[180:183], v[212:215], v[12:15]
	v_mfma_f32_16x16x32_bf16 v[8:11], v[168:171], v[216:219], 0
	v_mfma_f32_16x16x32_bf16 v[8:11], v[172:175], v[220:223], v[8:11]
	v_mfma_f32_16x16x32_bf16 v[4:7], v[176:179], v[216:219], 0
	v_mfma_f32_16x16x32_bf16 v[4:7], v[180:183], v[220:223], v[4:7]
	s_setprio 0
	s_barrier
	s_add_i32 s27, 0, 0x18000
	v_add_u32_e32 v158, s27, v145
	s_add_i32 s65, 0, 0x1c000
	ds_read_b128 v[140:143], v158
	ds_read_b128 v[148:151], v158 offset:1024
	ds_read_b128 v[152:155], v158 offset:2048
	ds_read_b128 v[164:167], v158 offset:3072
	v_add_u32_e32 v158, s65, v145
	ds_read_b128 v[168:171], v158
	ds_read_b128 v[172:175], v158 offset:1024
	ds_read_b128 v[176:179], v158 offset:2048
	ds_read_b128 v[180:183], v158 offset:3072
	s_add_u32 s30, s42, 0x80000
	s_addc_u32 s31, s43, 0
	s_mov_b32 m0, s60
	v_lshl_add_u64 v[228:229], s[30:31], 0, v[134:135]
	ds_read_b128 v[184:187], v147 offset:32768
	ds_read_b128 v[188:191], v147 offset:33792
	ds_read_b128 v[192:195], v147 offset:34816
	ds_read_b128 v[204:207], v147 offset:35840
	ds_read_b128 v[208:211], v147 offset:36864
	ds_read_b128 v[212:215], v147 offset:37888
	ds_read_b128 v[216:219], v147 offset:38912
	ds_read_b128 v[220:223], v147 offset:39936
	global_load_lds_dwordx4 v[228:229], off
	v_lshl_add_u64 v[228:229], s[30:31], 0, v[132:133]
	s_mov_b32 m0, s61
	s_nop 0
	global_load_lds_dwordx4 v[228:229], off
	s_waitcnt vmcnt(8)
	s_waitcnt lgkmcnt(0)
	s_barrier
	s_setprio 1
	s_waitcnt lgkmcnt(0)
	v_mfma_f32_16x16x32_bf16 v[128:131], v[140:143], v[184:187], v[128:131]
	v_mfma_f32_16x16x32_bf16 v[128:131], v[148:151], v[188:191], v[128:131]
	v_mfma_f32_16x16x32_bf16 v[124:127], v[152:155], v[184:187], v[124:127]
	v_mfma_f32_16x16x32_bf16 v[124:127], v[164:167], v[188:191], v[124:127]
	v_mfma_f32_16x16x32_bf16 v[120:123], v[140:143], v[192:195], v[120:123]
	v_mfma_f32_16x16x32_bf16 v[120:123], v[148:151], v[204:207], v[120:123]
	v_mfma_f32_16x16x32_bf16 v[112:115], v[152:155], v[192:195], v[112:115]
	v_mfma_f32_16x16x32_bf16 v[112:115], v[164:167], v[204:207], v[112:115]
	v_mfma_f32_16x16x32_bf16 v[104:107], v[140:143], v[208:211], v[104:107]
	v_mfma_f32_16x16x32_bf16 v[104:107], v[148:151], v[212:215], v[104:107]
	v_mfma_f32_16x16x32_bf16 v[96:99], v[152:155], v[208:211], v[96:99]
	v_mfma_f32_16x16x32_bf16 v[96:99], v[164:167], v[212:215], v[96:99]
	v_mfma_f32_16x16x32_bf16 v[88:91], v[140:143], v[216:219], v[88:91]
	v_mfma_f32_16x16x32_bf16 v[88:91], v[148:151], v[220:223], v[88:91]
	v_mfma_f32_16x16x32_bf16 v[80:83], v[152:155], v[216:219], v[80:83]
	v_mfma_f32_16x16x32_bf16 v[80:83], v[164:167], v[220:223], v[80:83]
	s_setprio 0
	s_setprio 1
	v_mfma_f32_16x16x32_bf16 v[116:119], v[168:171], v[184:187], v[116:119]
	v_mfma_f32_16x16x32_bf16 v[116:119], v[172:175], v[188:191], v[116:119]
	v_mfma_f32_16x16x32_bf16 v[108:111], v[176:179], v[184:187], v[108:111]
	v_mfma_f32_16x16x32_bf16 v[108:111], v[180:183], v[188:191], v[108:111]
	v_mfma_f32_16x16x32_bf16 v[100:103], v[168:171], v[192:195], v[100:103]
	v_mfma_f32_16x16x32_bf16 v[100:103], v[172:175], v[204:207], v[100:103]
	v_mfma_f32_16x16x32_bf16 v[92:95], v[176:179], v[192:195], v[92:95]
	v_mfma_f32_16x16x32_bf16 v[92:95], v[180:183], v[204:207], v[92:95]
	v_mfma_f32_16x16x32_bf16 v[84:87], v[168:171], v[208:211], v[84:87]
	v_mfma_f32_16x16x32_bf16 v[84:87], v[172:175], v[212:215], v[84:87]
	v_mfma_f32_16x16x32_bf16 v[76:79], v[176:179], v[208:211], v[76:79]
	v_mfma_f32_16x16x32_bf16 v[76:79], v[180:183], v[212:215], v[76:79]
	v_mfma_f32_16x16x32_bf16 v[72:75], v[168:171], v[216:219], v[72:75]
	v_mfma_f32_16x16x32_bf16 v[72:75], v[172:175], v[220:223], v[72:75]
	v_mfma_f32_16x16x32_bf16 v[68:71], v[176:179], v[216:219], v[68:71]
	v_mfma_f32_16x16x32_bf16 v[68:71], v[180:183], v[220:223], v[68:71]
	s_setprio 0
	s_barrier
; #define PG8_STAGE(bufoff, gbase, voff) do { _Pragma("unroll") for (int _i = 0; _i < 2; ++_i) \
;         __builtin_amdgcn_global_load_lds((const unsigned*)((const char*)(gbase) + (voff)[_i]), (LAS unsigned*)(lds + (bufoff) + ldsw + _i * 8192), 16, 0, 0); } while (0)
; #define PG8_LDA(dst, b, h) do { _Pragma("unroll") for (int m = 0; m < 4; ++m) _Pragma("unroll") for (int k = 0; k < 2; ++k) dst[m][k] = *(const LAS bf16x8*)(lds + PG8_SA(b, h) + aoff + m * 2048 + k * 1024); } while (0)
; #define PG8_LDB(dst, b, h) do { _Pragma("unroll") for (int n = 0; n < 2; ++n) _Pragma("unroll") for (int k = 0; k < 2; ++k) dst[n][k] = *(const LAS bf16x8*)(lds + PG8_SB(b, h) + boff + n * 2048 + k * 1024); } while (0)
; #define PG8_MMA(ai, bj, At, Bt) do { __builtin_amdgcn_s_setprio(1); _Pragma("unroll") for (int m = 0; m < 4; ++m) _Pragma("unroll") for (int n = 0; n < 2; ++n) _Pragma("unroll") for (int k = 0; k < 2; ++k) \
;         acc[ai][bj][m][n] = __builtin_amdgcn_mfma_f32_16x16x32_bf16(Bt[n][k], At[m][k], acc[ai][bj][m][n], 0, 0, 0); __builtin_amdgcn_s_setprio(0); } while (0)
; #define PG8_WAIT_V(n) asm volatile("s_waitcnt vmcnt(" #n ")" ::: "memory")
; #define PG8_WAIT_L(n) asm volatile("s_waitcnt lgkmcnt(" #n ")" ::: "memory")
; #define PG8_BAR __builtin_amdgcn_s_barrier()
; #define PG8_SCHED __builtin_amdgcn_sched_barrier(0)
; template <class Epi, class Sched, bool ALIGN_EPI = true>
; __device__ __forceinline__ void gemm_phase(LAS unsigned char* lds, const Gemm g, const Sched& S, const Epi& E) {
;     ...
;         for (int t = 0; t < nt; t += 2) {
;             const bool last = (t == nt - 2);
;             const char* a1 = cA + (size_t)(t + 1) * kstep;
;             const char* a2 = last ? nA : cA + (size_t)(t + 2) * kstep; const char* b2 = last ? nB : cB + (size_t)(t + 2) * kstep;
;             const char* a3 = a2 + kstep; const char* b3 = b2 + kstep;
;             PG8_LDB(B0, 0, 0); PG8_LDB(B1, 0, 1); PG8_SCHED; PG8_LDA(At, 0, 0); PG8_STAGE(PG8_SA(1, 1), a1 + hA, voffA);
;             PG8_WAIT_V(8); PG8_WAIT_L(0); PG8_BAR; PG8_MMA(0, 0, At, B0); PG8_MMA(0, 1, At, B1); PG8_BAR; PG8_SCHED;
;     ...
;             PG8_LDA(At, 1, 1); PG8_STAGE(PG8_SB(1, 0), b3, voffB); PG8_STAGE(PG8_SB(1, 1), b3 + hB, voffB); PG8_STAGE(PG8_SA(1, 0), a3, voffA);
;             PG8_WAIT_V(8); PG8_WAIT_L(0); PG8_BAR; PG8_MMA(1, 0, At, B0); PG8_MMA(1, 1, At, B1); PG8_BAR; PG8_SCHED;
	s_add_i32 s27, s27, s53
	v_lshl_add_u64 v[156:157], v[156:157], 0, s[86:87]
	s_mov_b32 m0, s27
	ds_read_b128 v[184:187], v147 offset:49152
	ds_read_b128 v[188:191], v147 offset:50176
	ds_read_b128 v[192:195], v147 offset:51200
	ds_read_b128 v[204:207], v147 offset:52224
	ds_read_b128 v[208:211], v147 offset:53248
	ds_read_b128 v[212:215], v147 offset:54272
	ds_read_b128 v[216:219], v147 offset:55296
	ds_read_b128 v[220:223], v147 offset:56320
	global_load_lds_dwordx4 v[156:157], off
	s_add_i32 m0, s27, 0x2000
	s_add_u32 s30, s40, 0x80080
	v_lshl_add_u64 v[156:157], v[196:197], 0, s[86:87]
	s_addc_u32 s31, s41, 0
	s_add_i32 s27, s65, s53
	global_load_lds_dwordx4 v[156:157], off
	v_lshl_add_u64 v[156:157], s[30:31], 0, v[2:3]
	s_mov_b32 m0, s27
	s_nop 0
	global_load_lds_dwordx4 v[156:157], off
	v_lshl_add_u64 v[156:157], s[30:31], 0, v[0:1]
	s_add_i32 m0, s27, 0x2000
	s_nop 0
	global_load_lds_dwordx4 v[156:157], off
	v_lshl_add_u64 v[156:157], v[224:225], 0, s[86:87]
	s_mov_b32 m0, s62
	s_nop 0
	global_load_lds_dwordx4 v[156:157], off
	v_lshl_add_u64 v[156:157], v[226:227], 0, s[86:87]
	s_mov_b32 m0, s63
	s_nop 0
	global_load_lds_dwordx4 v[156:157], off
	s_waitcnt vmcnt(8)
	s_waitcnt lgkmcnt(0)
	s_barrier
	s_setprio 1
	s_waitcnt lgkmcnt(0)
	v_mfma_f32_16x16x32_bf16 v[64:67], v[140:143], v[184:187], v[64:67]
	v_mfma_f32_16x16x32_bf16 v[64:67], v[148:151], v[188:191], v[64:67]
	v_mfma_f32_16x16x32_bf16 v[60:63], v[152:155], v[184:187], v[60:63]
	v_mfma_f32_16x16x32_bf16 v[60:63], v[164:167], v[188:191], v[60:63]
	v_mfma_f32_16x16x32_bf16 v[56:59], v[140:143], v[192:195], v[56:59]
	v_mfma_f32_16x16x32_bf16 v[56:59], v[148:151], v[204:207], v[56:59]
	v_mfma_f32_16x16x32_bf16 v[48:51], v[152:155], v[192:195], v[48:51]
	v_mfma_f32_16x16x32_bf16 v[48:51], v[164:167], v[204:207], v[48:51]
	v_mfma_f32_16x16x32_bf16 v[40:43], v[140:143], v[208:211], v[40:43]
	v_mfma_f32_16x16x32_bf16 v[40:43], v[148:151], v[212:215], v[40:43]
	v_mfma_f32_16x16x32_bf16 v[32:35], v[152:155], v[208:211], v[32:35]
	v_mfma_f32_16x16x32_bf16 v[32:35], v[164:167], v[212:215], v[32:35]
	v_mfma_f32_16x16x32_bf16 v[24:27], v[140:143], v[216:219], v[24:27]
	v_mfma_f32_16x16x32_bf16 v[24:27], v[148:151], v[220:223], v[24:27]
	v_mfma_f32_16x16x32_bf16 v[16:19], v[152:155], v[216:219], v[16:19]
	v_mfma_f32_16x16x32_bf16 v[16:19], v[164:167], v[220:223], v[16:19]
	s_setprio 0
	s_setprio 1
	v_mfma_f32_16x16x32_bf16 v[52:55], v[168:171], v[184:187], v[52:55]
	v_mfma_f32_16x16x32_bf16 v[52:55], v[172:175], v[188:191], v[52:55]
	v_mfma_f32_16x16x32_bf16 v[44:47], v[176:179], v[184:187], v[44:47]
	v_mfma_f32_16x16x32_bf16 v[44:47], v[180:183], v[188:191], v[44:47]
	v_mfma_f32_16x16x32_bf16 v[36:39], v[168:171], v[192:195], v[36:39]
	v_mfma_f32_16x16x32_bf16 v[36:39], v[172:175], v[204:207], v[36:39]
	v_mfma_f32_16x16x32_bf16 v[28:31], v[176:179], v[192:195], v[28:31]
	v_mfma_f32_16x16x32_bf16 v[28:31], v[180:183], v[204:207], v[28:31]
	v_mfma_f32_16x16x32_bf16 v[20:23], v[168:171], v[208:211], v[20:23]
	v_mfma_f32_16x16x32_bf16 v[20:23], v[172:175], v[212:215], v[20:23]
	v_mfma_f32_16x16x32_bf16 v[12:15], v[176:179], v[208:211], v[12:15]
	v_mfma_f32_16x16x32_bf16 v[12:15], v[180:183], v[212:215], v[12:15]
	v_mfma_f32_16x16x32_bf16 v[8:11], v[168:171], v[216:219], v[8:11]
	v_mfma_f32_16x16x32_bf16 v[8:11], v[172:175], v[220:223], v[8:11]
	v_mfma_f32_16x16x32_bf16 v[4:7], v[176:179], v[216:219], v[4:7]
	v_mfma_f32_16x16x32_bf16 v[4:7], v[180:183], v[220:223], v[4:7]
	s_setprio 0
	s_barrier
	s_add_i32 s26, s26, 2
	s_add_u32 s38, s38, 0x100
	s_addc_u32 s39, s39, 0
	s_add_u32 s24, s24, 0x100
	s_addc_u32 s25, s25, 0
	s_cmp_gt_u32 s26, 29
	s_cbranch_scc1 .Lpeel_exit_218
.LBB0_218:
	s_add_u32 s27, s38, 0xfff80080
	s_addc_u32 s30, s39, -1
	s_add_i32 s31, 0, 0x10000
	s_cmp_eq_u32 s26, 28
	s_cselect_b32 s43, s11, s30
	s_cselect_b32 s42, s18, s27
	v_add_u32_e32 v156, s31, v145
	s_cselect_b32 s41, s9, s25
	s_cselect_b32 s40, s19, s24
	s_add_i32 s27, 0, 0x14000
	ds_read_b128 v[140:143], v156
	ds_read_b128 v[148:151], v156 offset:1024
	ds_read_b128 v[152:155], v156 offset:2048
	ds_read_b128 v[164:167], v156 offset:3072
	v_add_u32_e32 v156, s27, v145
	ds_read_b128 v[168:171], v156
	ds_read_b128 v[172:175], v156 offset:1024
	ds_read_b128 v[176:179], v156 offset:2048
	ds_read_b128 v[180:183], v156 offset:3072
	v_lshl_add_u64 v[156:157], s[38:39], 0, v[136:137]
	s_add_i32 m0, s58, 0xc000
	ds_read_b128 v[184:187], v147
	ds_read_b128 v[188:191], v147 offset:1024
	ds_read_b128 v[192:195], v147 offset:2048
	ds_read_b128 v[204:207], v147 offset:3072
	ds_read_b128 v[208:211], v147 offset:4096
	ds_read_b128 v[212:215], v147 offset:5120
	ds_read_b128 v[216:219], v147 offset:6144
	ds_read_b128 v[220:223], v147 offset:7168
	global_load_lds_dwordx4 v[156:157], off
	v_lshl_add_u64 v[156:157], s[38:39], 0, v[138:139]
	s_add_i32 m0, s58, 0xe000
	s_nop 0
	global_load_lds_dwordx4 v[156:157], off
	s_waitcnt vmcnt(8)
	s_waitcnt lgkmcnt(0)
	s_barrier
; #define PG8_STAGE(bufoff, gbase, voff) do { _Pragma("unroll") for (int _i = 0; _i < 2; ++_i) \
;         __builtin_amdgcn_global_load_lds((const unsigned*)((const char*)(gbase) + (voff)[_i]), (LAS unsigned*)(lds + (bufoff) + ldsw + _i * 8192), 16, 0, 0); } while (0)
; #define PG8_LDA(dst, b, h) do { _Pragma("unroll") for (int m = 0; m < 4; ++m) _Pragma("unroll") for (int k = 0; k < 2; ++k) dst[m][k] = *(const LAS bf16x8*)(lds + PG8_SA(b, h) + aoff + m * 2048 + k * 1024); } while (0)
; #define PG8_MMA(ai, bj, At, Bt) do { __builtin_amdgcn_s_setprio(1); _Pragma("unroll") for (int m = 0; m < 4; ++m) _Pragma("unroll") for (int n = 0; n < 2; ++n) _Pragma("unroll") for (int k = 0; k < 2; ++k) \
;         acc[ai][bj][m][n] = __builtin_amdgcn_mfma_f32_16x16x32_bf16(Bt[n][k], At[m][k], acc[ai][bj][m][n], 0, 0, 0); __builtin_amdgcn_s_setprio(0); } while (0)
; #define PG8_WAIT_V(n) asm volatile("s_waitcnt vmcnt(" #n ")" ::: "memory")
; #define PG8_WAIT_L(n) asm volatile("s_waitcnt lgkmcnt(" #n ")" ::: "memory")
; #define PG8_BAR __builtin_amdgcn_s_barrier()
; #define PG8_SCHED __builtin_amdgcn_sched_barrier(0)
; template <class Epi, class Sched, bool ALIGN_EPI = true>
; __device__ __forceinline__ void gemm_phase(LAS unsigned char* lds, const Gemm g, const Sched& S, const Epi& E) {
;     ...
;             PG8_WAIT_V(8); PG8_WAIT_L(0); PG8_BAR; PG8_MMA(0, 0, At, B0); PG8_MMA(0, 1, At, B1); PG8_BAR; PG8_SCHED;
;             PG8_LDA(At, 0, 1); PG8_STAGE(PG8_SB(0, 0), b2, voffB); PG8_STAGE(PG8_SB(0, 1), b2 + hB, voffB); PG8_STAGE(PG8_SA(0, 0), a2, voffA);
;             PG8_WAIT_V(8); PG8_WAIT_L(0); PG8_BAR; PG8_MMA(1, 0, At, B0); PG8_MMA(1, 1, At, B1); PG8_BAR; PG8_SCHED;
	s_setprio 1
	s_waitcnt lgkmcnt(0)
	v_mfma_f32_16x16x32_bf16 v[128:131], v[140:143], v[184:187], v[128:131]
	v_mfma_f32_16x16x32_bf16 v[128:131], v[148:151], v[188:191], v[128:131]
	v_mfma_f32_16x16x32_bf16 v[124:127], v[152:155], v[184:187], v[124:127]
	v_mfma_f32_16x16x32_bf16 v[124:127], v[164:167], v[188:191], v[124:127]
	v_mfma_f32_16x16x32_bf16 v[120:123], v[140:143], v[192:195], v[120:123]
	v_mfma_f32_16x16x32_bf16 v[120:123], v[148:151], v[204:207], v[120:123]
	v_mfma_f32_16x16x32_bf16 v[112:115], v[152:155], v[192:195], v[112:115]
	v_mfma_f32_16x16x32_bf16 v[112:115], v[164:167], v[204:207], v[112:115]
	v_mfma_f32_16x16x32_bf16 v[104:107], v[140:143], v[208:211], v[104:107]
	v_mfma_f32_16x16x32_bf16 v[104:107], v[148:151], v[212:215], v[104:107]
	v_mfma_f32_16x16x32_bf16 v[96:99], v[152:155], v[208:211], v[96:99]
	v_mfma_f32_16x16x32_bf16 v[96:99], v[164:167], v[212:215], v[96:99]
	v_mfma_f32_16x16x32_bf16 v[88:91], v[140:143], v[216:219], v[88:91]
	v_mfma_f32_16x16x32_bf16 v[88:91], v[148:151], v[220:223], v[88:91]
	v_mfma_f32_16x16x32_bf16 v[80:83], v[152:155], v[216:219], v[80:83]
	v_mfma_f32_16x16x32_bf16 v[80:83], v[164:167], v[220:223], v[80:83]
	s_setprio 0
	s_setprio 1
	v_mfma_f32_16x16x32_bf16 v[116:119], v[168:171], v[184:187], v[116:119]
	v_mfma_f32_16x16x32_bf16 v[116:119], v[172:175], v[188:191], v[116:119]
	v_mfma_f32_16x16x32_bf16 v[108:111], v[176:179], v[184:187], v[108:111]
	v_mfma_f32_16x16x32_bf16 v[108:111], v[180:183], v[188:191], v[108:111]
	v_mfma_f32_16x16x32_bf16 v[100:103], v[168:171], v[192:195], v[100:103]
	v_mfma_f32_16x16x32_bf16 v[100:103], v[172:175], v[204:207], v[100:103]
	v_mfma_f32_16x16x32_bf16 v[92:95], v[176:179], v[192:195], v[92:95]
	v_mfma_f32_16x16x32_bf16 v[92:95], v[180:183], v[204:207], v[92:95]
	v_mfma_f32_16x16x32_bf16 v[84:87], v[168:171], v[208:211], v[84:87]
	v_mfma_f32_16x16x32_bf16 v[84:87], v[172:175], v[212:215], v[84:87]
	v_mfma_f32_16x16x32_bf16 v[76:79], v[176:179], v[208:211], v[76:79]
	v_mfma_f32_16x16x32_bf16 v[76:79], v[180:183], v[212:215], v[76:79]
	v_mfma_f32_16x16x32_bf16 v[72:75], v[168:171], v[216:219], v[72:75]
	v_mfma_f32_16x16x32_bf16 v[72:75], v[172:175], v[220:223], v[72:75]
	v_mfma_f32_16x16x32_bf16 v[68:71], v[176:179], v[216:219], v[68:71]
	v_mfma_f32_16x16x32_bf16 v[68:71], v[180:183], v[220:223], v[68:71]
	s_setprio 0
	s_barrier
	s_add_i32 s30, s31, s53
	v_lshl_add_u64 v[156:157], s[40:41], 0, v[2:3]
	s_mov_b32 m0, s30
	ds_read_b128 v[184:187], v147 offset:16384
	ds_read_b128 v[188:191], v147 offset:17408
	ds_read_b128 v[192:195], v147 offset:18432
	ds_read_b128 v[204:207], v147 offset:19456
	ds_read_b128 v[208:211], v147 offset:20480
	ds_read_b128 v[212:215], v147 offset:21504
	ds_read_b128 v[216:219], v147 offset:22528
	ds_read_b128 v[220:223], v147 offset:23552
	global_load_lds_dwordx4 v[156:157], off
	s_add_i32 m0, s30, 0x2000
	s_add_u32 s30, s40, 0x80000
	v_lshl_add_u64 v[196:197], s[40:41], 0, v[0:1]
	s_addc_u32 s31, s41, 0
	s_add_i32 s27, s27, s53
	global_load_lds_dwordx4 v[196:197], off
	v_lshl_add_u64 v[224:225], s[30:31], 0, v[2:3]
	s_mov_b32 m0, s27
	v_lshl_add_u64 v[226:227], s[42:43], 0, v[132:133]
	global_load_lds_dwordx4 v[224:225], off
	v_lshl_add_u64 v[224:225], s[30:31], 0, v[0:1]
	s_add_i32 m0, s27, 0x2000
	s_nop 0
	global_load_lds_dwordx4 v[224:225], off
	v_lshl_add_u64 v[224:225], s[42:43], 0, v[134:135]
	s_mov_b32 m0, s58
	s_nop 0
	global_load_lds_dwordx4 v[224:225], off
	s_mov_b32 m0, s59
	s_nop 0
	global_load_lds_dwordx4 v[226:227], off
	s_waitcnt vmcnt(8)
	s_waitcnt lgkmcnt(0)
	s_barrier
	s_setprio 1
	s_waitcnt lgkmcnt(0)
	v_mfma_f32_16x16x32_bf16 v[64:67], v[140:143], v[184:187], v[64:67]
	v_mfma_f32_16x16x32_bf16 v[64:67], v[148:151], v[188:191], v[64:67]
	v_mfma_f32_16x16x32_bf16 v[60:63], v[152:155], v[184:187], v[60:63]
	v_mfma_f32_16x16x32_bf16 v[60:63], v[164:167], v[188:191], v[60:63]
	v_mfma_f32_16x16x32_bf16 v[56:59], v[140:143], v[192:195], v[56:59]
	v_mfma_f32_16x16x32_bf16 v[56:59], v[148:151], v[204:207], v[56:59]
	v_mfma_f32_16x16x32_bf16 v[48:51], v[152:155], v[192:195], v[48:51]
	v_mfma_f32_16x16x32_bf16 v[48:51], v[164:167], v[204:207], v[48:51]
	v_mfma_f32_16x16x32_bf16 v[40:43], v[140:143], v[208:211], v[40:43]
	v_mfma_f32_16x16x32_bf16 v[40:43], v[148:151], v[212:215], v[40:43]
	v_mfma_f32_16x16x32_bf16 v[32:35], v[152:155], v[208:211], v[32:35]
	v_mfma_f32_16x16x32_bf16 v[32:35], v[164:167], v[212:215], v[32:35]
	v_mfma_f32_16x16x32_bf16 v[24:27], v[140:143], v[216:219], v[24:27]
	v_mfma_f32_16x16x32_bf16 v[24:27], v[148:151], v[220:223], v[24:27]
	v_mfma_f32_16x16x32_bf16 v[16:19], v[152:155], v[216:219], v[16:19]
	v_mfma_f32_16x16x32_bf16 v[16:19], v[164:167], v[220:223], v[16:19]
	s_setprio 0
	s_setprio 1
	v_mfma_f32_16x16x32_bf16 v[52:55], v[168:171], v[184:187], v[52:55]
	v_mfma_f32_16x16x32_bf16 v[52:55], v[172:175], v[188:191], v[52:55]
	v_mfma_f32_16x16x32_bf16 v[44:47], v[176:179], v[184:187], v[44:47]
	v_mfma_f32_16x16x32_bf16 v[44:47], v[180:183], v[188:191], v[44:47]
	v_mfma_f32_16x16x32_bf16 v[36:39], v[168:171], v[192:195], v[36:39]
	v_mfma_f32_16x16x32_bf16 v[36:39], v[172:175], v[204:207], v[36:39]
	v_mfma_f32_16x16x32_bf16 v[28:31], v[176:179], v[192:195], v[28:31]
	v_mfma_f32_16x16x32_bf16 v[28:31], v[180:183], v[204:207], v[28:31]
	v_mfma_f32_16x16x32_bf16 v[20:23], v[168:171], v[208:211], v[20:23]
	v_mfma_f32_16x16x32_bf16 v[20:23], v[172:175], v[212:215], v[20:23]
	v_mfma_f32_16x16x32_bf16 v[12:15], v[176:179], v[208:211], v[12:15]
	v_mfma_f32_16x16x32_bf16 v[12:15], v[180:183], v[212:215], v[12:15]
	v_mfma_f32_16x16x32_bf16 v[8:11], v[168:171], v[216:219], v[8:11]
	v_mfma_f32_16x16x32_bf16 v[8:11], v[172:175], v[220:223], v[8:11]
	v_mfma_f32_16x16x32_bf16 v[4:7], v[176:179], v[216:219], v[4:7]
	v_mfma_f32_16x16x32_bf16 v[4:7], v[180:183], v[220:223], v[4:7]
	s_setprio 0
	s_barrier
; #define PG8_STAGE(bufoff, gbase, voff) do { _Pragma("unroll") for (int _i = 0; _i < 2; ++_i) \
;         __builtin_amdgcn_global_load_lds((const unsigned*)((const char*)(gbase) + (voff)[_i]), (LAS unsigned*)(lds + (bufoff) + ldsw + _i * 8192), 16, 0, 0); } while (0)
; #define PG8_LDA(dst, b, h) do { _Pragma("unroll") for (int m = 0; m < 4; ++m) _Pragma("unroll") for (int k = 0; k < 2; ++k) dst[m][k] = *(const LAS bf16x8*)(lds + PG8_SA(b, h) + aoff + m * 2048 + k * 1024); } while (0)
; #define PG8_LDB(dst, b, h) do { _Pragma("unroll") for (int n = 0; n < 2; ++n) _Pragma("unroll") for (int k = 0; k < 2; ++k) dst[n][k] = *(const LAS bf16x8*)(lds + PG8_SB(b, h) + boff + n * 2048 + k * 1024); } while (0)
; #define PG8_MMA(ai, bj, At, Bt) do { __builtin_amdgcn_s_setprio(1); _Pragma("unroll") for (int m = 0; m < 4; ++m) _Pragma("unroll") for (int n = 0; n < 2; ++n) _Pragma("unroll") for (int k = 0; k < 2; ++k) \
;         acc[ai][bj][m][n] = __builtin_amdgcn_mfma_f32_16x16x32_bf16(Bt[n][k], At[m][k], acc[ai][bj][m][n], 0, 0, 0); __builtin_amdgcn_s_setprio(0); } while (0)
; #define PG8_WAIT_V(n) asm volatile("s_waitcnt vmcnt(" #n ")" ::: "memory")
; #define PG8_WAIT_L(n) asm volatile("s_waitcnt lgkmcnt(" #n ")" ::: "memory")
; #define PG8_BAR __builtin_amdgcn_s_barrier()
; #define PG8_SCHED __builtin_amdgcn_sched_barrier(0)
; template <class Epi, class Sched, bool ALIGN_EPI = true>
; __device__ __forceinline__ void gemm_phase(LAS unsigned char* lds, const Gemm g, const Sched& S, const Epi& E) {
;     ...
;             PG8_LDB(B0, 1, 0); PG8_LDB(B1, 1, 1); PG8_SCHED; PG8_LDA(At, 1, 0); PG8_STAGE(PG8_SA(0, 1), a2 + hA, voffA);
;             PG8_WAIT_V(8); PG8_WAIT_L(0); PG8_BAR; PG8_MMA(0, 0, At, B0); PG8_MMA(0, 1, At, B1); PG8_BAR; PG8_SCHED;
	s_add_i32 s27, 0, 0x18000
	v_add_u32_e32 v158, s27, v145
	s_add_i32 s65, 0, 0x1c000
	ds_read_b128 v[140:143], v158
	ds_read_b128 v[148:151], v158 offset:1024
	ds_read_b128 v[152:155], v158 offset:2048
	ds_read_b128 v[164:167], v158 offset:3072
	v_add_u32_e32 v158, s65, v145
	ds_read_b128 v[168:171], v158
	ds_read_b128 v[172:175], v158 offset:1024
	ds_read_b128 v[176:179], v158 offset:2048
	ds_read_b128 v[180:183], v158 offset:3072
	s_add_u32 s30, s42, 0x80000
	s_addc_u32 s31, s43, 0
	s_mov_b32 m0, s60
	v_lshl_add_u64 v[228:229], s[30:31], 0, v[134:135]
	ds_read_b128 v[184:187], v147 offset:32768
	ds_read_b128 v[188:191], v147 offset:33792
	ds_read_b128 v[192:195], v147 offset:34816
	ds_read_b128 v[204:207], v147 offset:35840
	ds_read_b128 v[208:211], v147 offset:36864
	ds_read_b128 v[212:215], v147 offset:37888
	ds_read_b128 v[216:219], v147 offset:38912
	ds_read_b128 v[220:223], v147 offset:39936
	global_load_lds_dwordx4 v[228:229], off
	v_lshl_add_u64 v[228:229], s[30:31], 0, v[132:133]
	s_mov_b32 m0, s61
	s_nop 0
	global_load_lds_dwordx4 v[228:229], off
	s_waitcnt vmcnt(8)
	s_waitcnt lgkmcnt(0)
	s_barrier
	s_setprio 1
	s_waitcnt lgkmcnt(0)
	v_mfma_f32_16x16x32_bf16 v[128:131], v[140:143], v[184:187], v[128:131]
	v_mfma_f32_16x16x32_bf16 v[128:131], v[148:151], v[188:191], v[128:131]
	v_mfma_f32_16x16x32_bf16 v[124:127], v[152:155], v[184:187], v[124:127]
	v_mfma_f32_16x16x32_bf16 v[124:127], v[164:167], v[188:191], v[124:127]
	v_mfma_f32_16x16x32_bf16 v[120:123], v[140:143], v[192:195], v[120:123]
	v_mfma_f32_16x16x32_bf16 v[120:123], v[148:151], v[204:207], v[120:123]
	v_mfma_f32_16x16x32_bf16 v[112:115], v[152:155], v[192:195], v[112:115]
	v_mfma_f32_16x16x32_bf16 v[112:115], v[164:167], v[204:207], v[112:115]
	v_mfma_f32_16x16x32_bf16 v[104:107], v[140:143], v[208:211], v[104:107]
	v_mfma_f32_16x16x32_bf16 v[104:107], v[148:151], v[212:215], v[104:107]
	v_mfma_f32_16x16x32_bf16 v[96:99], v[152:155], v[208:211], v[96:99]
	v_mfma_f32_16x16x32_bf16 v[96:99], v[164:167], v[212:215], v[96:99]
	v_mfma_f32_16x16x32_bf16 v[88:91], v[140:143], v[216:219], v[88:91]
	v_mfma_f32_16x16x32_bf16 v[88:91], v[148:151], v[220:223], v[88:91]
	v_mfma_f32_16x16x32_bf16 v[80:83], v[152:155], v[216:219], v[80:83]
	v_mfma_f32_16x16x32_bf16 v[80:83], v[164:167], v[220:223], v[80:83]
	s_setprio 0
	s_setprio 1
	v_mfma_f32_16x16x32_bf16 v[116:119], v[168:171], v[184:187], v[116:119]
	v_mfma_f32_16x16x32_bf16 v[116:119], v[172:175], v[188:191], v[116:119]
	v_mfma_f32_16x16x32_bf16 v[108:111], v[176:179], v[184:187], v[108:111]
	v_mfma_f32_16x16x32_bf16 v[108:111], v[180:183], v[188:191], v[108:111]
	v_mfma_f32_16x16x32_bf16 v[100:103], v[168:171], v[192:195], v[100:103]
	v_mfma_f32_16x16x32_bf16 v[100:103], v[172:175], v[204:207], v[100:103]
	v_mfma_f32_16x16x32_bf16 v[92:95], v[176:179], v[192:195], v[92:95]
	v_mfma_f32_16x16x32_bf16 v[92:95], v[180:183], v[204:207], v[92:95]
	v_mfma_f32_16x16x32_bf16 v[84:87], v[168:171], v[208:211], v[84:87]
	v_mfma_f32_16x16x32_bf16 v[84:87], v[172:175], v[212:215], v[84:87]
	v_mfma_f32_16x16x32_bf16 v[76:79], v[176:179], v[208:211], v[76:79]
	v_mfma_f32_16x16x32_bf16 v[76:79], v[180:183], v[212:215], v[76:79]
	v_mfma_f32_16x16x32_bf16 v[72:75], v[168:171], v[216:219], v[72:75]
	v_mfma_f32_16x16x32_bf16 v[72:75], v[172:175], v[220:223], v[72:75]
	v_mfma_f32_16x16x32_bf16 v[68:71], v[176:179], v[216:219], v[68:71]
	v_mfma_f32_16x16x32_bf16 v[68:71], v[180:183], v[220:223], v[68:71]
	s_setprio 0
	s_barrier
; #define PG8_STAGE(bufoff, gbase, voff) do { _Pragma("unroll") for (int _i = 0; _i < 2; ++_i) \
;         __builtin_amdgcn_global_load_lds((const unsigned*)((const char*)(gbase) + (voff)[_i]), (LAS unsigned*)(lds + (bufoff) + ldsw + _i * 8192), 16, 0, 0); } while (0)
; #define PG8_LDA(dst, b, h) do { _Pragma("unroll") for (int m = 0; m < 4; ++m) _Pragma("unroll") for (int k = 0; k < 2; ++k) dst[m][k] = *(const LAS bf16x8*)(lds + PG8_SA(b, h) + aoff + m * 2048 + k * 1024); } while (0)
; #define PG8_MMA(ai, bj, At, Bt) do { __builtin_amdgcn_s_setprio(1); _Pragma("unroll") for (int m = 0; m < 4; ++m) _Pragma("unroll") for (int n = 0; n < 2; ++n) _Pragma("unroll") for (int k = 0; k < 2; ++k) \
;         acc[ai][bj][m][n] = __builtin_amdgcn_mfma_f32_16x16x32_bf16(Bt[n][k], At[m][k], acc[ai][bj][m][n], 0, 0, 0); __builtin_amdgcn_s_setprio(0); } while (0)
; #define PG8_WAIT_V(n) asm volatile("s_waitcnt vmcnt(" #n ")" ::: "memory")
; #define PG8_WAIT_L(n) asm volatile("s_waitcnt lgkmcnt(" #n ")" ::: "memory")
; #define PG8_BAR __builtin_amdgcn_s_barrier()
; #define PG8_SCHED __builtin_amdgcn_sched_barrier(0)
; template <class Epi, class Sched, bool ALIGN_EPI = true>
; __device__ __forceinline__ void gemm_phase(LAS unsigned char* lds, const Gemm g, const Sched& S, const Epi& E) {
;     ...
;             PG8_LDA(At, 1, 1); PG8_STAGE(PG8_SB(1, 0), b3, voffB); PG8_STAGE(PG8_SB(1, 1), b3 + hB, voffB); PG8_STAGE(PG8_SA(1, 0), a3, voffA);
;             PG8_WAIT_V(8); PG8_WAIT_L(0); PG8_BAR; PG8_MMA(1, 0, At, B0); PG8_MMA(1, 1, At, B1); PG8_BAR; PG8_SCHED;
	s_add_i32 s27, s27, s53
	v_lshl_add_u64 v[156:157], v[156:157], 0, s[86:87]
	s_mov_b32 m0, s27
	ds_read_b128 v[184:187], v147 offset:49152
	ds_read_b128 v[188:191], v147 offset:50176
	ds_read_b128 v[192:195], v147 offset:51200
	ds_read_b128 v[204:207], v147 offset:52224
	ds_read_b128 v[208:211], v147 offset:53248
	ds_read_b128 v[212:215], v147 offset:54272
	ds_read_b128 v[216:219], v147 offset:55296
	ds_read_b128 v[220:223], v147 offset:56320
	global_load_lds_dwordx4 v[156:157], off
	s_add_i32 m0, s27, 0x2000
	s_add_u32 s30, s40, 0x80080
	v_lshl_add_u64 v[156:157], v[196:197], 0, s[86:87]
	s_addc_u32 s31, s41, 0
	s_add_i32 s27, s65, s53
	global_load_lds_dwordx4 v[156:157], off
	v_lshl_add_u64 v[156:157], s[30:31], 0, v[2:3]
	s_mov_b32 m0, s27
	s_nop 0
	global_load_lds_dwordx4 v[156:157], off
	v_lshl_add_u64 v[156:157], s[30:31], 0, v[0:1]
	s_add_i32 m0, s27, 0x2000
	s_nop 0
	global_load_lds_dwordx4 v[156:157], off
	v_lshl_add_u64 v[156:157], v[224:225], 0, s[86:87]
	s_mov_b32 m0, s62
	s_nop 0
	global_load_lds_dwordx4 v[156:157], off
	v_lshl_add_u64 v[156:157], v[226:227], 0, s[86:87]
	s_mov_b32 m0, s63
	s_nop 0
	global_load_lds_dwordx4 v[156:157], off
	s_waitcnt vmcnt(8)
	s_waitcnt lgkmcnt(0)
	s_barrier
	s_setprio 1
	s_waitcnt lgkmcnt(0)
	v_mfma_f32_16x16x32_bf16 v[64:67], v[140:143], v[184:187], v[64:67]
	v_mfma_f32_16x16x32_bf16 v[64:67], v[148:151], v[188:191], v[64:67]
	v_mfma_f32_16x16x32_bf16 v[60:63], v[152:155], v[184:187], v[60:63]
	v_mfma_f32_16x16x32_bf16 v[60:63], v[164:167], v[188:191], v[60:63]
	v_mfma_f32_16x16x32_bf16 v[56:59], v[140:143], v[192:195], v[56:59]
	v_mfma_f32_16x16x32_bf16 v[56:59], v[148:151], v[204:207], v[56:59]
	v_mfma_f32_16x16x32_bf16 v[48:51], v[152:155], v[192:195], v[48:51]
	v_mfma_f32_16x16x32_bf16 v[48:51], v[164:167], v[204:207], v[48:51]
	v_mfma_f32_16x16x32_bf16 v[40:43], v[140:143], v[208:211], v[40:43]
	v_mfma_f32_16x16x32_bf16 v[40:43], v[148:151], v[212:215], v[40:43]
	v_mfma_f32_16x16x32_bf16 v[32:35], v[152:155], v[208:211], v[32:35]
	v_mfma_f32_16x16x32_bf16 v[32:35], v[164:167], v[212:215], v[32:35]
	v_mfma_f32_16x16x32_bf16 v[24:27], v[140:143], v[216:219], v[24:27]
	v_mfma_f32_16x16x32_bf16 v[24:27], v[148:151], v[220:223], v[24:27]
	v_mfma_f32_16x16x32_bf16 v[16:19], v[152:155], v[216:219], v[16:19]
	v_mfma_f32_16x16x32_bf16 v[16:19], v[164:167], v[220:223], v[16:19]
	s_setprio 0
	s_setprio 1
	v_mfma_f32_16x16x32_bf16 v[52:55], v[168:171], v[184:187], v[52:55]
	v_mfma_f32_16x16x32_bf16 v[52:55], v[172:175], v[188:191], v[52:55]
	v_mfma_f32_16x16x32_bf16 v[44:47], v[176:179], v[184:187], v[44:47]
	v_mfma_f32_16x16x32_bf16 v[44:47], v[180:183], v[188:191], v[44:47]
	v_mfma_f32_16x16x32_bf16 v[36:39], v[168:171], v[192:195], v[36:39]
	v_mfma_f32_16x16x32_bf16 v[36:39], v[172:175], v[204:207], v[36:39]
	v_mfma_f32_16x16x32_bf16 v[28:31], v[176:179], v[192:195], v[28:31]
	v_mfma_f32_16x16x32_bf16 v[28:31], v[180:183], v[204:207], v[28:31]
	v_mfma_f32_16x16x32_bf16 v[20:23], v[168:171], v[208:211], v[20:23]
	v_mfma_f32_16x16x32_bf16 v[20:23], v[172:175], v[212:215], v[20:23]
	v_mfma_f32_16x16x32_bf16 v[12:15], v[176:179], v[208:211], v[12:15]
	v_mfma_f32_16x16x32_bf16 v[12:15], v[180:183], v[212:215], v[12:15]
	v_mfma_f32_16x16x32_bf16 v[8:11], v[168:171], v[216:219], v[8:11]
	v_mfma_f32_16x16x32_bf16 v[8:11], v[172:175], v[220:223], v[8:11]
	v_mfma_f32_16x16x32_bf16 v[4:7], v[176:179], v[216:219], v[4:7]
	v_mfma_f32_16x16x32_bf16 v[4:7], v[180:183], v[220:223], v[4:7]
	s_setprio 0
	s_barrier
	s_add_i32 s26, s26, 2
	s_add_u32 s38, s38, 0x100
	s_addc_u32 s39, s39, 0
	s_add_u32 s24, s24, 0x100
	s_addc_u32 s25, s25, 0
	s_cmp_gt_u32 s26, 29
	s_cbranch_scc0 .LBB0_218

;     __device__ bool next(int i, Unit& u) const { if (i >= 2) return false; const int x = c & 7, j = c >> 3; u.pm = 32 * i + 4 * x + (j & 3); u.pn = j >> 2; return true; }
; #define PG8_STAGE(bufoff, gbase, voff) do { _Pragma("unroll") for (int _i = 0; _i < 2; ++_i) \
;         __builtin_amdgcn_global_load_lds((const unsigned*)((const char*)(gbase) + (voff)[_i]), (LAS unsigned*)(lds + (bufoff) + ldsw + _i * 8192), 16, 0, 0); } while (0)
; #define PG8_LDA(dst, b, h) do { _Pragma("unroll") for (int m = 0; m < 4; ++m) _Pragma("unroll") for (int k = 0; k < 2; ++k) dst[m][k] = *(const LAS bf16x8*)(lds + PG8_SA(b, h) + aoff + m * 2048 + k * 1024); } while (0)
; #define PG8_LDB(dst, b, h) do { _Pragma("unroll") for (int n = 0; n < 2; ++n) _Pragma("unroll") for (int k = 0; k < 2; ++k) dst[n][k] = *(const LAS bf16x8*)(lds + PG8_SB(b, h) + boff + n * 2048 + k * 1024); } while (0)
; #define PG8_WAIT_V(n) asm volatile("s_waitcnt vmcnt(" #n ")" ::: "memory")
; #define PG8_WAIT_L(n) asm volatile("s_waitcnt lgkmcnt(" #n ")" ::: "memory")
; #define PG8_BAR __builtin_amdgcn_s_barrier()
; #define PG8_SCHED __builtin_amdgcn_sched_barrier(0)
; template <class Epi, class Sched, bool ALIGN_EPI = true>
; __device__ __forceinline__ void gemm_phase(LAS unsigned char* lds, const Gemm g, const Sched& S, const Epi& E) {
;     ...
;         const bool has_next = S.next(ui + 1, nxt);
;         const char* nA = has_next ? (const char*)g.A + ((size_t)nxt.pm * BM * g.lda + (size_t)nxt.pn * g.a_pn_off) * 2 : cA; const char* nB = has_next ? (const char*)g.Bt + (size_t)nxt.pn * BM * g.ldb * 2 : cB;
;         for (int t = 0; t < nt; t += 2) {
;             const bool last = (t == nt - 2);
;             const char* a1 = cA + (size_t)(t + 1) * kstep;
;             const char* a2 = last ? nA : cA + (size_t)(t + 2) * kstep; const char* b2 = last ? nB : cB + (size_t)(t + 2) * kstep;
;             const char* a3 = a2 + kstep; const char* b3 = b2 + kstep;
;             PG8_LDB(B0, 0, 0); PG8_LDB(B1, 0, 1); PG8_SCHED; PG8_LDA(At, 0, 0); PG8_STAGE(PG8_SA(1, 1), a1 + hA, voffA);
;             PG8_WAIT_V(8); PG8_WAIT_L(0); PG8_BAR; PG8_MMA(0, 0, At, B0); PG8_MMA(0, 1, At, B1); PG8_BAR; PG8_SCHED;
;             PG8_LDA(At, 0, 1); PG8_STAGE(PG8_SB(0, 0), b2, voffB); PG8_STAGE(PG8_SB(0, 1), b2 + hB, voffB); PG8_STAGE(PG8_SA(0, 0), a2, voffA);
.LBB0_666:
	s_mov_b32 s82, s81
	s_or_b32 s81, s17, s68
	s_mov_b64 s[10:11], s[12:13]
	s_lshl_b32 s12, s81, 20
	s_add_u32 s12, s28, s12
	s_addc_u32 s13, s29, 0
	s_and_b64 s[16:17], s[38:39], exec
	s_cselect_b32 s16, s13, s11
	s_cselect_b32 s17, s12, s10
	s_add_u32 s18, s10, 0x100
	s_addc_u32 s19, s11, 0
	s_add_u32 s10, s10, 0x80080
	s_addc_u32 s11, s11, 0
	v_lshl_add_u64 v[132:133], s[10:11], 0, v[166:167]
	v_lshl_add_u64 v[134:135], s[10:11], 0, v[168:169]
	s_mov_b32 s24, -2
	s_mov_b64 s[10:11], 0
	s_add_u32 vcc_lo, s10, 0x100
	s_addc_u32 vcc_hi, s11, 0
	s_add_u32 s25, s18, s10
	s_addc_u32 s26, s19, s11
	s_add_i32 s27, 0, 0x10000
	s_cmp_eq_u32 s24, 28
	s_cselect_b32 s65, s16, s26
	s_cselect_b32 s26, 0, vcc_lo
	s_cselect_b32 s64, s17, s25
	s_cselect_b32 s25, 0, vcc_hi
	s_add_u32 s62, s14, s26
	v_add_u32_e32 v160, s27, v186
	s_addc_u32 s63, s15, s25
	s_add_i32 s25, 0, 0x14000
	ds_read_b128 v[136:139], v160
	ds_read_b128 v[140:143], v160 offset:1024
	ds_read_b128 v[144:147], v160 offset:2048
	ds_read_b128 v[170:173], v160 offset:3072
	v_add_u32_e32 v160, s25, v186
	ds_read_b128 v[174:177], v160
	ds_read_b128 v[178:181], v160 offset:1024
	ds_read_b128 v[182:185], v160 offset:2048
	ds_read_b128 v[208:211], v160 offset:3072
	v_lshl_add_u64 v[244:245], v[132:133], 0, s[10:11]
	s_add_i32 m0, s53, 0xc000
	ds_read_b128 v[212:215], v197
	ds_read_b128 v[216:219], v197 offset:1024
	ds_read_b128 v[220:223], v197 offset:2048
	ds_read_b128 v[224:227], v197 offset:3072
	ds_read_b128 v[228:231], v197 offset:4096
	ds_read_b128 v[232:235], v197 offset:5120
	ds_read_b128 v[236:239], v197 offset:6144
	ds_read_b128 v[240:243], v197 offset:7168
	global_load_lds_dwordx4 v[244:245], off
	v_lshl_add_u64 v[244:245], v[134:135], 0, s[10:11]
	s_add_i32 m0, s53, 0xe000
	s_nop 0
	global_load_lds_dwordx4 v[244:245], off
	s_waitcnt vmcnt(8)
	s_waitcnt lgkmcnt(0)
	s_barrier
	s_setprio 1
	s_waitcnt lgkmcnt(0)
	v_mfma_f32_16x16x32_bf16 v[36:39], v[136:139], v[212:215], 0
	v_mfma_f32_16x16x32_bf16 v[36:39], v[140:143], v[216:219], v[36:39]
	v_mfma_f32_16x16x32_bf16 v[40:43], v[144:147], v[212:215], 0
	v_mfma_f32_16x16x32_bf16 v[40:43], v[170:173], v[216:219], v[40:43]
	v_mfma_f32_16x16x32_bf16 v[68:71], v[136:139], v[220:223], 0
	v_mfma_f32_16x16x32_bf16 v[68:71], v[140:143], v[224:227], v[68:71]
	v_mfma_f32_16x16x32_bf16 v[72:75], v[144:147], v[220:223], 0
	v_mfma_f32_16x16x32_bf16 v[72:75], v[170:173], v[224:227], v[72:75]
	v_mfma_f32_16x16x32_bf16 v[100:103], v[136:139], v[228:231], 0
	v_mfma_f32_16x16x32_bf16 v[100:103], v[140:143], v[232:235], v[100:103]
	v_mfma_f32_16x16x32_bf16 v[104:107], v[144:147], v[228:231], 0
	v_mfma_f32_16x16x32_bf16 v[104:107], v[170:173], v[232:235], v[104:107]
	v_mfma_f32_16x16x32_bf16 v[128:131], v[136:139], v[236:239], 0
	v_mfma_f32_16x16x32_bf16 v[128:131], v[140:143], v[240:243], v[128:131]
	v_mfma_f32_16x16x32_bf16 v[124:127], v[144:147], v[236:239], 0
	v_mfma_f32_16x16x32_bf16 v[124:127], v[170:173], v[240:243], v[124:127]
	s_setprio 0
	s_setprio 1
	v_mfma_f32_16x16x32_bf16 v[8:11], v[174:177], v[212:215], 0
	v_mfma_f32_16x16x32_bf16 v[8:11], v[178:181], v[216:219], v[8:11]
	v_mfma_f32_16x16x32_bf16 v[4:7], v[182:185], v[212:215], 0
	v_mfma_f32_16x16x32_bf16 v[4:7], v[208:211], v[216:219], v[4:7]
	v_mfma_f32_16x16x32_bf16 v[32:35], v[174:177], v[220:223], 0
	v_mfma_f32_16x16x32_bf16 v[32:35], v[178:181], v[224:227], v[32:35]
	v_mfma_f32_16x16x32_bf16 v[28:31], v[182:185], v[220:223], 0
	v_mfma_f32_16x16x32_bf16 v[28:31], v[208:211], v[224:227], v[28:31]
	v_mfma_f32_16x16x32_bf16 v[56:59], v[174:177], v[228:231], 0
	v_mfma_f32_16x16x32_bf16 v[56:59], v[178:181], v[232:235], v[56:59]
	v_mfma_f32_16x16x32_bf16 v[52:55], v[182:185], v[228:231], 0
	v_mfma_f32_16x16x32_bf16 v[52:55], v[208:211], v[232:235], v[52:55]
	v_mfma_f32_16x16x32_bf16 v[80:83], v[174:177], v[236:239], 0
	v_mfma_f32_16x16x32_bf16 v[80:83], v[178:181], v[240:243], v[80:83]
	v_mfma_f32_16x16x32_bf16 v[76:79], v[182:185], v[236:239], 0
	v_mfma_f32_16x16x32_bf16 v[76:79], v[208:211], v[240:243], v[76:79]
	s_setprio 0
	s_barrier
	s_add_i32 s10, s27, s67
	v_lshl_add_u64 v[244:245], s[62:63], 0, v[2:3]
	s_mov_b32 m0, s10
	ds_read_b128 v[212:215], v197 offset:16384
	ds_read_b128 v[216:219], v197 offset:17408
	ds_read_b128 v[220:223], v197 offset:18432
	ds_read_b128 v[224:227], v197 offset:19456
	ds_read_b128 v[228:231], v197 offset:20480
	ds_read_b128 v[232:235], v197 offset:21504
	ds_read_b128 v[236:239], v197 offset:22528
	ds_read_b128 v[240:243], v197 offset:23552
	global_load_lds_dwordx4 v[244:245], off
	s_add_i32 m0, s10, 0x2000
	s_add_u32 s10, s62, 0x80000
	v_lshl_add_u64 v[246:247], s[62:63], 0, v[150:151]
	s_addc_u32 s11, s63, 0
	s_add_i32 s25, s25, s67
	global_load_lds_dwordx4 v[246:247], off
	v_lshl_add_u64 v[248:249], s[10:11], 0, v[2:3]
	s_mov_b32 m0, s25
	v_lshl_add_u64 v[160:161], s[64:65], 0, v[148:149]
	global_load_lds_dwordx4 v[248:249], off
	v_lshl_add_u64 v[248:249], s[10:11], 0, v[150:151]
	s_add_i32 m0, s25, 0x2000
	s_nop 0
	global_load_lds_dwordx4 v[248:249], off
	v_lshl_add_u64 v[248:249], s[64:65], 0, v[0:1]
	s_mov_b32 m0, s53
	s_nop 0
	global_load_lds_dwordx4 v[248:249], off
	s_mov_b32 m0, s66
	s_nop 0
	global_load_lds_dwordx4 v[160:161], off
	s_waitcnt vmcnt(8)
	s_waitcnt lgkmcnt(0)
	s_barrier
; #define PG8_STAGE(bufoff, gbase, voff) do { _Pragma("unroll") for (int _i = 0; _i < 2; ++_i) \
;         __builtin_amdgcn_global_load_lds((const unsigned*)((const char*)(gbase) + (voff)[_i]), (LAS unsigned*)(lds + (bufoff) + ldsw + _i * 8192), 16, 0, 0); } while (0)
; #define PG8_LDA(dst, b, h) do { _Pragma("unroll") for (int m = 0; m < 4; ++m) _Pragma("unroll") for (int k = 0; k < 2; ++k) dst[m][k] = *(const LAS bf16x8*)(lds + PG8_SA(b, h) + aoff + m * 2048 + k * 1024); } while (0)
; #define PG8_LDB(dst, b, h) do { _Pragma("unroll") for (int n = 0; n < 2; ++n) _Pragma("unroll") for (int k = 0; k < 2; ++k) dst[n][k] = *(const LAS bf16x8*)(lds + PG8_SB(b, h) + boff + n * 2048 + k * 1024); } while (0)
; #define PG8_MMA(ai, bj, At, Bt) do { __builtin_amdgcn_s_setprio(1); _Pragma("unroll") for (int m = 0; m < 4; ++m) _Pragma("unroll") for (int n = 0; n < 2; ++n) _Pragma("unroll") for (int k = 0; k < 2; ++k) \
;         acc[ai][bj][m][n] = __builtin_amdgcn_mfma_f32_16x16x32_bf16(Bt[n][k], At[m][k], acc[ai][bj][m][n], 0, 0, 0); __builtin_amdgcn_s_setprio(0); } while (0)
; #define PG8_WAIT_V(n) asm volatile("s_waitcnt vmcnt(" #n ")" ::: "memory")
; #define PG8_WAIT_L(n) asm volatile("s_waitcnt lgkmcnt(" #n ")" ::: "memory")
; #define PG8_BAR __builtin_amdgcn_s_barrier()
; #define PG8_SCHED __builtin_amdgcn_sched_barrier(0)
; template <class Epi, class Sched, bool ALIGN_EPI = true>
; __device__ __forceinline__ void gemm_phase(LAS unsigned char* lds, const Gemm g, const Sched& S, const Epi& E) {
;     ...
;             PG8_WAIT_V(8); PG8_WAIT_L(0); PG8_BAR; PG8_MMA(1, 0, At, B0); PG8_MMA(1, 1, At, B1); PG8_BAR; PG8_SCHED;
;             PG8_LDB(B0, 1, 0); PG8_LDB(B1, 1, 1); PG8_SCHED; PG8_LDA(At, 1, 0); PG8_STAGE(PG8_SA(0, 1), a2 + hA, voffA);
;             PG8_WAIT_V(8); PG8_WAIT_L(0); PG8_BAR; PG8_MMA(0, 0, At, B0); PG8_MMA(0, 1, At, B1); PG8_BAR; PG8_SCHED;
	s_setprio 1
	s_waitcnt lgkmcnt(0)
	v_mfma_f32_16x16x32_bf16 v[120:123], v[136:139], v[212:215], 0
	v_mfma_f32_16x16x32_bf16 v[120:123], v[140:143], v[216:219], v[120:123]
	v_mfma_f32_16x16x32_bf16 v[116:119], v[144:147], v[212:215], 0
	v_mfma_f32_16x16x32_bf16 v[116:119], v[170:173], v[216:219], v[116:119]
	v_mfma_f32_16x16x32_bf16 v[96:99], v[136:139], v[220:223], 0
	v_mfma_f32_16x16x32_bf16 v[96:99], v[140:143], v[224:227], v[96:99]
	v_mfma_f32_16x16x32_bf16 v[92:95], v[144:147], v[220:223], 0
	v_mfma_f32_16x16x32_bf16 v[92:95], v[170:173], v[224:227], v[92:95]
	v_mfma_f32_16x16x32_bf16 v[64:67], v[136:139], v[228:231], 0
	v_mfma_f32_16x16x32_bf16 v[64:67], v[140:143], v[232:235], v[64:67]
	v_mfma_f32_16x16x32_bf16 v[60:63], v[144:147], v[228:231], 0
	v_mfma_f32_16x16x32_bf16 v[60:63], v[170:173], v[232:235], v[60:63]
	v_mfma_f32_16x16x32_bf16 v[24:27], v[136:139], v[236:239], 0
	v_mfma_f32_16x16x32_bf16 v[24:27], v[140:143], v[240:243], v[24:27]
	v_mfma_f32_16x16x32_bf16 v[20:23], v[144:147], v[236:239], 0
	v_mfma_f32_16x16x32_bf16 v[20:23], v[170:173], v[240:243], v[20:23]
	s_setprio 0
	s_setprio 1
	v_mfma_f32_16x16x32_bf16 v[112:115], v[174:177], v[212:215], 0
	v_mfma_f32_16x16x32_bf16 v[112:115], v[178:181], v[216:219], v[112:115]
	v_mfma_f32_16x16x32_bf16 v[108:111], v[182:185], v[212:215], 0
	v_mfma_f32_16x16x32_bf16 v[108:111], v[208:211], v[216:219], v[108:111]
	v_mfma_f32_16x16x32_bf16 v[88:91], v[174:177], v[220:223], 0
	v_mfma_f32_16x16x32_bf16 v[88:91], v[178:181], v[224:227], v[88:91]
	v_mfma_f32_16x16x32_bf16 v[84:87], v[182:185], v[220:223], 0
	v_mfma_f32_16x16x32_bf16 v[84:87], v[208:211], v[224:227], v[84:87]
	v_mfma_f32_16x16x32_bf16 v[48:51], v[174:177], v[228:231], 0
	v_mfma_f32_16x16x32_bf16 v[48:51], v[178:181], v[232:235], v[48:51]
	v_mfma_f32_16x16x32_bf16 v[44:47], v[182:185], v[228:231], 0
	v_mfma_f32_16x16x32_bf16 v[44:47], v[208:211], v[232:235], v[44:47]
	v_mfma_f32_16x16x32_bf16 v[16:19], v[174:177], v[236:239], 0
	v_mfma_f32_16x16x32_bf16 v[16:19], v[178:181], v[240:243], v[16:19]
	v_mfma_f32_16x16x32_bf16 v[12:15], v[182:185], v[236:239], 0
	v_mfma_f32_16x16x32_bf16 v[12:15], v[208:211], v[240:243], v[12:15]
	s_setprio 0
	s_barrier
	s_add_i32 s25, 0, 0x18000
	v_add_u32_e32 v162, s25, v186
	s_add_i32 s26, 0, 0x1c000
	ds_read_b128 v[136:139], v162
	ds_read_b128 v[140:143], v162 offset:1024
	ds_read_b128 v[144:147], v162 offset:2048
	ds_read_b128 v[170:173], v162 offset:3072
	v_add_u32_e32 v162, s26, v186
	ds_read_b128 v[174:177], v162
	ds_read_b128 v[178:181], v162 offset:1024
	ds_read_b128 v[182:185], v162 offset:2048
	ds_read_b128 v[208:211], v162 offset:3072
	s_add_u32 s10, s64, 0x80000
	s_addc_u32 s11, s65, 0
	s_mov_b32 m0, s75
	v_lshl_add_u64 v[162:163], s[10:11], 0, v[0:1]
	ds_read_b128 v[212:215], v197 offset:32768
	ds_read_b128 v[216:219], v197 offset:33792
	ds_read_b128 v[220:223], v197 offset:34816
	ds_read_b128 v[224:227], v197 offset:35840
	ds_read_b128 v[228:231], v197 offset:36864
	ds_read_b128 v[232:235], v197 offset:37888
	ds_read_b128 v[236:239], v197 offset:38912
	ds_read_b128 v[240:243], v197 offset:39936
	global_load_lds_dwordx4 v[162:163], off
	v_lshl_add_u64 v[162:163], s[10:11], 0, v[148:149]
	s_mov_b32 m0, s76
	s_nop 0
	global_load_lds_dwordx4 v[162:163], off
	s_waitcnt vmcnt(8)
	s_waitcnt lgkmcnt(0)
	s_barrier
	s_setprio 1
	s_waitcnt lgkmcnt(0)
	v_mfma_f32_16x16x32_bf16 v[36:39], v[136:139], v[212:215], v[36:39]
	v_mfma_f32_16x16x32_bf16 v[36:39], v[140:143], v[216:219], v[36:39]
	v_mfma_f32_16x16x32_bf16 v[40:43], v[144:147], v[212:215], v[40:43]
	v_mfma_f32_16x16x32_bf16 v[40:43], v[170:173], v[216:219], v[40:43]
	v_mfma_f32_16x16x32_bf16 v[68:71], v[136:139], v[220:223], v[68:71]
	v_mfma_f32_16x16x32_bf16 v[68:71], v[140:143], v[224:227], v[68:71]
	v_mfma_f32_16x16x32_bf16 v[72:75], v[144:147], v[220:223], v[72:75]
	v_mfma_f32_16x16x32_bf16 v[72:75], v[170:173], v[224:227], v[72:75]
	v_mfma_f32_16x16x32_bf16 v[100:103], v[136:139], v[228:231], v[100:103]
	v_mfma_f32_16x16x32_bf16 v[100:103], v[140:143], v[232:235], v[100:103]
	v_mfma_f32_16x16x32_bf16 v[104:107], v[144:147], v[228:231], v[104:107]
	v_mfma_f32_16x16x32_bf16 v[104:107], v[170:173], v[232:235], v[104:107]
	v_mfma_f32_16x16x32_bf16 v[128:131], v[136:139], v[236:239], v[128:131]
	v_mfma_f32_16x16x32_bf16 v[128:131], v[140:143], v[240:243], v[128:131]
	v_mfma_f32_16x16x32_bf16 v[124:127], v[144:147], v[236:239], v[124:127]
	v_mfma_f32_16x16x32_bf16 v[124:127], v[170:173], v[240:243], v[124:127]
	s_setprio 0
	s_setprio 1
	v_mfma_f32_16x16x32_bf16 v[8:11], v[174:177], v[212:215], v[8:11]
	v_mfma_f32_16x16x32_bf16 v[8:11], v[178:181], v[216:219], v[8:11]
	v_mfma_f32_16x16x32_bf16 v[4:7], v[182:185], v[212:215], v[4:7]
	v_mfma_f32_16x16x32_bf16 v[4:7], v[208:211], v[216:219], v[4:7]
	v_mfma_f32_16x16x32_bf16 v[32:35], v[174:177], v[220:223], v[32:35]
	v_mfma_f32_16x16x32_bf16 v[32:35], v[178:181], v[224:227], v[32:35]
	v_mfma_f32_16x16x32_bf16 v[28:31], v[182:185], v[220:223], v[28:31]
	v_mfma_f32_16x16x32_bf16 v[28:31], v[208:211], v[224:227], v[28:31]
	v_mfma_f32_16x16x32_bf16 v[56:59], v[174:177], v[228:231], v[56:59]
	v_mfma_f32_16x16x32_bf16 v[56:59], v[178:181], v[232:235], v[56:59]
	v_mfma_f32_16x16x32_bf16 v[52:55], v[182:185], v[228:231], v[52:55]
	v_mfma_f32_16x16x32_bf16 v[52:55], v[208:211], v[232:235], v[52:55]
	v_mfma_f32_16x16x32_bf16 v[80:83], v[174:177], v[236:239], v[80:83]
	v_mfma_f32_16x16x32_bf16 v[80:83], v[178:181], v[240:243], v[80:83]
	v_mfma_f32_16x16x32_bf16 v[76:79], v[182:185], v[236:239], v[76:79]
	v_mfma_f32_16x16x32_bf16 v[76:79], v[208:211], v[240:243], v[76:79]
	s_setprio 0
	s_barrier
; #define PG8_STAGE(bufoff, gbase, voff) do { _Pragma("unroll") for (int _i = 0; _i < 2; ++_i) \
;         __builtin_amdgcn_global_load_lds((const unsigned*)((const char*)(gbase) + (voff)[_i]), (LAS unsigned*)(lds + (bufoff) + ldsw + _i * 8192), 16, 0, 0); } while (0)
; #define PG8_LDA(dst, b, h) do { _Pragma("unroll") for (int m = 0; m < 4; ++m) _Pragma("unroll") for (int k = 0; k < 2; ++k) dst[m][k] = *(const LAS bf16x8*)(lds + PG8_SA(b, h) + aoff + m * 2048 + k * 1024); } while (0)
; #define PG8_LDB(dst, b, h) do { _Pragma("unroll") for (int n = 0; n < 2; ++n) _Pragma("unroll") for (int k = 0; k < 2; ++k) dst[n][k] = *(const LAS bf16x8*)(lds + PG8_SB(b, h) + boff + n * 2048 + k * 1024); } while (0)
; #define PG8_MMA(ai, bj, At, Bt) do { __builtin_amdgcn_s_setprio(1); _Pragma("unroll") for (int m = 0; m < 4; ++m) _Pragma("unroll") for (int n = 0; n < 2; ++n) _Pragma("unroll") for (int k = 0; k < 2; ++k) \
;         acc[ai][bj][m][n] = __builtin_amdgcn_mfma_f32_16x16x32_bf16(Bt[n][k], At[m][k], acc[ai][bj][m][n], 0, 0, 0); __builtin_amdgcn_s_setprio(0); } while (0)
; #define PG8_WAIT_V(n) asm volatile("s_waitcnt vmcnt(" #n ")" ::: "memory")
; #define PG8_BAR __builtin_amdgcn_s_barrier()
; template <class Epi, class Sched, bool ALIGN_EPI = true>
; __device__ __forceinline__ void gemm_phase(LAS unsigned char* lds, const Gemm g, const Sched& S, const Epi& E) {
;     ...
;             PG8_LDB(B0, 0, 0); PG8_LDB(B1, 0, 1); PG8_SCHED; PG8_LDA(At, 0, 0); PG8_STAGE(PG8_SA(1, 1), a1 + hA, voffA);
;             PG8_WAIT_V(8); PG8_WAIT_L(0); PG8_BAR; PG8_MMA(0, 0, At, B0); PG8_MMA(0, 1, At, B1); PG8_BAR; PG8_SCHED;
;             PG8_LDA(At, 0, 1); PG8_STAGE(PG8_SB(0, 0), b2, voffB); PG8_STAGE(PG8_SB(0, 1), b2 + hB, voffB); PG8_STAGE(PG8_SA(0, 0), a2, voffA);
;             PG8_WAIT_V(8); PG8_WAIT_L(0); PG8_BAR; PG8_MMA(1, 0, At, B0); PG8_MMA(1, 1, At, B1); PG8_BAR; PG8_SCHED;
;             PG8_LDB(B0, 1, 0); PG8_LDB(B1, 1, 1); PG8_SCHED; PG8_LDA(At, 1, 0); PG8_STAGE(PG8_SA(0, 1), a2 + hA, voffA);
;             PG8_WAIT_V(8); PG8_WAIT_L(0); PG8_BAR; PG8_MMA(0, 0, At, B0); PG8_MMA(0, 1, At, B1); PG8_BAR; PG8_SCHED;
;             PG8_LDA(At, 1, 1); PG8_STAGE(PG8_SB(1, 0), b3, voffB); PG8_STAGE(PG8_SB(1, 1), b3 + hB, voffB); PG8_STAGE(PG8_SA(1, 0), a3, voffA);
;             PG8_WAIT_V(8); PG8_WAIT_L(0); PG8_BAR; PG8_MMA(1, 0, At, B0); PG8_MMA(1, 1, At, B1); PG8_BAR; PG8_SCHED;
	s_add_i32 s10, s25, s67
	v_lshl_add_u64 v[162:163], v[244:245], 0, s[86:87]
	s_mov_b32 m0, s10
	ds_read_b128 v[212:215], v197 offset:49152
	ds_read_b128 v[216:219], v197 offset:50176
	ds_read_b128 v[220:223], v197 offset:51200
	ds_read_b128 v[224:227], v197 offset:52224
	ds_read_b128 v[228:231], v197 offset:53248
	ds_read_b128 v[232:235], v197 offset:54272
	ds_read_b128 v[236:239], v197 offset:55296
	ds_read_b128 v[240:243], v197 offset:56320
	global_load_lds_dwordx4 v[162:163], off
	s_add_i32 m0, s10, 0x2000
	s_add_u32 s10, s62, 0x80080
	v_lshl_add_u64 v[162:163], v[246:247], 0, s[86:87]
	s_addc_u32 s11, s63, 0
	s_add_i32 s25, s26, s67
	global_load_lds_dwordx4 v[162:163], off
	v_lshl_add_u64 v[162:163], s[10:11], 0, v[2:3]
	s_mov_b32 m0, s25
	v_lshl_add_u64 v[160:161], v[160:161], 0, s[86:87]
	global_load_lds_dwordx4 v[162:163], off
	v_lshl_add_u64 v[162:163], s[10:11], 0, v[150:151]
	s_add_i32 m0, s25, 0x2000
	s_nop 0
	global_load_lds_dwordx4 v[162:163], off
	v_lshl_add_u64 v[162:163], v[248:249], 0, s[86:87]
	s_mov_b32 m0, s79
	s_nop 0
	global_load_lds_dwordx4 v[162:163], off
	s_mov_b32 m0, s80
	s_nop 0
	global_load_lds_dwordx4 v[160:161], off
	s_waitcnt vmcnt(8)
	s_waitcnt lgkmcnt(0)
	s_barrier
	s_setprio 1
	s_waitcnt lgkmcnt(0)
	v_mfma_f32_16x16x32_bf16 v[120:123], v[136:139], v[212:215], v[120:123]
	v_mfma_f32_16x16x32_bf16 v[120:123], v[140:143], v[216:219], v[120:123]
	v_mfma_f32_16x16x32_bf16 v[116:119], v[144:147], v[212:215], v[116:119]
	v_mfma_f32_16x16x32_bf16 v[116:119], v[170:173], v[216:219], v[116:119]
	v_mfma_f32_16x16x32_bf16 v[96:99], v[136:139], v[220:223], v[96:99]
	v_mfma_f32_16x16x32_bf16 v[96:99], v[140:143], v[224:227], v[96:99]
	v_mfma_f32_16x16x32_bf16 v[92:95], v[144:147], v[220:223], v[92:95]
	v_mfma_f32_16x16x32_bf16 v[92:95], v[170:173], v[224:227], v[92:95]
	v_mfma_f32_16x16x32_bf16 v[64:67], v[136:139], v[228:231], v[64:67]
	v_mfma_f32_16x16x32_bf16 v[64:67], v[140:143], v[232:235], v[64:67]
	v_mfma_f32_16x16x32_bf16 v[60:63], v[144:147], v[228:231], v[60:63]
	v_mfma_f32_16x16x32_bf16 v[60:63], v[170:173], v[232:235], v[60:63]
	v_mfma_f32_16x16x32_bf16 v[24:27], v[136:139], v[236:239], v[24:27]
	v_mfma_f32_16x16x32_bf16 v[24:27], v[140:143], v[240:243], v[24:27]
	v_mfma_f32_16x16x32_bf16 v[20:23], v[144:147], v[236:239], v[20:23]
	v_mfma_f32_16x16x32_bf16 v[20:23], v[170:173], v[240:243], v[20:23]
	s_setprio 0
	s_setprio 1
	v_mfma_f32_16x16x32_bf16 v[112:115], v[174:177], v[212:215], v[112:115]
	v_mfma_f32_16x16x32_bf16 v[112:115], v[178:181], v[216:219], v[112:115]
	v_mfma_f32_16x16x32_bf16 v[108:111], v[182:185], v[212:215], v[108:111]
	v_mfma_f32_16x16x32_bf16 v[108:111], v[208:211], v[216:219], v[108:111]
	v_mfma_f32_16x16x32_bf16 v[88:91], v[174:177], v[220:223], v[88:91]
	v_mfma_f32_16x16x32_bf16 v[88:91], v[178:181], v[224:227], v[88:91]
	v_mfma_f32_16x16x32_bf16 v[84:87], v[182:185], v[220:223], v[84:87]
	v_mfma_f32_16x16x32_bf16 v[84:87], v[208:211], v[224:227], v[84:87]
	v_mfma_f32_16x16x32_bf16 v[48:51], v[174:177], v[228:231], v[48:51]
	v_mfma_f32_16x16x32_bf16 v[48:51], v[178:181], v[232:235], v[48:51]
	v_mfma_f32_16x16x32_bf16 v[44:47], v[182:185], v[228:231], v[44:47]
	v_mfma_f32_16x16x32_bf16 v[44:47], v[208:211], v[232:235], v[44:47]
	v_mfma_f32_16x16x32_bf16 v[16:19], v[174:177], v[236:239], v[16:19]
	v_mfma_f32_16x16x32_bf16 v[16:19], v[178:181], v[240:243], v[16:19]
	v_mfma_f32_16x16x32_bf16 v[12:15], v[182:185], v[236:239], v[12:15]
	v_mfma_f32_16x16x32_bf16 v[12:15], v[208:211], v[240:243], v[12:15]
	s_setprio 0
	s_barrier
	s_add_i32 s24, s24, 2
	s_cmp_gt_u32 s24, 29
	s_mov_b64 s[10:11], vcc
	s_cbranch_scc1 .Lpeel_exit_667
.LBB0_667:
	s_add_u32 vcc_lo, s10, 0x100
	s_addc_u32 vcc_hi, s11, 0
	s_add_u32 s25, s18, s10
	s_addc_u32 s26, s19, s11
	s_add_i32 s27, 0, 0x10000
	s_cmp_eq_u32 s24, 28
	s_cselect_b32 s65, s16, s26
	s_cselect_b32 s26, 0, vcc_lo
	s_cselect_b32 s64, s17, s25
	s_cselect_b32 s25, 0, vcc_hi
	s_add_u32 s62, s14, s26
	v_add_u32_e32 v160, s27, v186
	s_addc_u32 s63, s15, s25
	s_add_i32 s25, 0, 0x14000
	ds_read_b128 v[136:139], v160
	ds_read_b128 v[140:143], v160 offset:1024
	ds_read_b128 v[144:147], v160 offset:2048
	ds_read_b128 v[170:173], v160 offset:3072
	v_add_u32_e32 v160, s25, v186
	ds_read_b128 v[174:177], v160
	ds_read_b128 v[178:181], v160 offset:1024
	ds_read_b128 v[182:185], v160 offset:2048
	ds_read_b128 v[208:211], v160 offset:3072
	v_lshl_add_u64 v[244:245], v[132:133], 0, s[10:11]
	s_add_i32 m0, s53, 0xc000
	ds_read_b128 v[212:215], v197
	ds_read_b128 v[216:219], v197 offset:1024
	ds_read_b128 v[220:223], v197 offset:2048
	ds_read_b128 v[224:227], v197 offset:3072
	ds_read_b128 v[228:231], v197 offset:4096
	ds_read_b128 v[232:235], v197 offset:5120
	ds_read_b128 v[236:239], v197 offset:6144
	ds_read_b128 v[240:243], v197 offset:7168
	global_load_lds_dwordx4 v[244:245], off
	v_lshl_add_u64 v[244:245], v[134:135], 0, s[10:11]
	s_add_i32 m0, s53, 0xe000
	s_nop 0
	global_load_lds_dwordx4 v[244:245], off
	s_waitcnt vmcnt(8)
	s_waitcnt lgkmcnt(0)
	s_barrier
; #define PG8_STAGE(bufoff, gbase, voff) do { _Pragma("unroll") for (int _i = 0; _i < 2; ++_i) \
;         __builtin_amdgcn_global_load_lds((const unsigned*)((const char*)(gbase) + (voff)[_i]), (LAS unsigned*)(lds + (bufoff) + ldsw + _i * 8192), 16, 0, 0); } while (0)
; #define PG8_LDA(dst, b, h) do { _Pragma("unroll") for (int m = 0; m < 4; ++m) _Pragma("unroll") for (int k = 0; k < 2; ++k) dst[m][k] = *(const LAS bf16x8*)(lds + PG8_SA(b, h) + aoff + m * 2048 + k * 1024); } while (0)
; #define PG8_MMA(ai, bj, At, Bt) do { __builtin_amdgcn_s_setprio(1); _Pragma("unroll") for (int m = 0; m < 4; ++m) _Pragma("unroll") for (int n = 0; n < 2; ++n) _Pragma("unroll") for (int k = 0; k < 2; ++k) \
;         acc[ai][bj][m][n] = __builtin_amdgcn_mfma_f32_16x16x32_bf16(Bt[n][k], At[m][k], acc[ai][bj][m][n], 0, 0, 0); __builtin_amdgcn_s_setprio(0); } while (0)
; #define PG8_WAIT_V(n) asm volatile("s_waitcnt vmcnt(" #n ")" ::: "memory")
; #define PG8_WAIT_L(n) asm volatile("s_waitcnt lgkmcnt(" #n ")" ::: "memory")
; #define PG8_BAR __builtin_amdgcn_s_barrier()
; #define PG8_SCHED __builtin_amdgcn_sched_barrier(0)
; template <class Epi, class Sched, bool ALIGN_EPI = true>
; __device__ __forceinline__ void gemm_phase(LAS unsigned char* lds, const Gemm g, const Sched& S, const Epi& E) {
;     ...
;             PG8_WAIT_V(8); PG8_WAIT_L(0); PG8_BAR; PG8_MMA(0, 0, At, B0); PG8_MMA(0, 1, At, B1); PG8_BAR; PG8_SCHED;
;             PG8_LDA(At, 0, 1); PG8_STAGE(PG8_SB(0, 0), b2, voffB); PG8_STAGE(PG8_SB(0, 1), b2 + hB, voffB); PG8_STAGE(PG8_SA(0, 0), a2, voffA);
;             PG8_WAIT_V(8); PG8_WAIT_L(0); PG8_BAR; PG8_MMA(1, 0, At, B0); PG8_MMA(1, 1, At, B1); PG8_BAR; PG8_SCHED;
	s_setprio 1
	s_waitcnt lgkmcnt(0)
	v_mfma_f32_16x16x32_bf16 v[36:39], v[136:139], v[212:215], v[36:39]
	v_mfma_f32_16x16x32_bf16 v[36:39], v[140:143], v[216:219], v[36:39]
	v_mfma_f32_16x16x32_bf16 v[40:43], v[144:147], v[212:215], v[40:43]
	v_mfma_f32_16x16x32_bf16 v[40:43], v[170:173], v[216:219], v[40:43]
	v_mfma_f32_16x16x32_bf16 v[68:71], v[136:139], v[220:223], v[68:71]
	v_mfma_f32_16x16x32_bf16 v[68:71], v[140:143], v[224:227], v[68:71]
	v_mfma_f32_16x16x32_bf16 v[72:75], v[144:147], v[220:223], v[72:75]
	v_mfma_f32_16x16x32_bf16 v[72:75], v[170:173], v[224:227], v[72:75]
	v_mfma_f32_16x16x32_bf16 v[100:103], v[136:139], v[228:231], v[100:103]
	v_mfma_f32_16x16x32_bf16 v[100:103], v[140:143], v[232:235], v[100:103]
	v_mfma_f32_16x16x32_bf16 v[104:107], v[144:147], v[228:231], v[104:107]
	v_mfma_f32_16x16x32_bf16 v[104:107], v[170:173], v[232:235], v[104:107]
	v_mfma_f32_16x16x32_bf16 v[128:131], v[136:139], v[236:239], v[128:131]
	v_mfma_f32_16x16x32_bf16 v[128:131], v[140:143], v[240:243], v[128:131]
	v_mfma_f32_16x16x32_bf16 v[124:127], v[144:147], v[236:239], v[124:127]
	v_mfma_f32_16x16x32_bf16 v[124:127], v[170:173], v[240:243], v[124:127]
	s_setprio 0
	s_setprio 1
	v_mfma_f32_16x16x32_bf16 v[8:11], v[174:177], v[212:215], v[8:11]
	v_mfma_f32_16x16x32_bf16 v[8:11], v[178:181], v[216:219], v[8:11]
	v_mfma_f32_16x16x32_bf16 v[4:7], v[182:185], v[212:215], v[4:7]
	v_mfma_f32_16x16x32_bf16 v[4:7], v[208:211], v[216:219], v[4:7]
	v_mfma_f32_16x16x32_bf16 v[32:35], v[174:177], v[220:223], v[32:35]
	v_mfma_f32_16x16x32_bf16 v[32:35], v[178:181], v[224:227], v[32:35]
	v_mfma_f32_16x16x32_bf16 v[28:31], v[182:185], v[220:223], v[28:31]
	v_mfma_f32_16x16x32_bf16 v[28:31], v[208:211], v[224:227], v[28:31]
	v_mfma_f32_16x16x32_bf16 v[56:59], v[174:177], v[228:231], v[56:59]
	v_mfma_f32_16x16x32_bf16 v[56:59], v[178:181], v[232:235], v[56:59]
	v_mfma_f32_16x16x32_bf16 v[52:55], v[182:185], v[228:231], v[52:55]
	v_mfma_f32_16x16x32_bf16 v[52:55], v[208:211], v[232:235], v[52:55]
	v_mfma_f32_16x16x32_bf16 v[80:83], v[174:177], v[236:239], v[80:83]
	v_mfma_f32_16x16x32_bf16 v[80:83], v[178:181], v[240:243], v[80:83]
	v_mfma_f32_16x16x32_bf16 v[76:79], v[182:185], v[236:239], v[76:79]
	v_mfma_f32_16x16x32_bf16 v[76:79], v[208:211], v[240:243], v[76:79]
	s_setprio 0
	s_barrier
	s_add_i32 s10, s27, s67
	v_lshl_add_u64 v[244:245], s[62:63], 0, v[2:3]
	s_mov_b32 m0, s10
	ds_read_b128 v[212:215], v197 offset:16384
	ds_read_b128 v[216:219], v197 offset:17408
	ds_read_b128 v[220:223], v197 offset:18432
	ds_read_b128 v[224:227], v197 offset:19456
	ds_read_b128 v[228:231], v197 offset:20480
	ds_read_b128 v[232:235], v197 offset:21504
	ds_read_b128 v[236:239], v197 offset:22528
	ds_read_b128 v[240:243], v197 offset:23552
	global_load_lds_dwordx4 v[244:245], off
	s_add_i32 m0, s10, 0x2000
	s_add_u32 s10, s62, 0x80000
	v_lshl_add_u64 v[246:247], s[62:63], 0, v[150:151]
	s_addc_u32 s11, s63, 0
	s_add_i32 s25, s25, s67
	global_load_lds_dwordx4 v[246:247], off
	v_lshl_add_u64 v[248:249], s[10:11], 0, v[2:3]
	s_mov_b32 m0, s25
	v_lshl_add_u64 v[160:161], s[64:65], 0, v[148:149]
	global_load_lds_dwordx4 v[248:249], off
	v_lshl_add_u64 v[248:249], s[10:11], 0, v[150:151]
	s_add_i32 m0, s25, 0x2000
	s_nop 0
	global_load_lds_dwordx4 v[248:249], off
	v_lshl_add_u64 v[248:249], s[64:65], 0, v[0:1]
	s_mov_b32 m0, s53
	s_nop 0
	global_load_lds_dwordx4 v[248:249], off
	s_mov_b32 m0, s66
	s_nop 0
	global_load_lds_dwordx4 v[160:161], off
	s_waitcnt vmcnt(8)
	s_waitcnt lgkmcnt(0)
	s_barrier
	s_setprio 1
	s_waitcnt lgkmcnt(0)
	v_mfma_f32_16x16x32_bf16 v[120:123], v[136:139], v[212:215], v[120:123]
	v_mfma_f32_16x16x32_bf16 v[120:123], v[140:143], v[216:219], v[120:123]
	v_mfma_f32_16x16x32_bf16 v[116:119], v[144:147], v[212:215], v[116:119]
	v_mfma_f32_16x16x32_bf16 v[116:119], v[170:173], v[216:219], v[116:119]
	v_mfma_f32_16x16x32_bf16 v[96:99], v[136:139], v[220:223], v[96:99]
	v_mfma_f32_16x16x32_bf16 v[96:99], v[140:143], v[224:227], v[96:99]
	v_mfma_f32_16x16x32_bf16 v[92:95], v[144:147], v[220:223], v[92:95]
	v_mfma_f32_16x16x32_bf16 v[92:95], v[170:173], v[224:227], v[92:95]
	v_mfma_f32_16x16x32_bf16 v[64:67], v[136:139], v[228:231], v[64:67]
	v_mfma_f32_16x16x32_bf16 v[64:67], v[140:143], v[232:235], v[64:67]
	v_mfma_f32_16x16x32_bf16 v[60:63], v[144:147], v[228:231], v[60:63]
	v_mfma_f32_16x16x32_bf16 v[60:63], v[170:173], v[232:235], v[60:63]
	v_mfma_f32_16x16x32_bf16 v[24:27], v[136:139], v[236:239], v[24:27]
	v_mfma_f32_16x16x32_bf16 v[24:27], v[140:143], v[240:243], v[24:27]
	v_mfma_f32_16x16x32_bf16 v[20:23], v[144:147], v[236:239], v[20:23]
	v_mfma_f32_16x16x32_bf16 v[20:23], v[170:173], v[240:243], v[20:23]
	s_setprio 0
	s_setprio 1
	v_mfma_f32_16x16x32_bf16 v[112:115], v[174:177], v[212:215], v[112:115]
	v_mfma_f32_16x16x32_bf16 v[112:115], v[178:181], v[216:219], v[112:115]
	v_mfma_f32_16x16x32_bf16 v[108:111], v[182:185], v[212:215], v[108:111]
	v_mfma_f32_16x16x32_bf16 v[108:111], v[208:211], v[216:219], v[108:111]
	v_mfma_f32_16x16x32_bf16 v[88:91], v[174:177], v[220:223], v[88:91]
	v_mfma_f32_16x16x32_bf16 v[88:91], v[178:181], v[224:227], v[88:91]
	v_mfma_f32_16x16x32_bf16 v[84:87], v[182:185], v[220:223], v[84:87]
	v_mfma_f32_16x16x32_bf16 v[84:87], v[208:211], v[224:227], v[84:87]
	v_mfma_f32_16x16x32_bf16 v[48:51], v[174:177], v[228:231], v[48:51]
	v_mfma_f32_16x16x32_bf16 v[48:51], v[178:181], v[232:235], v[48:51]
	v_mfma_f32_16x16x32_bf16 v[44:47], v[182:185], v[228:231], v[44:47]
	v_mfma_f32_16x16x32_bf16 v[44:47], v[208:211], v[232:235], v[44:47]
	v_mfma_f32_16x16x32_bf16 v[16:19], v[174:177], v[236:239], v[16:19]
	v_mfma_f32_16x16x32_bf16 v[16:19], v[178:181], v[240:243], v[16:19]
	v_mfma_f32_16x16x32_bf16 v[12:15], v[182:185], v[236:239], v[12:15]
	v_mfma_f32_16x16x32_bf16 v[12:15], v[208:211], v[240:243], v[12:15]
	s_setprio 0
	s_barrier
; #define PG8_STAGE(bufoff, gbase, voff) do { _Pragma("unroll") for (int _i = 0; _i < 2; ++_i) \
;         __builtin_amdgcn_global_load_lds((const unsigned*)((const char*)(gbase) + (voff)[_i]), (LAS unsigned*)(lds + (bufoff) + ldsw + _i * 8192), 16, 0, 0); } while (0)
; #define PG8_LDA(dst, b, h) do { _Pragma("unroll") for (int m = 0; m < 4; ++m) _Pragma("unroll") for (int k = 0; k < 2; ++k) dst[m][k] = *(const LAS bf16x8*)(lds + PG8_SA(b, h) + aoff + m * 2048 + k * 1024); } while (0)
; #define PG8_LDB(dst, b, h) do { _Pragma("unroll") for (int n = 0; n < 2; ++n) _Pragma("unroll") for (int k = 0; k < 2; ++k) dst[n][k] = *(const LAS bf16x8*)(lds + PG8_SB(b, h) + boff + n * 2048 + k * 1024); } while (0)
; #define PG8_MMA(ai, bj, At, Bt) do { __builtin_amdgcn_s_setprio(1); _Pragma("unroll") for (int m = 0; m < 4; ++m) _Pragma("unroll") for (int n = 0; n < 2; ++n) _Pragma("unroll") for (int k = 0; k < 2; ++k) \
;         acc[ai][bj][m][n] = __builtin_amdgcn_mfma_f32_16x16x32_bf16(Bt[n][k], At[m][k], acc[ai][bj][m][n], 0, 0, 0); __builtin_amdgcn_s_setprio(0); } while (0)
; #define PG8_WAIT_V(n) asm volatile("s_waitcnt vmcnt(" #n ")" ::: "memory")
; #define PG8_WAIT_L(n) asm volatile("s_waitcnt lgkmcnt(" #n ")" ::: "memory")
; #define PG8_BAR __builtin_amdgcn_s_barrier()
; #define PG8_SCHED __builtin_amdgcn_sched_barrier(0)
; template <class Epi, class Sched, bool ALIGN_EPI = true>
; __device__ __forceinline__ void gemm_phase(LAS unsigned char* lds, const Gemm g, const Sched& S, const Epi& E) {
;     ...
;             PG8_LDB(B0, 1, 0); PG8_LDB(B1, 1, 1); PG8_SCHED; PG8_LDA(At, 1, 0); PG8_STAGE(PG8_SA(0, 1), a2 + hA, voffA);
;             PG8_WAIT_V(8); PG8_WAIT_L(0); PG8_BAR; PG8_MMA(0, 0, At, B0); PG8_MMA(0, 1, At, B1); PG8_BAR; PG8_SCHED;
	s_add_i32 s25, 0, 0x18000
	v_add_u32_e32 v162, s25, v186
	s_add_i32 s26, 0, 0x1c000
	ds_read_b128 v[136:139], v162
	ds_read_b128 v[140:143], v162 offset:1024
	ds_read_b128 v[144:147], v162 offset:2048
	ds_read_b128 v[170:173], v162 offset:3072
	v_add_u32_e32 v162, s26, v186
	ds_read_b128 v[174:177], v162
	ds_read_b128 v[178:181], v162 offset:1024
	ds_read_b128 v[182:185], v162 offset:2048
	ds_read_b128 v[208:211], v162 offset:3072
	s_add_u32 s10, s64, 0x80000
	s_addc_u32 s11, s65, 0
	s_mov_b32 m0, s75
	v_lshl_add_u64 v[162:163], s[10:11], 0, v[0:1]
	ds_read_b128 v[212:215], v197 offset:32768
	ds_read_b128 v[216:219], v197 offset:33792
	ds_read_b128 v[220:223], v197 offset:34816
	ds_read_b128 v[224:227], v197 offset:35840
	ds_read_b128 v[228:231], v197 offset:36864
	ds_read_b128 v[232:235], v197 offset:37888
	ds_read_b128 v[236:239], v197 offset:38912
	ds_read_b128 v[240:243], v197 offset:39936
	global_load_lds_dwordx4 v[162:163], off
	v_lshl_add_u64 v[162:163], s[10:11], 0, v[148:149]
	s_mov_b32 m0, s76
	s_nop 0
	global_load_lds_dwordx4 v[162:163], off
	s_waitcnt vmcnt(8)
	s_waitcnt lgkmcnt(0)
	s_barrier
	s_setprio 1
	s_waitcnt lgkmcnt(0)
	v_mfma_f32_16x16x32_bf16 v[36:39], v[136:139], v[212:215], v[36:39]
	v_mfma_f32_16x16x32_bf16 v[36:39], v[140:143], v[216:219], v[36:39]
	v_mfma_f32_16x16x32_bf16 v[40:43], v[144:147], v[212:215], v[40:43]
	v_mfma_f32_16x16x32_bf16 v[40:43], v[170:173], v[216:219], v[40:43]
	v_mfma_f32_16x16x32_bf16 v[68:71], v[136:139], v[220:223], v[68:71]
	v_mfma_f32_16x16x32_bf16 v[68:71], v[140:143], v[224:227], v[68:71]
	v_mfma_f32_16x16x32_bf16 v[72:75], v[144:147], v[220:223], v[72:75]
	v_mfma_f32_16x16x32_bf16 v[72:75], v[170:173], v[224:227], v[72:75]
	v_mfma_f32_16x16x32_bf16 v[100:103], v[136:139], v[228:231], v[100:103]
	v_mfma_f32_16x16x32_bf16 v[100:103], v[140:143], v[232:235], v[100:103]
	v_mfma_f32_16x16x32_bf16 v[104:107], v[144:147], v[228:231], v[104:107]
	v_mfma_f32_16x16x32_bf16 v[104:107], v[170:173], v[232:235], v[104:107]
	v_mfma_f32_16x16x32_bf16 v[128:131], v[136:139], v[236:239], v[128:131]
	v_mfma_f32_16x16x32_bf16 v[128:131], v[140:143], v[240:243], v[128:131]
	v_mfma_f32_16x16x32_bf16 v[124:127], v[144:147], v[236:239], v[124:127]
	v_mfma_f32_16x16x32_bf16 v[124:127], v[170:173], v[240:243], v[124:127]
	s_setprio 0
	s_setprio 1
	v_mfma_f32_16x16x32_bf16 v[8:11], v[174:177], v[212:215], v[8:11]
	v_mfma_f32_16x16x32_bf16 v[8:11], v[178:181], v[216:219], v[8:11]
	v_mfma_f32_16x16x32_bf16 v[4:7], v[182:185], v[212:215], v[4:7]
	v_mfma_f32_16x16x32_bf16 v[4:7], v[208:211], v[216:219], v[4:7]
	v_mfma_f32_16x16x32_bf16 v[32:35], v[174:177], v[220:223], v[32:35]
	v_mfma_f32_16x16x32_bf16 v[32:35], v[178:181], v[224:227], v[32:35]
	v_mfma_f32_16x16x32_bf16 v[28:31], v[182:185], v[220:223], v[28:31]
	v_mfma_f32_16x16x32_bf16 v[28:31], v[208:211], v[224:227], v[28:31]
	v_mfma_f32_16x16x32_bf16 v[56:59], v[174:177], v[228:231], v[56:59]
	v_mfma_f32_16x16x32_bf16 v[56:59], v[178:181], v[232:235], v[56:59]
	v_mfma_f32_16x16x32_bf16 v[52:55], v[182:185], v[228:231], v[52:55]
	v_mfma_f32_16x16x32_bf16 v[52:55], v[208:211], v[232:235], v[52:55]
	v_mfma_f32_16x16x32_bf16 v[80:83], v[174:177], v[236:239], v[80:83]
	v_mfma_f32_16x16x32_bf16 v[80:83], v[178:181], v[240:243], v[80:83]
	v_mfma_f32_16x16x32_bf16 v[76:79], v[182:185], v[236:239], v[76:79]
	v_mfma_f32_16x16x32_bf16 v[76:79], v[208:211], v[240:243], v[76:79]
	s_setprio 0
	s_barrier
; #define PG8_STAGE(bufoff, gbase, voff) do { _Pragma("unroll") for (int _i = 0; _i < 2; ++_i) \
;         __builtin_amdgcn_global_load_lds((const unsigned*)((const char*)(gbase) + (voff)[_i]), (LAS unsigned*)(lds + (bufoff) + ldsw + _i * 8192), 16, 0, 0); } while (0)
; #define PG8_LDA(dst, b, h) do { _Pragma("unroll") for (int m = 0; m < 4; ++m) _Pragma("unroll") for (int k = 0; k < 2; ++k) dst[m][k] = *(const LAS bf16x8*)(lds + PG8_SA(b, h) + aoff + m * 2048 + k * 1024); } while (0)
; #define PG8_MMA(ai, bj, At, Bt) do { __builtin_amdgcn_s_setprio(1); _Pragma("unroll") for (int m = 0; m < 4; ++m) _Pragma("unroll") for (int n = 0; n < 2; ++n) _Pragma("unroll") for (int k = 0; k < 2; ++k) \
;         acc[ai][bj][m][n] = __builtin_amdgcn_mfma_f32_16x16x32_bf16(Bt[n][k], At[m][k], acc[ai][bj][m][n], 0, 0, 0); __builtin_amdgcn_s_setprio(0); } while (0)
; #define PG8_WAIT_V(n) asm volatile("s_waitcnt vmcnt(" #n ")" ::: "memory")
; #define PG8_WAIT_L(n) asm volatile("s_waitcnt lgkmcnt(" #n ")" ::: "memory")
; #define PG8_BAR __builtin_amdgcn_s_barrier()
; #define PG8_SCHED __builtin_amdgcn_sched_barrier(0)
; template <class Epi, class Sched, bool ALIGN_EPI = true>
; __device__ __forceinline__ void gemm_phase(LAS unsigned char* lds, const Gemm g, const Sched& S, const Epi& E) {
;     ...
;             PG8_LDA(At, 1, 1); PG8_STAGE(PG8_SB(1, 0), b3, voffB); PG8_STAGE(PG8_SB(1, 1), b3 + hB, voffB); PG8_STAGE(PG8_SA(1, 0), a3, voffA);
;             PG8_WAIT_V(8); PG8_WAIT_L(0); PG8_BAR; PG8_MMA(1, 0, At, B0); PG8_MMA(1, 1, At, B1); PG8_BAR; PG8_SCHED;
	s_add_i32 s10, s25, s67
	v_lshl_add_u64 v[162:163], v[244:245], 0, s[86:87]
	s_mov_b32 m0, s10
	ds_read_b128 v[212:215], v197 offset:49152
	ds_read_b128 v[216:219], v197 offset:50176
	ds_read_b128 v[220:223], v197 offset:51200
	ds_read_b128 v[224:227], v197 offset:52224
	ds_read_b128 v[228:231], v197 offset:53248
	ds_read_b128 v[232:235], v197 offset:54272
	ds_read_b128 v[236:239], v197 offset:55296
	ds_read_b128 v[240:243], v197 offset:56320
	global_load_lds_dwordx4 v[162:163], off
	s_add_i32 m0, s10, 0x2000
	s_add_u32 s10, s62, 0x80080
	v_lshl_add_u64 v[162:163], v[246:247], 0, s[86:87]
	s_addc_u32 s11, s63, 0
	s_add_i32 s25, s26, s67
	global_load_lds_dwordx4 v[162:163], off
	v_lshl_add_u64 v[162:163], s[10:11], 0, v[2:3]
	s_mov_b32 m0, s25
	v_lshl_add_u64 v[160:161], v[160:161], 0, s[86:87]
	global_load_lds_dwordx4 v[162:163], off
	v_lshl_add_u64 v[162:163], s[10:11], 0, v[150:151]
	s_add_i32 m0, s25, 0x2000
	s_nop 0
	global_load_lds_dwordx4 v[162:163], off
	v_lshl_add_u64 v[162:163], v[248:249], 0, s[86:87]
	s_mov_b32 m0, s79
	s_nop 0
	global_load_lds_dwordx4 v[162:163], off
	s_mov_b32 m0, s80
	s_nop 0
	global_load_lds_dwordx4 v[160:161], off
	s_waitcnt vmcnt(8)
	s_waitcnt lgkmcnt(0)
	s_barrier
	s_setprio 1
	s_waitcnt lgkmcnt(0)
	v_mfma_f32_16x16x32_bf16 v[120:123], v[136:139], v[212:215], v[120:123]
	v_mfma_f32_16x16x32_bf16 v[120:123], v[140:143], v[216:219], v[120:123]
	v_mfma_f32_16x16x32_bf16 v[116:119], v[144:147], v[212:215], v[116:119]
	v_mfma_f32_16x16x32_bf16 v[116:119], v[170:173], v[216:219], v[116:119]
	v_mfma_f32_16x16x32_bf16 v[96:99], v[136:139], v[220:223], v[96:99]
	v_mfma_f32_16x16x32_bf16 v[96:99], v[140:143], v[224:227], v[96:99]
	v_mfma_f32_16x16x32_bf16 v[92:95], v[144:147], v[220:223], v[92:95]
	v_mfma_f32_16x16x32_bf16 v[92:95], v[170:173], v[224:227], v[92:95]
	v_mfma_f32_16x16x32_bf16 v[64:67], v[136:139], v[228:231], v[64:67]
	v_mfma_f32_16x16x32_bf16 v[64:67], v[140:143], v[232:235], v[64:67]
	v_mfma_f32_16x16x32_bf16 v[60:63], v[144:147], v[228:231], v[60:63]
	v_mfma_f32_16x16x32_bf16 v[60:63], v[170:173], v[232:235], v[60:63]
	v_mfma_f32_16x16x32_bf16 v[24:27], v[136:139], v[236:239], v[24:27]
	v_mfma_f32_16x16x32_bf16 v[24:27], v[140:143], v[240:243], v[24:27]
	v_mfma_f32_16x16x32_bf16 v[20:23], v[144:147], v[236:239], v[20:23]
	v_mfma_f32_16x16x32_bf16 v[20:23], v[170:173], v[240:243], v[20:23]
	s_setprio 0
	s_setprio 1
	v_mfma_f32_16x16x32_bf16 v[112:115], v[174:177], v[212:215], v[112:115]
	v_mfma_f32_16x16x32_bf16 v[112:115], v[178:181], v[216:219], v[112:115]
	v_mfma_f32_16x16x32_bf16 v[108:111], v[182:185], v[212:215], v[108:111]
	v_mfma_f32_16x16x32_bf16 v[108:111], v[208:211], v[216:219], v[108:111]
	v_mfma_f32_16x16x32_bf16 v[88:91], v[174:177], v[220:223], v[88:91]
	v_mfma_f32_16x16x32_bf16 v[88:91], v[178:181], v[224:227], v[88:91]
	v_mfma_f32_16x16x32_bf16 v[84:87], v[182:185], v[220:223], v[84:87]
	v_mfma_f32_16x16x32_bf16 v[84:87], v[208:211], v[224:227], v[84:87]
	v_mfma_f32_16x16x32_bf16 v[48:51], v[174:177], v[228:231], v[48:51]
	v_mfma_f32_16x16x32_bf16 v[48:51], v[178:181], v[232:235], v[48:51]
	v_mfma_f32_16x16x32_bf16 v[44:47], v[182:185], v[228:231], v[44:47]
	v_mfma_f32_16x16x32_bf16 v[44:47], v[208:211], v[232:235], v[44:47]
	v_mfma_f32_16x16x32_bf16 v[16:19], v[174:177], v[236:239], v[16:19]
	v_mfma_f32_16x16x32_bf16 v[16:19], v[178:181], v[240:243], v[16:19]
	v_mfma_f32_16x16x32_bf16 v[12:15], v[182:185], v[236:239], v[12:15]
	v_mfma_f32_16x16x32_bf16 v[12:15], v[208:211], v[240:243], v[12:15]
	s_setprio 0
	s_barrier
	s_add_i32 s24, s24, 2
	s_cmp_gt_u32 s24, 29
	s_mov_b64 s[10:11], vcc
	s_cbranch_scc0 .LBB0_667

;     __device__ bool next(int i, Unit& u) const { if (i >= 2) return false; const int x = c & 7, j = c >> 3; u.pm = 32 * i + 4 * x + (j & 3); u.pn = j >> 2; return true; }
; #define PG8_STAGE(bufoff, gbase, voff) do { _Pragma("unroll") for (int _i = 0; _i < 2; ++_i) \
;         __builtin_amdgcn_global_load_lds((const unsigned*)((const char*)(gbase) + (voff)[_i]), (LAS unsigned*)(lds + (bufoff) + ldsw + _i * 8192), 16, 0, 0); } while (0)
; #define PG8_LDA(dst, b, h) do { _Pragma("unroll") for (int m = 0; m < 4; ++m) _Pragma("unroll") for (int k = 0; k < 2; ++k) dst[m][k] = *(const LAS bf16x8*)(lds + PG8_SA(b, h) + aoff + m * 2048 + k * 1024); } while (0)
; #define PG8_WAIT_V(n) asm volatile("s_waitcnt vmcnt(" #n ")" ::: "memory")
;     __device__ __forceinline__ void operator()(f32x4 (&acc)[2][2][4][2], const Unit& u, int wr, int wc, int fr_, int fq_, int wid, int lane_) const {
;     ...
;             const int t = wid * 64 + lane, kind = t >> 6, pr = t & 63, bj = kind >> 2, tap = kind & 3;
;             const float* src = (tap < 3) ? (cw + (size_t)tap * FF2 + bj * FF + u.pn * 128 + 2 * pr) : (cb + bj * FF + u.pn * 128 + 2 * pr);
;             const f32x2 wv = *(const f32x2*)src;
; template <class Epi, class Sched, bool ALIGN_EPI = true>
; __device__ __forceinline__ void gemm_phase(LAS unsigned char* lds, const Gemm g, const Sched& S, const Epi& E) {
;     ...
;         const bool has_next = S.next(ui + 1, nxt);
;         const char* nA = has_next ? (const char*)g.A + ((size_t)nxt.pm * BM * g.lda + (size_t)nxt.pn * g.a_pn_off) * 2 : cA; const char* nB = has_next ? (const char*)g.Bt + (size_t)nxt.pn * BM * g.ldb * 2 : cB;
;         for (int t = 0; t < nt; t += 2) {
;             const bool last = (t == nt - 2);
;             const char* a1 = cA + (size_t)(t + 1) * kstep;
;             const char* a2 = last ? nA : cA + (size_t)(t + 2) * kstep; const char* b2 = last ? nB : cB + (size_t)(t + 2) * kstep;
;             const char* a3 = a2 + kstep; const char* b3 = b2 + kstep;
;             PG8_LDB(B0, 0, 0); PG8_LDB(B1, 0, 1); PG8_SCHED; PG8_LDA(At, 0, 0); PG8_STAGE(PG8_SA(1, 1), a1 + hA, voffA);
;             PG8_WAIT_V(8); PG8_WAIT_L(0); PG8_BAR; PG8_MMA(0, 0, At, B0); PG8_MMA(0, 1, At, B1); PG8_BAR; PG8_SCHED;
;             PG8_LDA(At, 0, 1); PG8_STAGE(PG8_SB(0, 0), b2, voffB); PG8_STAGE(PG8_SB(0, 1), b2 + hB, voffB); PG8_STAGE(PG8_SA(0, 0), a2, voffA);
.LBB0_827:
	s_ashr_i32 s39, s38, 31
	s_lshl_b64 s[16:17], s[38:39], 20
	s_add_u32 s40, s46, s16
	s_addc_u32 s41, s47, s17
	s_and_b64 s[16:17], s[4:5], exec
	s_cselect_b32 s16, s41, s7
	s_cselect_b32 s17, s40, s6
	s_ashr_i32 s15, s14, 31
	s_lshl_b64 s[18:19], s[14:15], 20
	s_add_u32 s42, s53, s18
	s_addc_u32 s43, s60, s19
	s_and_b64 s[18:19], s[4:5], exec
	s_cselect_b32 s15, s43, s45
	s_cselect_b32 s18, s42, s44
	s_add_u32 s6, s6, 0x80080
	s_addc_u32 s7, s7, 0
	s_add_u32 s19, s44, 0x100
	s_addc_u32 s24, s45, 0
	s_mov_b32 s25, -2
	v_add_u32_e32 v228, s77, v158
	v_ashrrev_i32_e32 v229, 6, v228
	v_and_b32_e32 v230, 3, v229
	v_lshrrev_b32_e32 v231, 8, v228
	v_mul_u32_u24_e32 v228, 0x2c00, v230
	v_lshlrev_b32_e32 v228, 2, v228
	v_mov_b32_e32 v229, 0
	v_lshl_add_u64 v[232:233], s[2:3], 0, v[228:229]
	v_mov_b32_e32 v228, s9
	v_cmp_eq_u32_e32 vcc, 3, v230
	v_mul_i32_i24_e32 v234, 0x1600, v231
	v_ashrrev_i32_e32 v235, 31, v234
	v_cndmask_b32_e32 v233, v233, v228, vcc
	v_mov_b32_e32 v228, s8
	v_cndmask_b32_e32 v232, v232, v228, vcc
	v_lshl_add_u64 v[232:233], v[234:235], 2, v[232:233]
	s_lshl_b32 s26, s82, 7
	s_ashr_i32 s27, s26, 31
	v_lshl_add_u64 v[232:233], s[26:27], 2, v[232:233]
	v_and_b32_e32 v228, 63, v158
	v_lshlrev_b32_e32 v228, 3, v228
	v_mov_b32_e32 v229, 0
	v_lshl_add_u64 v[232:233], v[232:233], 0, v[228:229]
	global_load_dwordx2 v[226:227], v[232:233], off
	s_add_u32 s26, s6, 0xfff80080
	s_addc_u32 s27, s7, -1
	s_add_i32 s30, 0, 0x10000
	s_cmp_eq_u32 s25, 28
	s_cselect_b32 s59, s16, s27
	s_cselect_b32 s58, s17, s26
	v_add_u32_e32 v2, s30, v204
	s_cselect_b32 s45, s15, s24
	s_cselect_b32 s44, s18, s19
	s_add_i32 s31, 0, 0x14000
	ds_read_b128 v[132:135], v2
	ds_read_b128 v[136:139], v2 offset:1024
	ds_read_b128 v[140:143], v2 offset:2048
	ds_read_b128 v[144:147], v2 offset:3072
	v_add_u32_e32 v2, s31, v204
	ds_read_b128 v[148:151], v2
	ds_read_b128 v[152:155], v2 offset:1024
	ds_read_b128 v[174:177], v2 offset:2048
	ds_read_b128 v[178:181], v2 offset:3072
	v_lshl_add_u64 v[156:157], s[6:7], 0, v[170:171]
	s_add_i32 m0, s62, 0xc000
	ds_read_b128 v[182:185], v205
	ds_read_b128 v[186:189], v205 offset:1024
	ds_read_b128 v[190:193], v205 offset:2048
	ds_read_b128 v[194:197], v205 offset:3072
	ds_read_b128 v[206:209], v205 offset:4096
	ds_read_b128 v[210:213], v205 offset:5120
	ds_read_b128 v[214:217], v205 offset:6144
	ds_read_b128 v[218:221], v205 offset:7168
	global_load_lds_dwordx4 v[156:157], off
	v_lshl_add_u64 v[156:157], s[6:7], 0, v[172:173]
	s_add_i32 m0, s62, 0xe000
	s_nop 0
	global_load_lds_dwordx4 v[156:157], off
	s_waitcnt vmcnt(8)
	s_waitcnt lgkmcnt(0)
	s_barrier
	s_setprio 1
	s_waitcnt lgkmcnt(0)
	v_mfma_f32_16x16x32_bf16 v[116:119], v[132:135], v[182:185], 0
	v_mfma_f32_16x16x32_bf16 v[116:119], v[136:139], v[186:189], v[116:119]
	v_mfma_f32_16x16x32_bf16 v[100:103], v[140:143], v[182:185], 0
	v_mfma_f32_16x16x32_bf16 v[100:103], v[144:147], v[186:189], v[100:103]
	v_mfma_f32_16x16x32_bf16 v[108:111], v[132:135], v[190:193], 0
	v_mfma_f32_16x16x32_bf16 v[108:111], v[136:139], v[194:197], v[108:111]
	v_mfma_f32_16x16x32_bf16 v[96:99], v[140:143], v[190:193], 0
	v_mfma_f32_16x16x32_bf16 v[96:99], v[144:147], v[194:197], v[96:99]
	v_mfma_f32_16x16x32_bf16 v[88:91], v[132:135], v[206:209], 0
	v_mfma_f32_16x16x32_bf16 v[88:91], v[136:139], v[210:213], v[88:91]
	v_mfma_f32_16x16x32_bf16 v[84:87], v[140:143], v[206:209], 0
	v_mfma_f32_16x16x32_bf16 v[84:87], v[144:147], v[210:213], v[84:87]
	v_mfma_f32_16x16x32_bf16 v[72:75], v[132:135], v[214:217], 0
	v_mfma_f32_16x16x32_bf16 v[72:75], v[136:139], v[218:221], v[72:75]
	v_mfma_f32_16x16x32_bf16 v[80:83], v[140:143], v[214:217], 0
	v_mfma_f32_16x16x32_bf16 v[80:83], v[144:147], v[218:221], v[80:83]
	s_setprio 0
	s_setprio 1
	v_mfma_f32_16x16x32_bf16 v[128:131], v[148:151], v[182:185], 0
	v_mfma_f32_16x16x32_bf16 v[128:131], v[152:155], v[186:189], v[128:131]
	v_mfma_f32_16x16x32_bf16 v[44:47], v[174:177], v[182:185], 0
	v_mfma_f32_16x16x32_bf16 v[44:47], v[178:181], v[186:189], v[44:47]
	v_mfma_f32_16x16x32_bf16 v[124:127], v[148:151], v[190:193], 0
	v_mfma_f32_16x16x32_bf16 v[124:127], v[152:155], v[194:197], v[124:127]
	v_mfma_f32_16x16x32_bf16 v[36:39], v[174:177], v[190:193], 0
	v_mfma_f32_16x16x32_bf16 v[36:39], v[178:181], v[194:197], v[36:39]
	v_mfma_f32_16x16x32_bf16 v[120:123], v[148:151], v[206:209], 0
	v_mfma_f32_16x16x32_bf16 v[120:123], v[152:155], v[210:213], v[120:123]
	v_mfma_f32_16x16x32_bf16 v[32:35], v[174:177], v[206:209], 0
	v_mfma_f32_16x16x32_bf16 v[32:35], v[178:181], v[210:213], v[32:35]
	v_mfma_f32_16x16x32_bf16 v[112:115], v[148:151], v[214:217], 0
	v_mfma_f32_16x16x32_bf16 v[112:115], v[152:155], v[218:221], v[112:115]
	v_mfma_f32_16x16x32_bf16 v[28:31], v[174:177], v[214:217], 0
	v_mfma_f32_16x16x32_bf16 v[28:31], v[178:181], v[218:221], v[28:31]
	s_setprio 0
	s_barrier
	s_add_i32 s26, s30, s61
	v_lshl_add_u64 v[156:157], s[44:45], 0, v[166:167]
	s_mov_b32 m0, s26
	ds_read_b128 v[182:185], v205 offset:16384
	ds_read_b128 v[186:189], v205 offset:17408
	ds_read_b128 v[190:193], v205 offset:18432
	ds_read_b128 v[194:197], v205 offset:19456
	ds_read_b128 v[206:209], v205 offset:20480
	ds_read_b128 v[210:213], v205 offset:21504
	ds_read_b128 v[214:217], v205 offset:22528
	ds_read_b128 v[218:221], v205 offset:23552
	global_load_lds_dwordx4 v[156:157], off
	s_add_i32 m0, s26, 0x2000
	s_add_u32 s26, s44, 0x80000
	v_lshl_add_u64 v[160:161], s[44:45], 0, v[0:1]
	s_addc_u32 s27, s45, 0
	s_add_i32 s30, s31, s61
	global_load_lds_dwordx4 v[160:161], off
	v_lshl_add_u64 v[162:163], s[26:27], 0, v[166:167]
	s_mov_b32 m0, s30
	v_lshl_add_u64 v[222:223], s[58:59], 0, v[164:165]
	global_load_lds_dwordx4 v[162:163], off
	v_lshl_add_u64 v[162:163], s[26:27], 0, v[0:1]
	s_add_i32 m0, s30, 0x2000
	s_nop 0
	global_load_lds_dwordx4 v[162:163], off
	v_lshl_add_u64 v[162:163], s[58:59], 0, v[168:169]
	s_mov_b32 m0, s62
	s_nop 0
	global_load_lds_dwordx4 v[162:163], off
	s_mov_b32 m0, s63
	s_nop 0
	global_load_lds_dwordx4 v[222:223], off
	s_waitcnt vmcnt(8)
	s_waitcnt lgkmcnt(0)
	s_barrier
; #define PG8_STAGE(bufoff, gbase, voff) do { _Pragma("unroll") for (int _i = 0; _i < 2; ++_i) \
;         __builtin_amdgcn_global_load_lds((const unsigned*)((const char*)(gbase) + (voff)[_i]), (LAS unsigned*)(lds + (bufoff) + ldsw + _i * 8192), 16, 0, 0); } while (0)
; #define PG8_LDA(dst, b, h) do { _Pragma("unroll") for (int m = 0; m < 4; ++m) _Pragma("unroll") for (int k = 0; k < 2; ++k) dst[m][k] = *(const LAS bf16x8*)(lds + PG8_SA(b, h) + aoff + m * 2048 + k * 1024); } while (0)
; #define PG8_LDB(dst, b, h) do { _Pragma("unroll") for (int n = 0; n < 2; ++n) _Pragma("unroll") for (int k = 0; k < 2; ++k) dst[n][k] = *(const LAS bf16x8*)(lds + PG8_SB(b, h) + boff + n * 2048 + k * 1024); } while (0)
; #define PG8_MMA(ai, bj, At, Bt) do { __builtin_amdgcn_s_setprio(1); _Pragma("unroll") for (int m = 0; m < 4; ++m) _Pragma("unroll") for (int n = 0; n < 2; ++n) _Pragma("unroll") for (int k = 0; k < 2; ++k) \
;         acc[ai][bj][m][n] = __builtin_amdgcn_mfma_f32_16x16x32_bf16(Bt[n][k], At[m][k], acc[ai][bj][m][n], 0, 0, 0); __builtin_amdgcn_s_setprio(0); } while (0)
; #define PG8_WAIT_V(n) asm volatile("s_waitcnt vmcnt(" #n ")" ::: "memory")
; #define PG8_WAIT_L(n) asm volatile("s_waitcnt lgkmcnt(" #n ")" ::: "memory")
; #define PG8_BAR __builtin_amdgcn_s_barrier()
; #define PG8_SCHED __builtin_amdgcn_sched_barrier(0)
; template <class Epi, class Sched, bool ALIGN_EPI = true>
; __device__ __forceinline__ void gemm_phase(LAS unsigned char* lds, const Gemm g, const Sched& S, const Epi& E) {
;     ...
;             PG8_WAIT_V(8); PG8_WAIT_L(0); PG8_BAR; PG8_MMA(1, 0, At, B0); PG8_MMA(1, 1, At, B1); PG8_BAR; PG8_SCHED;
;             PG8_LDB(B0, 1, 0); PG8_LDB(B1, 1, 1); PG8_SCHED; PG8_LDA(At, 1, 0); PG8_STAGE(PG8_SA(0, 1), a2 + hA, voffA);
;             PG8_WAIT_V(8); PG8_WAIT_L(0); PG8_BAR; PG8_MMA(0, 0, At, B0); PG8_MMA(0, 1, At, B1); PG8_BAR; PG8_SCHED;
	s_setprio 1
	s_waitcnt lgkmcnt(0)
	v_mfma_f32_16x16x32_bf16 v[60:63], v[132:135], v[182:185], 0
	v_mfma_f32_16x16x32_bf16 v[60:63], v[136:139], v[186:189], v[60:63]
	v_mfma_f32_16x16x32_bf16 v[68:71], v[140:143], v[182:185], 0
	v_mfma_f32_16x16x32_bf16 v[68:71], v[144:147], v[186:189], v[68:71]
	v_mfma_f32_16x16x32_bf16 v[40:43], v[132:135], v[190:193], 0
	v_mfma_f32_16x16x32_bf16 v[40:43], v[136:139], v[194:197], v[40:43]
	v_mfma_f32_16x16x32_bf16 v[64:67], v[140:143], v[190:193], 0
	v_mfma_f32_16x16x32_bf16 v[64:67], v[144:147], v[194:197], v[64:67]
	v_mfma_f32_16x16x32_bf16 v[24:27], v[132:135], v[206:209], 0
	v_mfma_f32_16x16x32_bf16 v[24:27], v[136:139], v[210:213], v[24:27]
	v_mfma_f32_16x16x32_bf16 v[56:59], v[140:143], v[206:209], 0
	v_mfma_f32_16x16x32_bf16 v[56:59], v[144:147], v[210:213], v[56:59]
	v_mfma_f32_16x16x32_bf16 v[12:15], v[132:135], v[214:217], 0
	v_mfma_f32_16x16x32_bf16 v[12:15], v[136:139], v[218:221], v[12:15]
	v_mfma_f32_16x16x32_bf16 v[48:51], v[140:143], v[214:217], 0
	v_mfma_f32_16x16x32_bf16 v[48:51], v[144:147], v[218:221], v[48:51]
	s_setprio 0
	s_setprio 1
	v_mfma_f32_16x16x32_bf16 v[104:107], v[148:151], v[182:185], 0
	v_mfma_f32_16x16x32_bf16 v[104:107], v[152:155], v[186:189], v[104:107]
	v_mfma_f32_16x16x32_bf16 v[20:23], v[174:177], v[182:185], 0
	v_mfma_f32_16x16x32_bf16 v[20:23], v[178:181], v[186:189], v[20:23]
	v_mfma_f32_16x16x32_bf16 v[92:95], v[148:151], v[190:193], 0
	v_mfma_f32_16x16x32_bf16 v[92:95], v[152:155], v[194:197], v[92:95]
	v_mfma_f32_16x16x32_bf16 v[16:19], v[174:177], v[190:193], 0
	v_mfma_f32_16x16x32_bf16 v[16:19], v[178:181], v[194:197], v[16:19]
	v_mfma_f32_16x16x32_bf16 v[76:79], v[148:151], v[206:209], 0
	v_mfma_f32_16x16x32_bf16 v[76:79], v[152:155], v[210:213], v[76:79]
	v_mfma_f32_16x16x32_bf16 v[8:11], v[174:177], v[206:209], 0
	v_mfma_f32_16x16x32_bf16 v[8:11], v[178:181], v[210:213], v[8:11]
	v_mfma_f32_16x16x32_bf16 v[52:55], v[148:151], v[214:217], 0
	v_mfma_f32_16x16x32_bf16 v[52:55], v[152:155], v[218:221], v[52:55]
	v_mfma_f32_16x16x32_bf16 v[4:7], v[174:177], v[214:217], 0
	v_mfma_f32_16x16x32_bf16 v[4:7], v[178:181], v[218:221], v[4:7]
	s_setprio 0
	s_barrier
	s_add_i32 s30, 0, 0x18000
	v_add_u32_e32 v2, s30, v204
	s_add_i32 s31, 0, 0x1c000
	ds_read_b128 v[132:135], v2
	ds_read_b128 v[136:139], v2 offset:1024
	ds_read_b128 v[140:143], v2 offset:2048
	ds_read_b128 v[144:147], v2 offset:3072
	v_add_u32_e32 v2, s31, v204
	ds_read_b128 v[148:151], v2
	ds_read_b128 v[152:155], v2 offset:1024
	ds_read_b128 v[174:177], v2 offset:2048
	ds_read_b128 v[178:181], v2 offset:3072
	s_add_u32 s26, s58, 0x80000
	s_addc_u32 s27, s59, 0
	s_mov_b32 m0, s64
	v_lshl_add_u64 v[224:225], s[26:27], 0, v[168:169]
	ds_read_b128 v[182:185], v205 offset:32768
	ds_read_b128 v[186:189], v205 offset:33792
	ds_read_b128 v[190:193], v205 offset:34816
	ds_read_b128 v[194:197], v205 offset:35840
	ds_read_b128 v[206:209], v205 offset:36864
	ds_read_b128 v[210:213], v205 offset:37888
	ds_read_b128 v[214:217], v205 offset:38912
	ds_read_b128 v[218:221], v205 offset:39936
	global_load_lds_dwordx4 v[224:225], off
	v_lshl_add_u64 v[224:225], s[26:27], 0, v[164:165]
	s_mov_b32 m0, s65
	s_nop 0
	global_load_lds_dwordx4 v[224:225], off
	s_waitcnt vmcnt(8)
	s_waitcnt lgkmcnt(0)
	s_barrier
	s_setprio 1
	s_waitcnt lgkmcnt(0)
	v_mfma_f32_16x16x32_bf16 v[116:119], v[132:135], v[182:185], v[116:119]
	v_mfma_f32_16x16x32_bf16 v[116:119], v[136:139], v[186:189], v[116:119]
	v_mfma_f32_16x16x32_bf16 v[100:103], v[140:143], v[182:185], v[100:103]
	v_mfma_f32_16x16x32_bf16 v[100:103], v[144:147], v[186:189], v[100:103]
	v_mfma_f32_16x16x32_bf16 v[108:111], v[132:135], v[190:193], v[108:111]
	v_mfma_f32_16x16x32_bf16 v[108:111], v[136:139], v[194:197], v[108:111]
	v_mfma_f32_16x16x32_bf16 v[96:99], v[140:143], v[190:193], v[96:99]
	v_mfma_f32_16x16x32_bf16 v[96:99], v[144:147], v[194:197], v[96:99]
	v_mfma_f32_16x16x32_bf16 v[88:91], v[132:135], v[206:209], v[88:91]
	v_mfma_f32_16x16x32_bf16 v[88:91], v[136:139], v[210:213], v[88:91]
	v_mfma_f32_16x16x32_bf16 v[84:87], v[140:143], v[206:209], v[84:87]
	v_mfma_f32_16x16x32_bf16 v[84:87], v[144:147], v[210:213], v[84:87]
	v_mfma_f32_16x16x32_bf16 v[72:75], v[132:135], v[214:217], v[72:75]
	v_mfma_f32_16x16x32_bf16 v[72:75], v[136:139], v[218:221], v[72:75]
	v_mfma_f32_16x16x32_bf16 v[80:83], v[140:143], v[214:217], v[80:83]
	v_mfma_f32_16x16x32_bf16 v[80:83], v[144:147], v[218:221], v[80:83]
	s_setprio 0
	s_setprio 1
	v_mfma_f32_16x16x32_bf16 v[128:131], v[148:151], v[182:185], v[128:131]
	v_mfma_f32_16x16x32_bf16 v[128:131], v[152:155], v[186:189], v[128:131]
	v_mfma_f32_16x16x32_bf16 v[44:47], v[174:177], v[182:185], v[44:47]
	v_mfma_f32_16x16x32_bf16 v[44:47], v[178:181], v[186:189], v[44:47]
	v_mfma_f32_16x16x32_bf16 v[124:127], v[148:151], v[190:193], v[124:127]
	v_mfma_f32_16x16x32_bf16 v[124:127], v[152:155], v[194:197], v[124:127]
	v_mfma_f32_16x16x32_bf16 v[36:39], v[174:177], v[190:193], v[36:39]
	v_mfma_f32_16x16x32_bf16 v[36:39], v[178:181], v[194:197], v[36:39]
	v_mfma_f32_16x16x32_bf16 v[120:123], v[148:151], v[206:209], v[120:123]
	v_mfma_f32_16x16x32_bf16 v[120:123], v[152:155], v[210:213], v[120:123]
	v_mfma_f32_16x16x32_bf16 v[32:35], v[174:177], v[206:209], v[32:35]
	v_mfma_f32_16x16x32_bf16 v[32:35], v[178:181], v[210:213], v[32:35]
	v_mfma_f32_16x16x32_bf16 v[112:115], v[148:151], v[214:217], v[112:115]
	v_mfma_f32_16x16x32_bf16 v[112:115], v[152:155], v[218:221], v[112:115]
	v_mfma_f32_16x16x32_bf16 v[28:31], v[174:177], v[214:217], v[28:31]
	v_mfma_f32_16x16x32_bf16 v[28:31], v[178:181], v[218:221], v[28:31]
	s_setprio 0
	s_barrier
; #define PG8_STAGE(bufoff, gbase, voff) do { _Pragma("unroll") for (int _i = 0; _i < 2; ++_i) \
;         __builtin_amdgcn_global_load_lds((const unsigned*)((const char*)(gbase) + (voff)[_i]), (LAS unsigned*)(lds + (bufoff) + ldsw + _i * 8192), 16, 0, 0); } while (0)
; #define PG8_LDA(dst, b, h) do { _Pragma("unroll") for (int m = 0; m < 4; ++m) _Pragma("unroll") for (int k = 0; k < 2; ++k) dst[m][k] = *(const LAS bf16x8*)(lds + PG8_SA(b, h) + aoff + m * 2048 + k * 1024); } while (0)
; #define PG8_LDB(dst, b, h) do { _Pragma("unroll") for (int n = 0; n < 2; ++n) _Pragma("unroll") for (int k = 0; k < 2; ++k) dst[n][k] = *(const LAS bf16x8*)(lds + PG8_SB(b, h) + boff + n * 2048 + k * 1024); } while (0)
; #define PG8_MMA(ai, bj, At, Bt) do { __builtin_amdgcn_s_setprio(1); _Pragma("unroll") for (int m = 0; m < 4; ++m) _Pragma("unroll") for (int n = 0; n < 2; ++n) _Pragma("unroll") for (int k = 0; k < 2; ++k) \
;         acc[ai][bj][m][n] = __builtin_amdgcn_mfma_f32_16x16x32_bf16(Bt[n][k], At[m][k], acc[ai][bj][m][n], 0, 0, 0); __builtin_amdgcn_s_setprio(0); } while (0)
; #define PG8_WAIT_V(n) asm volatile("s_waitcnt vmcnt(" #n ")" ::: "memory")
; #define PG8_BAR __builtin_amdgcn_s_barrier()
; template <class Epi, class Sched, bool ALIGN_EPI = true>
; __device__ __forceinline__ void gemm_phase(LAS unsigned char* lds, const Gemm g, const Sched& S, const Epi& E) {
;     ...
;             PG8_LDB(B0, 0, 0); PG8_LDB(B1, 0, 1); PG8_SCHED; PG8_LDA(At, 0, 0); PG8_STAGE(PG8_SA(1, 1), a1 + hA, voffA);
;             PG8_WAIT_V(8); PG8_WAIT_L(0); PG8_BAR; PG8_MMA(0, 0, At, B0); PG8_MMA(0, 1, At, B1); PG8_BAR; PG8_SCHED;
;             PG8_LDA(At, 0, 1); PG8_STAGE(PG8_SB(0, 0), b2, voffB); PG8_STAGE(PG8_SB(0, 1), b2 + hB, voffB); PG8_STAGE(PG8_SA(0, 0), a2, voffA);
;             PG8_WAIT_V(8); PG8_WAIT_L(0); PG8_BAR; PG8_MMA(1, 0, At, B0); PG8_MMA(1, 1, At, B1); PG8_BAR; PG8_SCHED;
;             PG8_LDB(B0, 1, 0); PG8_LDB(B1, 1, 1); PG8_SCHED; PG8_LDA(At, 1, 0); PG8_STAGE(PG8_SA(0, 1), a2 + hA, voffA);
;             PG8_WAIT_V(8); PG8_WAIT_L(0); PG8_BAR; PG8_MMA(0, 0, At, B0); PG8_MMA(0, 1, At, B1); PG8_BAR; PG8_SCHED;
;             PG8_LDA(At, 1, 1); PG8_STAGE(PG8_SB(1, 0), b3, voffB); PG8_STAGE(PG8_SB(1, 1), b3 + hB, voffB); PG8_STAGE(PG8_SA(1, 0), a3, voffA);
;             PG8_WAIT_V(8); PG8_WAIT_L(0); PG8_BAR; PG8_MMA(1, 0, At, B0); PG8_MMA(1, 1, At, B1); PG8_BAR; PG8_SCHED;
	s_add_i32 s26, s30, s61
	v_lshl_add_u64 v[156:157], v[156:157], 0, s[86:87]
	s_mov_b32 m0, s26
	ds_read_b128 v[182:185], v205 offset:49152
	ds_read_b128 v[186:189], v205 offset:50176
	ds_read_b128 v[190:193], v205 offset:51200
	ds_read_b128 v[194:197], v205 offset:52224
	ds_read_b128 v[206:209], v205 offset:53248
	ds_read_b128 v[210:213], v205 offset:54272
	ds_read_b128 v[214:217], v205 offset:55296
	ds_read_b128 v[218:221], v205 offset:56320
	global_load_lds_dwordx4 v[156:157], off
	s_add_i32 m0, s26, 0x2000
	s_add_u32 s26, s44, 0x80080
	v_lshl_add_u64 v[156:157], v[160:161], 0, s[86:87]
	s_addc_u32 s27, s45, 0
	s_add_i32 s30, s31, s61
	global_load_lds_dwordx4 v[156:157], off
	v_lshl_add_u64 v[156:157], s[26:27], 0, v[166:167]
	s_mov_b32 m0, s30
	s_nop 0
	global_load_lds_dwordx4 v[156:157], off
	v_lshl_add_u64 v[156:157], s[26:27], 0, v[0:1]
	s_add_i32 m0, s30, 0x2000
	s_nop 0
	global_load_lds_dwordx4 v[156:157], off
	v_lshl_add_u64 v[156:157], v[162:163], 0, s[86:87]
	s_mov_b32 m0, s75
	s_nop 0
	global_load_lds_dwordx4 v[156:157], off
	v_lshl_add_u64 v[156:157], v[222:223], 0, s[86:87]
	s_mov_b32 m0, s76
	s_nop 0
	global_load_lds_dwordx4 v[156:157], off
	s_waitcnt vmcnt(8)
	s_waitcnt lgkmcnt(0)
	s_barrier
	s_setprio 1
	s_waitcnt lgkmcnt(0)
	v_mfma_f32_16x16x32_bf16 v[60:63], v[132:135], v[182:185], v[60:63]
	v_mfma_f32_16x16x32_bf16 v[60:63], v[136:139], v[186:189], v[60:63]
	v_mfma_f32_16x16x32_bf16 v[68:71], v[140:143], v[182:185], v[68:71]
	v_mfma_f32_16x16x32_bf16 v[68:71], v[144:147], v[186:189], v[68:71]
	v_mfma_f32_16x16x32_bf16 v[40:43], v[132:135], v[190:193], v[40:43]
	v_mfma_f32_16x16x32_bf16 v[40:43], v[136:139], v[194:197], v[40:43]
	v_mfma_f32_16x16x32_bf16 v[64:67], v[140:143], v[190:193], v[64:67]
	v_mfma_f32_16x16x32_bf16 v[64:67], v[144:147], v[194:197], v[64:67]
	v_mfma_f32_16x16x32_bf16 v[24:27], v[132:135], v[206:209], v[24:27]
	v_mfma_f32_16x16x32_bf16 v[24:27], v[136:139], v[210:213], v[24:27]
	v_mfma_f32_16x16x32_bf16 v[56:59], v[140:143], v[206:209], v[56:59]
	v_mfma_f32_16x16x32_bf16 v[56:59], v[144:147], v[210:213], v[56:59]
	v_mfma_f32_16x16x32_bf16 v[12:15], v[132:135], v[214:217], v[12:15]
	v_mfma_f32_16x16x32_bf16 v[12:15], v[136:139], v[218:221], v[12:15]
	v_mfma_f32_16x16x32_bf16 v[48:51], v[140:143], v[214:217], v[48:51]
	v_mfma_f32_16x16x32_bf16 v[48:51], v[144:147], v[218:221], v[48:51]
	s_setprio 0
	s_setprio 1
	v_mfma_f32_16x16x32_bf16 v[104:107], v[148:151], v[182:185], v[104:107]
	v_mfma_f32_16x16x32_bf16 v[104:107], v[152:155], v[186:189], v[104:107]
	v_mfma_f32_16x16x32_bf16 v[20:23], v[174:177], v[182:185], v[20:23]
	v_mfma_f32_16x16x32_bf16 v[20:23], v[178:181], v[186:189], v[20:23]
	v_mfma_f32_16x16x32_bf16 v[92:95], v[148:151], v[190:193], v[92:95]
	v_mfma_f32_16x16x32_bf16 v[92:95], v[152:155], v[194:197], v[92:95]
	v_mfma_f32_16x16x32_bf16 v[16:19], v[174:177], v[190:193], v[16:19]
	v_mfma_f32_16x16x32_bf16 v[16:19], v[178:181], v[194:197], v[16:19]
	v_mfma_f32_16x16x32_bf16 v[76:79], v[148:151], v[206:209], v[76:79]
	v_mfma_f32_16x16x32_bf16 v[76:79], v[152:155], v[210:213], v[76:79]
	v_mfma_f32_16x16x32_bf16 v[8:11], v[174:177], v[206:209], v[8:11]
	v_mfma_f32_16x16x32_bf16 v[8:11], v[178:181], v[210:213], v[8:11]
	v_mfma_f32_16x16x32_bf16 v[52:55], v[148:151], v[214:217], v[52:55]
	v_mfma_f32_16x16x32_bf16 v[52:55], v[152:155], v[218:221], v[52:55]
	v_mfma_f32_16x16x32_bf16 v[4:7], v[174:177], v[214:217], v[4:7]
	v_mfma_f32_16x16x32_bf16 v[4:7], v[178:181], v[218:221], v[4:7]
	s_setprio 0
	s_barrier
	s_add_i32 s25, s25, 2
	s_add_u32 s6, s6, 0x100
	s_addc_u32 s7, s7, 0
	s_add_u32 s19, s19, 0x100
	s_addc_u32 s24, s24, 0
	s_cmp_gt_u32 s25, 29
	s_cbranch_scc1 .Lpeel_exit_828
.LBB0_828:
	s_add_u32 s26, s6, 0xfff80080
	s_addc_u32 s27, s7, -1
	s_add_i32 s30, 0, 0x10000
	s_cmp_eq_u32 s25, 28
	s_cselect_b32 s59, s16, s27
	s_cselect_b32 s58, s17, s26
	v_add_u32_e32 v2, s30, v204
	s_cselect_b32 s45, s15, s24
	s_cselect_b32 s44, s18, s19
	s_add_i32 s31, 0, 0x14000
	ds_read_b128 v[132:135], v2
	ds_read_b128 v[136:139], v2 offset:1024
	ds_read_b128 v[140:143], v2 offset:2048
	ds_read_b128 v[144:147], v2 offset:3072
	v_add_u32_e32 v2, s31, v204
	ds_read_b128 v[148:151], v2
	ds_read_b128 v[152:155], v2 offset:1024
	ds_read_b128 v[174:177], v2 offset:2048
	ds_read_b128 v[178:181], v2 offset:3072
	v_lshl_add_u64 v[156:157], s[6:7], 0, v[170:171]
	s_add_i32 m0, s62, 0xc000
	ds_read_b128 v[182:185], v205
	ds_read_b128 v[186:189], v205 offset:1024
	ds_read_b128 v[190:193], v205 offset:2048
	ds_read_b128 v[194:197], v205 offset:3072
	ds_read_b128 v[206:209], v205 offset:4096
	ds_read_b128 v[210:213], v205 offset:5120
	ds_read_b128 v[214:217], v205 offset:6144
	ds_read_b128 v[218:221], v205 offset:7168
	global_load_lds_dwordx4 v[156:157], off
	v_lshl_add_u64 v[156:157], s[6:7], 0, v[172:173]
	s_add_i32 m0, s62, 0xe000
	s_nop 0
	global_load_lds_dwordx4 v[156:157], off
	s_waitcnt vmcnt(8)
	s_waitcnt lgkmcnt(0)
	s_barrier
; #define PG8_STAGE(bufoff, gbase, voff) do { _Pragma("unroll") for (int _i = 0; _i < 2; ++_i) \
;         __builtin_amdgcn_global_load_lds((const unsigned*)((const char*)(gbase) + (voff)[_i]), (LAS unsigned*)(lds + (bufoff) + ldsw + _i * 8192), 16, 0, 0); } while (0)
; #define PG8_LDA(dst, b, h) do { _Pragma("unroll") for (int m = 0; m < 4; ++m) _Pragma("unroll") for (int k = 0; k < 2; ++k) dst[m][k] = *(const LAS bf16x8*)(lds + PG8_SA(b, h) + aoff + m * 2048 + k * 1024); } while (0)
; #define PG8_MMA(ai, bj, At, Bt) do { __builtin_amdgcn_s_setprio(1); _Pragma("unroll") for (int m = 0; m < 4; ++m) _Pragma("unroll") for (int n = 0; n < 2; ++n) _Pragma("unroll") for (int k = 0; k < 2; ++k) \
;         acc[ai][bj][m][n] = __builtin_amdgcn_mfma_f32_16x16x32_bf16(Bt[n][k], At[m][k], acc[ai][bj][m][n], 0, 0, 0); __builtin_amdgcn_s_setprio(0); } while (0)
; #define PG8_WAIT_V(n) asm volatile("s_waitcnt vmcnt(" #n ")" ::: "memory")
; #define PG8_WAIT_L(n) asm volatile("s_waitcnt lgkmcnt(" #n ")" ::: "memory")
; #define PG8_BAR __builtin_amdgcn_s_barrier()
; #define PG8_SCHED __builtin_amdgcn_sched_barrier(0)
; template <class Epi, class Sched, bool ALIGN_EPI = true>
; __device__ __forceinline__ void gemm_phase(LAS unsigned char* lds, const Gemm g, const Sched& S, const Epi& E) {
;     ...
;             PG8_WAIT_V(8); PG8_WAIT_L(0); PG8_BAR; PG8_MMA(0, 0, At, B0); PG8_MMA(0, 1, At, B1); PG8_BAR; PG8_SCHED;
;             PG8_LDA(At, 0, 1); PG8_STAGE(PG8_SB(0, 0), b2, voffB); PG8_STAGE(PG8_SB(0, 1), b2 + hB, voffB); PG8_STAGE(PG8_SA(0, 0), a2, voffA);
;             PG8_WAIT_V(8); PG8_WAIT_L(0); PG8_BAR; PG8_MMA(1, 0, At, B0); PG8_MMA(1, 1, At, B1); PG8_BAR; PG8_SCHED;
	s_setprio 1
	s_waitcnt lgkmcnt(0)
	v_mfma_f32_16x16x32_bf16 v[116:119], v[132:135], v[182:185], v[116:119]
	v_mfma_f32_16x16x32_bf16 v[116:119], v[136:139], v[186:189], v[116:119]
	v_mfma_f32_16x16x32_bf16 v[100:103], v[140:143], v[182:185], v[100:103]
	v_mfma_f32_16x16x32_bf16 v[100:103], v[144:147], v[186:189], v[100:103]
	v_mfma_f32_16x16x32_bf16 v[108:111], v[132:135], v[190:193], v[108:111]
	v_mfma_f32_16x16x32_bf16 v[108:111], v[136:139], v[194:197], v[108:111]
	v_mfma_f32_16x16x32_bf16 v[96:99], v[140:143], v[190:193], v[96:99]
	v_mfma_f32_16x16x32_bf16 v[96:99], v[144:147], v[194:197], v[96:99]
	v_mfma_f32_16x16x32_bf16 v[88:91], v[132:135], v[206:209], v[88:91]
	v_mfma_f32_16x16x32_bf16 v[88:91], v[136:139], v[210:213], v[88:91]
	v_mfma_f32_16x16x32_bf16 v[84:87], v[140:143], v[206:209], v[84:87]
	v_mfma_f32_16x16x32_bf16 v[84:87], v[144:147], v[210:213], v[84:87]
	v_mfma_f32_16x16x32_bf16 v[72:75], v[132:135], v[214:217], v[72:75]
	v_mfma_f32_16x16x32_bf16 v[72:75], v[136:139], v[218:221], v[72:75]
	v_mfma_f32_16x16x32_bf16 v[80:83], v[140:143], v[214:217], v[80:83]
	v_mfma_f32_16x16x32_bf16 v[80:83], v[144:147], v[218:221], v[80:83]
	s_setprio 0
	s_setprio 1
	v_mfma_f32_16x16x32_bf16 v[128:131], v[148:151], v[182:185], v[128:131]
	v_mfma_f32_16x16x32_bf16 v[128:131], v[152:155], v[186:189], v[128:131]
	v_mfma_f32_16x16x32_bf16 v[44:47], v[174:177], v[182:185], v[44:47]
	v_mfma_f32_16x16x32_bf16 v[44:47], v[178:181], v[186:189], v[44:47]
	v_mfma_f32_16x16x32_bf16 v[124:127], v[148:151], v[190:193], v[124:127]
	v_mfma_f32_16x16x32_bf16 v[124:127], v[152:155], v[194:197], v[124:127]
	v_mfma_f32_16x16x32_bf16 v[36:39], v[174:177], v[190:193], v[36:39]
	v_mfma_f32_16x16x32_bf16 v[36:39], v[178:181], v[194:197], v[36:39]
	v_mfma_f32_16x16x32_bf16 v[120:123], v[148:151], v[206:209], v[120:123]
	v_mfma_f32_16x16x32_bf16 v[120:123], v[152:155], v[210:213], v[120:123]
	v_mfma_f32_16x16x32_bf16 v[32:35], v[174:177], v[206:209], v[32:35]
	v_mfma_f32_16x16x32_bf16 v[32:35], v[178:181], v[210:213], v[32:35]
	v_mfma_f32_16x16x32_bf16 v[112:115], v[148:151], v[214:217], v[112:115]
	v_mfma_f32_16x16x32_bf16 v[112:115], v[152:155], v[218:221], v[112:115]
	v_mfma_f32_16x16x32_bf16 v[28:31], v[174:177], v[214:217], v[28:31]
	v_mfma_f32_16x16x32_bf16 v[28:31], v[178:181], v[218:221], v[28:31]
	s_setprio 0
	s_barrier
	s_add_i32 s26, s30, s61
	v_lshl_add_u64 v[156:157], s[44:45], 0, v[166:167]
	s_mov_b32 m0, s26
	ds_read_b128 v[182:185], v205 offset:16384
	ds_read_b128 v[186:189], v205 offset:17408
	ds_read_b128 v[190:193], v205 offset:18432
	ds_read_b128 v[194:197], v205 offset:19456
	ds_read_b128 v[206:209], v205 offset:20480
	ds_read_b128 v[210:213], v205 offset:21504
	ds_read_b128 v[214:217], v205 offset:22528
	ds_read_b128 v[218:221], v205 offset:23552
	global_load_lds_dwordx4 v[156:157], off
	s_add_i32 m0, s26, 0x2000
	s_add_u32 s26, s44, 0x80000
	v_lshl_add_u64 v[160:161], s[44:45], 0, v[0:1]
	s_addc_u32 s27, s45, 0
	s_add_i32 s30, s31, s61
	global_load_lds_dwordx4 v[160:161], off
	v_lshl_add_u64 v[162:163], s[26:27], 0, v[166:167]
	s_mov_b32 m0, s30
	v_lshl_add_u64 v[222:223], s[58:59], 0, v[164:165]
	global_load_lds_dwordx4 v[162:163], off
	v_lshl_add_u64 v[162:163], s[26:27], 0, v[0:1]
	s_add_i32 m0, s30, 0x2000
	s_nop 0
	global_load_lds_dwordx4 v[162:163], off
	v_lshl_add_u64 v[162:163], s[58:59], 0, v[168:169]
	s_mov_b32 m0, s62
	s_nop 0
	global_load_lds_dwordx4 v[162:163], off
	s_mov_b32 m0, s63
	s_nop 0
	global_load_lds_dwordx4 v[222:223], off
	s_waitcnt vmcnt(8)
	s_waitcnt lgkmcnt(0)
	s_barrier
	s_setprio 1
	s_waitcnt lgkmcnt(0)
	v_mfma_f32_16x16x32_bf16 v[60:63], v[132:135], v[182:185], v[60:63]
	v_mfma_f32_16x16x32_bf16 v[60:63], v[136:139], v[186:189], v[60:63]
	v_mfma_f32_16x16x32_bf16 v[68:71], v[140:143], v[182:185], v[68:71]
	v_mfma_f32_16x16x32_bf16 v[68:71], v[144:147], v[186:189], v[68:71]
	v_mfma_f32_16x16x32_bf16 v[40:43], v[132:135], v[190:193], v[40:43]
	v_mfma_f32_16x16x32_bf16 v[40:43], v[136:139], v[194:197], v[40:43]
	v_mfma_f32_16x16x32_bf16 v[64:67], v[140:143], v[190:193], v[64:67]
	v_mfma_f32_16x16x32_bf16 v[64:67], v[144:147], v[194:197], v[64:67]
	v_mfma_f32_16x16x32_bf16 v[24:27], v[132:135], v[206:209], v[24:27]
	v_mfma_f32_16x16x32_bf16 v[24:27], v[136:139], v[210:213], v[24:27]
	v_mfma_f32_16x16x32_bf16 v[56:59], v[140:143], v[206:209], v[56:59]
	v_mfma_f32_16x16x32_bf16 v[56:59], v[144:147], v[210:213], v[56:59]
	v_mfma_f32_16x16x32_bf16 v[12:15], v[132:135], v[214:217], v[12:15]
	v_mfma_f32_16x16x32_bf16 v[12:15], v[136:139], v[218:221], v[12:15]
	v_mfma_f32_16x16x32_bf16 v[48:51], v[140:143], v[214:217], v[48:51]
	v_mfma_f32_16x16x32_bf16 v[48:51], v[144:147], v[218:221], v[48:51]
	s_setprio 0
	s_setprio 1
	v_mfma_f32_16x16x32_bf16 v[104:107], v[148:151], v[182:185], v[104:107]
	v_mfma_f32_16x16x32_bf16 v[104:107], v[152:155], v[186:189], v[104:107]
	v_mfma_f32_16x16x32_bf16 v[20:23], v[174:177], v[182:185], v[20:23]
	v_mfma_f32_16x16x32_bf16 v[20:23], v[178:181], v[186:189], v[20:23]
	v_mfma_f32_16x16x32_bf16 v[92:95], v[148:151], v[190:193], v[92:95]
	v_mfma_f32_16x16x32_bf16 v[92:95], v[152:155], v[194:197], v[92:95]
	v_mfma_f32_16x16x32_bf16 v[16:19], v[174:177], v[190:193], v[16:19]
	v_mfma_f32_16x16x32_bf16 v[16:19], v[178:181], v[194:197], v[16:19]
	v_mfma_f32_16x16x32_bf16 v[76:79], v[148:151], v[206:209], v[76:79]
	v_mfma_f32_16x16x32_bf16 v[76:79], v[152:155], v[210:213], v[76:79]
	v_mfma_f32_16x16x32_bf16 v[8:11], v[174:177], v[206:209], v[8:11]
	v_mfma_f32_16x16x32_bf16 v[8:11], v[178:181], v[210:213], v[8:11]
	v_mfma_f32_16x16x32_bf16 v[52:55], v[148:151], v[214:217], v[52:55]
	v_mfma_f32_16x16x32_bf16 v[52:55], v[152:155], v[218:221], v[52:55]
	v_mfma_f32_16x16x32_bf16 v[4:7], v[174:177], v[214:217], v[4:7]
	v_mfma_f32_16x16x32_bf16 v[4:7], v[178:181], v[218:221], v[4:7]
	s_setprio 0
	s_barrier
; #define PG8_STAGE(bufoff, gbase, voff) do { _Pragma("unroll") for (int _i = 0; _i < 2; ++_i) \
;         __builtin_amdgcn_global_load_lds((const unsigned*)((const char*)(gbase) + (voff)[_i]), (LAS unsigned*)(lds + (bufoff) + ldsw + _i * 8192), 16, 0, 0); } while (0)
; #define PG8_LDA(dst, b, h) do { _Pragma("unroll") for (int m = 0; m < 4; ++m) _Pragma("unroll") for (int k = 0; k < 2; ++k) dst[m][k] = *(const LAS bf16x8*)(lds + PG8_SA(b, h) + aoff + m * 2048 + k * 1024); } while (0)
; #define PG8_LDB(dst, b, h) do { _Pragma("unroll") for (int n = 0; n < 2; ++n) _Pragma("unroll") for (int k = 0; k < 2; ++k) dst[n][k] = *(const LAS bf16x8*)(lds + PG8_SB(b, h) + boff + n * 2048 + k * 1024); } while (0)
; #define PG8_MMA(ai, bj, At, Bt) do { __builtin_amdgcn_s_setprio(1); _Pragma("unroll") for (int m = 0; m < 4; ++m) _Pragma("unroll") for (int n = 0; n < 2; ++n) _Pragma("unroll") for (int k = 0; k < 2; ++k) \
;         acc[ai][bj][m][n] = __builtin_amdgcn_mfma_f32_16x16x32_bf16(Bt[n][k], At[m][k], acc[ai][bj][m][n], 0, 0, 0); __builtin_amdgcn_s_setprio(0); } while (0)
; #define PG8_WAIT_V(n) asm volatile("s_waitcnt vmcnt(" #n ")" ::: "memory")
; #define PG8_WAIT_L(n) asm volatile("s_waitcnt lgkmcnt(" #n ")" ::: "memory")
; #define PG8_BAR __builtin_amdgcn_s_barrier()
; #define PG8_SCHED __builtin_amdgcn_sched_barrier(0)
; template <class Epi, class Sched, bool ALIGN_EPI = true>
; __device__ __forceinline__ void gemm_phase(LAS unsigned char* lds, const Gemm g, const Sched& S, const Epi& E) {
;     ...
;             PG8_LDB(B0, 1, 0); PG8_LDB(B1, 1, 1); PG8_SCHED; PG8_LDA(At, 1, 0); PG8_STAGE(PG8_SA(0, 1), a2 + hA, voffA);
;             PG8_WAIT_V(8); PG8_WAIT_L(0); PG8_BAR; PG8_MMA(0, 0, At, B0); PG8_MMA(0, 1, At, B1); PG8_BAR; PG8_SCHED;
	s_add_i32 s30, 0, 0x18000
	v_add_u32_e32 v2, s30, v204
	s_add_i32 s31, 0, 0x1c000
	ds_read_b128 v[132:135], v2
	ds_read_b128 v[136:139], v2 offset:1024
	ds_read_b128 v[140:143], v2 offset:2048
	ds_read_b128 v[144:147], v2 offset:3072
	v_add_u32_e32 v2, s31, v204
	ds_read_b128 v[148:151], v2
	ds_read_b128 v[152:155], v2 offset:1024
	ds_read_b128 v[174:177], v2 offset:2048
	ds_read_b128 v[178:181], v2 offset:3072
	s_add_u32 s26, s58, 0x80000
	s_addc_u32 s27, s59, 0
	s_mov_b32 m0, s64
	v_lshl_add_u64 v[224:225], s[26:27], 0, v[168:169]
	ds_read_b128 v[182:185], v205 offset:32768
	ds_read_b128 v[186:189], v205 offset:33792
	ds_read_b128 v[190:193], v205 offset:34816
	ds_read_b128 v[194:197], v205 offset:35840
	ds_read_b128 v[206:209], v205 offset:36864
	ds_read_b128 v[210:213], v205 offset:37888
	ds_read_b128 v[214:217], v205 offset:38912
	ds_read_b128 v[218:221], v205 offset:39936
	global_load_lds_dwordx4 v[224:225], off
	v_lshl_add_u64 v[224:225], s[26:27], 0, v[164:165]
	s_mov_b32 m0, s65
	s_nop 0
	global_load_lds_dwordx4 v[224:225], off
	s_waitcnt vmcnt(8)
	s_waitcnt lgkmcnt(0)
	s_barrier
	s_setprio 1
	s_waitcnt lgkmcnt(0)
	v_mfma_f32_16x16x32_bf16 v[116:119], v[132:135], v[182:185], v[116:119]
	v_mfma_f32_16x16x32_bf16 v[116:119], v[136:139], v[186:189], v[116:119]
	v_mfma_f32_16x16x32_bf16 v[100:103], v[140:143], v[182:185], v[100:103]
	v_mfma_f32_16x16x32_bf16 v[100:103], v[144:147], v[186:189], v[100:103]
	v_mfma_f32_16x16x32_bf16 v[108:111], v[132:135], v[190:193], v[108:111]
	v_mfma_f32_16x16x32_bf16 v[108:111], v[136:139], v[194:197], v[108:111]
	v_mfma_f32_16x16x32_bf16 v[96:99], v[140:143], v[190:193], v[96:99]
	v_mfma_f32_16x16x32_bf16 v[96:99], v[144:147], v[194:197], v[96:99]
	v_mfma_f32_16x16x32_bf16 v[88:91], v[132:135], v[206:209], v[88:91]
	v_mfma_f32_16x16x32_bf16 v[88:91], v[136:139], v[210:213], v[88:91]
	v_mfma_f32_16x16x32_bf16 v[84:87], v[140:143], v[206:209], v[84:87]
	v_mfma_f32_16x16x32_bf16 v[84:87], v[144:147], v[210:213], v[84:87]
	v_mfma_f32_16x16x32_bf16 v[72:75], v[132:135], v[214:217], v[72:75]
	v_mfma_f32_16x16x32_bf16 v[72:75], v[136:139], v[218:221], v[72:75]
	v_mfma_f32_16x16x32_bf16 v[80:83], v[140:143], v[214:217], v[80:83]
	v_mfma_f32_16x16x32_bf16 v[80:83], v[144:147], v[218:221], v[80:83]
	s_setprio 0
	s_setprio 1
	v_mfma_f32_16x16x32_bf16 v[128:131], v[148:151], v[182:185], v[128:131]
	v_mfma_f32_16x16x32_bf16 v[128:131], v[152:155], v[186:189], v[128:131]
	v_mfma_f32_16x16x32_bf16 v[44:47], v[174:177], v[182:185], v[44:47]
	v_mfma_f32_16x16x32_bf16 v[44:47], v[178:181], v[186:189], v[44:47]
	v_mfma_f32_16x16x32_bf16 v[124:127], v[148:151], v[190:193], v[124:127]
	v_mfma_f32_16x16x32_bf16 v[124:127], v[152:155], v[194:197], v[124:127]
	v_mfma_f32_16x16x32_bf16 v[36:39], v[174:177], v[190:193], v[36:39]
	v_mfma_f32_16x16x32_bf16 v[36:39], v[178:181], v[194:197], v[36:39]
	v_mfma_f32_16x16x32_bf16 v[120:123], v[148:151], v[206:209], v[120:123]
	v_mfma_f32_16x16x32_bf16 v[120:123], v[152:155], v[210:213], v[120:123]
	v_mfma_f32_16x16x32_bf16 v[32:35], v[174:177], v[206:209], v[32:35]
	v_mfma_f32_16x16x32_bf16 v[32:35], v[178:181], v[210:213], v[32:35]
	v_mfma_f32_16x16x32_bf16 v[112:115], v[148:151], v[214:217], v[112:115]
	v_mfma_f32_16x16x32_bf16 v[112:115], v[152:155], v[218:221], v[112:115]
	v_mfma_f32_16x16x32_bf16 v[28:31], v[174:177], v[214:217], v[28:31]
	v_mfma_f32_16x16x32_bf16 v[28:31], v[178:181], v[218:221], v[28:31]
	s_setprio 0
	s_barrier
; #define PG8_STAGE(bufoff, gbase, voff) do { _Pragma("unroll") for (int _i = 0; _i < 2; ++_i) \
;         __builtin_amdgcn_global_load_lds((const unsigned*)((const char*)(gbase) + (voff)[_i]), (LAS unsigned*)(lds + (bufoff) + ldsw + _i * 8192), 16, 0, 0); } while (0)
; #define PG8_LDA(dst, b, h) do { _Pragma("unroll") for (int m = 0; m < 4; ++m) _Pragma("unroll") for (int k = 0; k < 2; ++k) dst[m][k] = *(const LAS bf16x8*)(lds + PG8_SA(b, h) + aoff + m * 2048 + k * 1024); } while (0)
; #define PG8_MMA(ai, bj, At, Bt) do { __builtin_amdgcn_s_setprio(1); _Pragma("unroll") for (int m = 0; m < 4; ++m) _Pragma("unroll") for (int n = 0; n < 2; ++n) _Pragma("unroll") for (int k = 0; k < 2; ++k) \
;         acc[ai][bj][m][n] = __builtin_amdgcn_mfma_f32_16x16x32_bf16(Bt[n][k], At[m][k], acc[ai][bj][m][n], 0, 0, 0); __builtin_amdgcn_s_setprio(0); } while (0)
; #define PG8_WAIT_V(n) asm volatile("s_waitcnt vmcnt(" #n ")" ::: "memory")
; #define PG8_WAIT_L(n) asm volatile("s_waitcnt lgkmcnt(" #n ")" ::: "memory")
; #define PG8_BAR __builtin_amdgcn_s_barrier()
; #define PG8_SCHED __builtin_amdgcn_sched_barrier(0)
; template <class Epi, class Sched, bool ALIGN_EPI = true>
; __device__ __forceinline__ void gemm_phase(LAS unsigned char* lds, const Gemm g, const Sched& S, const Epi& E) {
;     ...
;             PG8_LDA(At, 1, 1); PG8_STAGE(PG8_SB(1, 0), b3, voffB); PG8_STAGE(PG8_SB(1, 1), b3 + hB, voffB); PG8_STAGE(PG8_SA(1, 0), a3, voffA);
;             PG8_WAIT_V(8); PG8_WAIT_L(0); PG8_BAR; PG8_MMA(1, 0, At, B0); PG8_MMA(1, 1, At, B1); PG8_BAR; PG8_SCHED;
	s_add_i32 s26, s30, s61
	v_lshl_add_u64 v[156:157], v[156:157], 0, s[86:87]
	s_mov_b32 m0, s26
	ds_read_b128 v[182:185], v205 offset:49152
	ds_read_b128 v[186:189], v205 offset:50176
	ds_read_b128 v[190:193], v205 offset:51200
	ds_read_b128 v[194:197], v205 offset:52224
	ds_read_b128 v[206:209], v205 offset:53248
	ds_read_b128 v[210:213], v205 offset:54272
	ds_read_b128 v[214:217], v205 offset:55296
	ds_read_b128 v[218:221], v205 offset:56320
	global_load_lds_dwordx4 v[156:157], off
	s_add_i32 m0, s26, 0x2000
	s_add_u32 s26, s44, 0x80080
	v_lshl_add_u64 v[156:157], v[160:161], 0, s[86:87]
	s_addc_u32 s27, s45, 0
	s_add_i32 s30, s31, s61
	global_load_lds_dwordx4 v[156:157], off
	v_lshl_add_u64 v[156:157], s[26:27], 0, v[166:167]
	s_mov_b32 m0, s30
	s_nop 0
	global_load_lds_dwordx4 v[156:157], off
	v_lshl_add_u64 v[156:157], s[26:27], 0, v[0:1]
	s_add_i32 m0, s30, 0x2000
	s_nop 0
	global_load_lds_dwordx4 v[156:157], off
	v_lshl_add_u64 v[156:157], v[162:163], 0, s[86:87]
	s_mov_b32 m0, s75
	s_nop 0
	global_load_lds_dwordx4 v[156:157], off
	v_lshl_add_u64 v[156:157], v[222:223], 0, s[86:87]
	s_mov_b32 m0, s76
	s_nop 0
	global_load_lds_dwordx4 v[156:157], off
	s_waitcnt vmcnt(8)
	s_waitcnt lgkmcnt(0)
	s_barrier
	s_setprio 1
	s_waitcnt lgkmcnt(0)
	v_mfma_f32_16x16x32_bf16 v[60:63], v[132:135], v[182:185], v[60:63]
	v_mfma_f32_16x16x32_bf16 v[60:63], v[136:139], v[186:189], v[60:63]
	v_mfma_f32_16x16x32_bf16 v[68:71], v[140:143], v[182:185], v[68:71]
	v_mfma_f32_16x16x32_bf16 v[68:71], v[144:147], v[186:189], v[68:71]
	v_mfma_f32_16x16x32_bf16 v[40:43], v[132:135], v[190:193], v[40:43]
	v_mfma_f32_16x16x32_bf16 v[40:43], v[136:139], v[194:197], v[40:43]
	v_mfma_f32_16x16x32_bf16 v[64:67], v[140:143], v[190:193], v[64:67]
	v_mfma_f32_16x16x32_bf16 v[64:67], v[144:147], v[194:197], v[64:67]
	v_mfma_f32_16x16x32_bf16 v[24:27], v[132:135], v[206:209], v[24:27]
	v_mfma_f32_16x16x32_bf16 v[24:27], v[136:139], v[210:213], v[24:27]
	v_mfma_f32_16x16x32_bf16 v[56:59], v[140:143], v[206:209], v[56:59]
	v_mfma_f32_16x16x32_bf16 v[56:59], v[144:147], v[210:213], v[56:59]
	v_mfma_f32_16x16x32_bf16 v[12:15], v[132:135], v[214:217], v[12:15]
	v_mfma_f32_16x16x32_bf16 v[12:15], v[136:139], v[218:221], v[12:15]
	v_mfma_f32_16x16x32_bf16 v[48:51], v[140:143], v[214:217], v[48:51]
	v_mfma_f32_16x16x32_bf16 v[48:51], v[144:147], v[218:221], v[48:51]
	s_setprio 0
	s_setprio 1
	v_mfma_f32_16x16x32_bf16 v[104:107], v[148:151], v[182:185], v[104:107]
	v_mfma_f32_16x16x32_bf16 v[104:107], v[152:155], v[186:189], v[104:107]
	v_mfma_f32_16x16x32_bf16 v[20:23], v[174:177], v[182:185], v[20:23]
	v_mfma_f32_16x16x32_bf16 v[20:23], v[178:181], v[186:189], v[20:23]
	v_mfma_f32_16x16x32_bf16 v[92:95], v[148:151], v[190:193], v[92:95]
	v_mfma_f32_16x16x32_bf16 v[92:95], v[152:155], v[194:197], v[92:95]
	v_mfma_f32_16x16x32_bf16 v[16:19], v[174:177], v[190:193], v[16:19]
	v_mfma_f32_16x16x32_bf16 v[16:19], v[178:181], v[194:197], v[16:19]
	v_mfma_f32_16x16x32_bf16 v[76:79], v[148:151], v[206:209], v[76:79]
	v_mfma_f32_16x16x32_bf16 v[76:79], v[152:155], v[210:213], v[76:79]
	v_mfma_f32_16x16x32_bf16 v[8:11], v[174:177], v[206:209], v[8:11]
	v_mfma_f32_16x16x32_bf16 v[8:11], v[178:181], v[210:213], v[8:11]
	v_mfma_f32_16x16x32_bf16 v[52:55], v[148:151], v[214:217], v[52:55]
	v_mfma_f32_16x16x32_bf16 v[52:55], v[152:155], v[218:221], v[52:55]
	v_mfma_f32_16x16x32_bf16 v[4:7], v[174:177], v[214:217], v[4:7]
	v_mfma_f32_16x16x32_bf16 v[4:7], v[178:181], v[218:221], v[4:7]
	s_setprio 0
	s_barrier
	s_add_i32 s25, s25, 2
	s_add_u32 s6, s6, 0x100
	s_addc_u32 s7, s7, 0
	s_add_u32 s19, s19, 0x100
	s_addc_u32 s24, s24, 0
	s_cmp_gt_u32 s25, 29
	s_cbranch_scc0 .LBB0_828

; #define PG8_STAGE(bufoff, gbase, voff) do { _Pragma("unroll") for (int _i = 0; _i < 2; ++_i) \
;         __builtin_amdgcn_global_load_lds((const unsigned*)((const char*)(gbase) + (voff)[_i]), (LAS unsigned*)(lds + (bufoff) + ldsw + _i * 8192), 16, 0, 0); } while (0)
; #define PG8_LDA(dst, b, h) do { _Pragma("unroll") for (int m = 0; m < 4; ++m) _Pragma("unroll") for (int k = 0; k < 2; ++k) dst[m][k] = *(const LAS bf16x8*)(lds + PG8_SA(b, h) + aoff + m * 2048 + k * 1024); } while (0)
; #define PG8_LDB(dst, b, h) do { _Pragma("unroll") for (int n = 0; n < 2; ++n) _Pragma("unroll") for (int k = 0; k < 2; ++k) dst[n][k] = *(const LAS bf16x8*)(lds + PG8_SB(b, h) + boff + n * 2048 + k * 1024); } while (0)
; #define PG8_MMA(ai, bj, At, Bt) do { __builtin_amdgcn_s_setprio(1); _Pragma("unroll") for (int m = 0; m < 4; ++m) _Pragma("unroll") for (int n = 0; n < 2; ++n) _Pragma("unroll") for (int k = 0; k < 2; ++k) \
;         acc[ai][bj][m][n] = __builtin_amdgcn_mfma_f32_16x16x32_bf16(Bt[n][k], At[m][k], acc[ai][bj][m][n], 0, 0, 0); __builtin_amdgcn_s_setprio(0); } while (0)
; #define PG8_WAIT_V(n) asm volatile("s_waitcnt vmcnt(" #n ")" ::: "memory")
; #define PG8_WAIT_L(n) asm volatile("s_waitcnt lgkmcnt(" #n ")" ::: "memory")
; #define PG8_BAR __builtin_amdgcn_s_barrier()
; #define PG8_SCHED __builtin_amdgcn_sched_barrier(0)
; template <class Epi, class Sched, bool ALIGN_EPI = true>
; __device__ __forceinline__ void gemm_phase(LAS unsigned char* lds, const Gemm g, const Sched& S, const Epi& E) {
;     ...
;         for (int t = 0; t < nt; t += 2) {
;             const bool last = (t == nt - 2);
;             const char* a1 = cA + (size_t)(t + 1) * kstep;
;             const char* a2 = last ? nA : cA + (size_t)(t + 2) * kstep; const char* b2 = last ? nB : cB + (size_t)(t + 2) * kstep;
;             const char* a3 = a2 + kstep; const char* b3 = b2 + kstep;
;             PG8_LDB(B0, 0, 0); PG8_LDB(B1, 0, 1); PG8_SCHED; PG8_LDA(At, 0, 0); PG8_STAGE(PG8_SA(1, 1), a1 + hA, voffA);
;             PG8_WAIT_V(8); PG8_WAIT_L(0); PG8_BAR; PG8_MMA(0, 0, At, B0); PG8_MMA(0, 1, At, B1); PG8_BAR; PG8_SCHED;
;             PG8_LDA(At, 0, 1); PG8_STAGE(PG8_SB(0, 0), b2, voffB); PG8_STAGE(PG8_SB(0, 1), b2 + hB, voffB); PG8_STAGE(PG8_SA(0, 0), a2, voffA);
.LBB0_1110:
	s_add_u32 s16, s10, 0x100
	s_addc_u32 s17, s11, 0
	s_add_u32 s10, s10, 0x160080
	s_addc_u32 s11, s11, 0
	v_lshl_add_u64 v[132:133], s[10:11], 0, v[168:169]
	v_lshl_add_u64 v[134:135], s[10:11], 0, v[170:171]
	s_mov_b32 s18, -2
	s_mov_b64 s[10:11], 0
	s_add_u32 vcc_lo, s10, 0x100
	s_addc_u32 vcc_hi, s11, 0
	s_add_u32 s19, s16, s10
	s_addc_u32 s24, s17, s11
	s_add_i32 s25, 0, 0x10000
	s_cmpk_eq_i32 s18, 0x54
	s_cselect_b32 s65, s61, s24
	s_cselect_b32 s24, 0, vcc_lo
	s_cselect_b32 s64, s60, s19
	s_cselect_b32 s19, 0, vcc_hi
	s_add_u32 s62, s2, s24
	v_add_u32_e32 v160, s25, v188
	s_addc_u32 s63, s3, s19
	s_add_i32 s19, 0, 0x14000
	ds_read_b128 v[136:139], v160
	ds_read_b128 v[140:143], v160 offset:1024
	ds_read_b128 v[144:147], v160 offset:2048
	ds_read_b128 v[172:175], v160 offset:3072
	v_add_u32_e32 v160, s19, v188
	ds_read_b128 v[176:179], v160
	ds_read_b128 v[180:183], v160 offset:1024
	ds_read_b128 v[184:187], v160 offset:2048
	ds_read_b128 v[208:211], v160 offset:3072
	v_lshl_add_u64 v[160:161], v[132:133], 0, s[10:11]
	s_add_i32 m0, s67, 0xc000
	ds_read_b128 v[212:215], v197
	ds_read_b128 v[216:219], v197 offset:1024
	ds_read_b128 v[220:223], v197 offset:2048
	ds_read_b128 v[224:227], v197 offset:3072
	ds_read_b128 v[228:231], v197 offset:4096
	ds_read_b128 v[232:235], v197 offset:5120
	ds_read_b128 v[236:239], v197 offset:6144
	ds_read_b128 v[240:243], v197 offset:7168
	global_load_lds_dwordx4 v[160:161], off
	v_lshl_add_u64 v[160:161], v[134:135], 0, s[10:11]
	s_add_i32 m0, s67, 0xe000
	s_nop 0
	global_load_lds_dwordx4 v[160:161], off
	s_waitcnt vmcnt(8)
	s_waitcnt lgkmcnt(0)
	s_barrier
	s_setprio 1
	s_waitcnt lgkmcnt(0)
	v_mfma_f32_16x16x32_bf16 v[16:19], v[136:139], v[212:215], 0
	v_mfma_f32_16x16x32_bf16 v[16:19], v[140:143], v[216:219], v[16:19]
	v_mfma_f32_16x16x32_bf16 v[12:15], v[144:147], v[212:215], 0
	v_mfma_f32_16x16x32_bf16 v[12:15], v[172:175], v[216:219], v[12:15]
	v_mfma_f32_16x16x32_bf16 v[56:59], v[136:139], v[220:223], 0
	v_mfma_f32_16x16x32_bf16 v[56:59], v[140:143], v[224:227], v[56:59]
	v_mfma_f32_16x16x32_bf16 v[52:55], v[144:147], v[220:223], 0
	v_mfma_f32_16x16x32_bf16 v[52:55], v[172:175], v[224:227], v[52:55]
	v_mfma_f32_16x16x32_bf16 v[88:91], v[136:139], v[228:231], 0
	v_mfma_f32_16x16x32_bf16 v[88:91], v[140:143], v[232:235], v[88:91]
	v_mfma_f32_16x16x32_bf16 v[76:79], v[144:147], v[228:231], 0
	v_mfma_f32_16x16x32_bf16 v[76:79], v[172:175], v[232:235], v[76:79]
	v_mfma_f32_16x16x32_bf16 v[112:115], v[136:139], v[236:239], 0
	v_mfma_f32_16x16x32_bf16 v[112:115], v[140:143], v[240:243], v[112:115]
	v_mfma_f32_16x16x32_bf16 v[108:111], v[144:147], v[236:239], 0
	v_mfma_f32_16x16x32_bf16 v[108:111], v[172:175], v[240:243], v[108:111]
	s_setprio 0
	s_setprio 1
	v_mfma_f32_16x16x32_bf16 v[8:11], v[176:179], v[212:215], 0
	v_mfma_f32_16x16x32_bf16 v[8:11], v[180:183], v[216:219], v[8:11]
	v_mfma_f32_16x16x32_bf16 v[4:7], v[184:187], v[212:215], 0
	v_mfma_f32_16x16x32_bf16 v[4:7], v[208:211], v[216:219], v[4:7]
	v_mfma_f32_16x16x32_bf16 v[40:43], v[176:179], v[220:223], 0
	v_mfma_f32_16x16x32_bf16 v[40:43], v[180:183], v[224:227], v[40:43]
	v_mfma_f32_16x16x32_bf16 v[36:39], v[184:187], v[220:223], 0
	v_mfma_f32_16x16x32_bf16 v[36:39], v[208:211], v[224:227], v[36:39]
	v_mfma_f32_16x16x32_bf16 v[64:67], v[176:179], v[228:231], 0
	v_mfma_f32_16x16x32_bf16 v[64:67], v[180:183], v[232:235], v[64:67]
	v_mfma_f32_16x16x32_bf16 v[60:63], v[184:187], v[228:231], 0
	v_mfma_f32_16x16x32_bf16 v[60:63], v[208:211], v[232:235], v[60:63]
	v_mfma_f32_16x16x32_bf16 v[96:99], v[176:179], v[236:239], 0
	v_mfma_f32_16x16x32_bf16 v[96:99], v[180:183], v[240:243], v[96:99]
	v_mfma_f32_16x16x32_bf16 v[92:95], v[184:187], v[236:239], 0
	v_mfma_f32_16x16x32_bf16 v[92:95], v[208:211], v[240:243], v[92:95]
	s_setprio 0
	s_barrier
	s_add_i32 s10, s25, s66
	v_lshl_add_u64 v[160:161], s[62:63], 0, v[2:3]
	s_mov_b32 m0, s10
	ds_read_b128 v[212:215], v197 offset:16384
	ds_read_b128 v[216:219], v197 offset:17408
	ds_read_b128 v[220:223], v197 offset:18432
	ds_read_b128 v[224:227], v197 offset:19456
	ds_read_b128 v[228:231], v197 offset:20480
	ds_read_b128 v[232:235], v197 offset:21504
	ds_read_b128 v[236:239], v197 offset:22528
	ds_read_b128 v[240:243], v197 offset:23552
	global_load_lds_dwordx4 v[160:161], off
	s_add_i32 m0, s10, 0x2000
	s_add_u32 s10, s62, 0x160000
	v_lshl_add_u64 v[162:163], s[62:63], 0, v[150:151]
	s_addc_u32 s11, s63, 0
	s_add_i32 s19, s19, s66
	global_load_lds_dwordx4 v[162:163], off
	v_lshl_add_u64 v[244:245], s[10:11], 0, v[2:3]
	s_mov_b32 m0, s19
	v_lshl_add_u64 v[246:247], s[64:65], 0, v[148:149]
	global_load_lds_dwordx4 v[244:245], off
	v_lshl_add_u64 v[244:245], s[10:11], 0, v[150:151]
	s_add_i32 m0, s19, 0x2000
	s_nop 0
	global_load_lds_dwordx4 v[244:245], off
	v_lshl_add_u64 v[244:245], s[64:65], 0, v[0:1]
	s_mov_b32 m0, s67
	s_nop 0
	global_load_lds_dwordx4 v[244:245], off
	s_mov_b32 m0, s75
	s_nop 0
	global_load_lds_dwordx4 v[246:247], off
	s_waitcnt vmcnt(8)
	s_waitcnt lgkmcnt(0)
	s_barrier
; #define PG8_STAGE(bufoff, gbase, voff) do { _Pragma("unroll") for (int _i = 0; _i < 2; ++_i) \
;         __builtin_amdgcn_global_load_lds((const unsigned*)((const char*)(gbase) + (voff)[_i]), (LAS unsigned*)(lds + (bufoff) + ldsw + _i * 8192), 16, 0, 0); } while (0)
; #define PG8_LDA(dst, b, h) do { _Pragma("unroll") for (int m = 0; m < 4; ++m) _Pragma("unroll") for (int k = 0; k < 2; ++k) dst[m][k] = *(const LAS bf16x8*)(lds + PG8_SA(b, h) + aoff + m * 2048 + k * 1024); } while (0)
; #define PG8_LDB(dst, b, h) do { _Pragma("unroll") for (int n = 0; n < 2; ++n) _Pragma("unroll") for (int k = 0; k < 2; ++k) dst[n][k] = *(const LAS bf16x8*)(lds + PG8_SB(b, h) + boff + n * 2048 + k * 1024); } while (0)
; #define PG8_MMA(ai, bj, At, Bt) do { __builtin_amdgcn_s_setprio(1); _Pragma("unroll") for (int m = 0; m < 4; ++m) _Pragma("unroll") for (int n = 0; n < 2; ++n) _Pragma("unroll") for (int k = 0; k < 2; ++k) \
;         acc[ai][bj][m][n] = __builtin_amdgcn_mfma_f32_16x16x32_bf16(Bt[n][k], At[m][k], acc[ai][bj][m][n], 0, 0, 0); __builtin_amdgcn_s_setprio(0); } while (0)
; #define PG8_WAIT_V(n) asm volatile("s_waitcnt vmcnt(" #n ")" ::: "memory")
; #define PG8_WAIT_L(n) asm volatile("s_waitcnt lgkmcnt(" #n ")" ::: "memory")
; #define PG8_BAR __builtin_amdgcn_s_barrier()
; #define PG8_SCHED __builtin_amdgcn_sched_barrier(0)
; template <class Epi, class Sched, bool ALIGN_EPI = true>
; __device__ __forceinline__ void gemm_phase(LAS unsigned char* lds, const Gemm g, const Sched& S, const Epi& E) {
;     ...
;             PG8_WAIT_V(8); PG8_WAIT_L(0); PG8_BAR; PG8_MMA(1, 0, At, B0); PG8_MMA(1, 1, At, B1); PG8_BAR; PG8_SCHED;
;             PG8_LDB(B0, 1, 0); PG8_LDB(B1, 1, 1); PG8_SCHED; PG8_LDA(At, 1, 0); PG8_STAGE(PG8_SA(0, 1), a2 + hA, voffA);
;             PG8_WAIT_V(8); PG8_WAIT_L(0); PG8_BAR; PG8_MMA(0, 0, At, B0); PG8_MMA(0, 1, At, B1); PG8_BAR; PG8_SCHED;
	s_setprio 1
	s_waitcnt lgkmcnt(0)
	v_mfma_f32_16x16x32_bf16 v[128:131], v[136:139], v[212:215], 0
	v_mfma_f32_16x16x32_bf16 v[128:131], v[140:143], v[216:219], v[128:131]
	v_mfma_f32_16x16x32_bf16 v[124:127], v[144:147], v[212:215], 0
	v_mfma_f32_16x16x32_bf16 v[124:127], v[172:175], v[216:219], v[124:127]
	v_mfma_f32_16x16x32_bf16 v[104:107], v[136:139], v[220:223], 0
	v_mfma_f32_16x16x32_bf16 v[104:107], v[140:143], v[224:227], v[104:107]
	v_mfma_f32_16x16x32_bf16 v[100:103], v[144:147], v[220:223], 0
	v_mfma_f32_16x16x32_bf16 v[100:103], v[172:175], v[224:227], v[100:103]
	v_mfma_f32_16x16x32_bf16 v[72:75], v[136:139], v[228:231], 0
	v_mfma_f32_16x16x32_bf16 v[72:75], v[140:143], v[232:235], v[72:75]
	v_mfma_f32_16x16x32_bf16 v[68:71], v[144:147], v[228:231], 0
	v_mfma_f32_16x16x32_bf16 v[68:71], v[172:175], v[232:235], v[68:71]
	v_mfma_f32_16x16x32_bf16 v[32:35], v[136:139], v[236:239], 0
	v_mfma_f32_16x16x32_bf16 v[32:35], v[140:143], v[240:243], v[32:35]
	v_mfma_f32_16x16x32_bf16 v[28:31], v[144:147], v[236:239], 0
	v_mfma_f32_16x16x32_bf16 v[28:31], v[172:175], v[240:243], v[28:31]
	s_setprio 0
	s_setprio 1
	v_mfma_f32_16x16x32_bf16 v[120:123], v[176:179], v[212:215], 0
	v_mfma_f32_16x16x32_bf16 v[120:123], v[180:183], v[216:219], v[120:123]
	v_mfma_f32_16x16x32_bf16 v[116:119], v[184:187], v[212:215], 0
	v_mfma_f32_16x16x32_bf16 v[116:119], v[208:211], v[216:219], v[116:119]
	v_mfma_f32_16x16x32_bf16 v[84:87], v[176:179], v[220:223], 0
	v_mfma_f32_16x16x32_bf16 v[84:87], v[180:183], v[224:227], v[84:87]
	v_mfma_f32_16x16x32_bf16 v[80:83], v[184:187], v[220:223], 0
	v_mfma_f32_16x16x32_bf16 v[80:83], v[208:211], v[224:227], v[80:83]
	v_mfma_f32_16x16x32_bf16 v[48:51], v[176:179], v[228:231], 0
	v_mfma_f32_16x16x32_bf16 v[48:51], v[180:183], v[232:235], v[48:51]
	v_mfma_f32_16x16x32_bf16 v[44:47], v[184:187], v[228:231], 0
	v_mfma_f32_16x16x32_bf16 v[44:47], v[208:211], v[232:235], v[44:47]
	v_mfma_f32_16x16x32_bf16 v[24:27], v[176:179], v[236:239], 0
	v_mfma_f32_16x16x32_bf16 v[24:27], v[180:183], v[240:243], v[24:27]
	v_mfma_f32_16x16x32_bf16 v[20:23], v[184:187], v[236:239], 0
	v_mfma_f32_16x16x32_bf16 v[20:23], v[208:211], v[240:243], v[20:23]
	s_setprio 0
	s_barrier
	s_add_i32 s19, 0, 0x18000
	s_add_i32 s24, 0, 0x1c000
	v_add_u32_e32 v172, s19, v188
	v_add_u32_e32 v207, s24, v188
	ds_read_b128 v[136:139], v172
	ds_read_b128 v[140:143], v172 offset:1024
	ds_read_b128 v[144:147], v172 offset:2048
	ds_read_b128 v[172:175], v172 offset:3072
	ds_read_b128 v[176:179], v207
	ds_read_b128 v[180:183], v207 offset:1024
	ds_read_b128 v[184:187], v207 offset:2048
	ds_read_b128 v[208:211], v207 offset:3072
	s_add_u32 s10, s64, 0x160000
	s_addc_u32 s11, s65, 0
	s_mov_b32 m0, s76
	v_lshl_add_u64 v[248:249], s[10:11], 0, v[0:1]
	ds_read_b128 v[212:215], v197 offset:32768
	ds_read_b128 v[216:219], v197 offset:33792
	ds_read_b128 v[220:223], v197 offset:34816
	ds_read_b128 v[224:227], v197 offset:35840
	ds_read_b128 v[228:231], v197 offset:36864
	ds_read_b128 v[232:235], v197 offset:37888
	ds_read_b128 v[236:239], v197 offset:38912
	ds_read_b128 v[240:243], v197 offset:39936
	global_load_lds_dwordx4 v[248:249], off
	v_lshl_add_u64 v[248:249], s[10:11], 0, v[148:149]
	s_mov_b32 m0, s77
	s_nop 0
	global_load_lds_dwordx4 v[248:249], off
	s_waitcnt vmcnt(8)
	s_waitcnt lgkmcnt(0)
	s_barrier
	s_setprio 1
	s_waitcnt lgkmcnt(0)
	v_mfma_f32_16x16x32_bf16 v[16:19], v[136:139], v[212:215], v[16:19]
	v_mfma_f32_16x16x32_bf16 v[16:19], v[140:143], v[216:219], v[16:19]
	v_mfma_f32_16x16x32_bf16 v[12:15], v[144:147], v[212:215], v[12:15]
	v_mfma_f32_16x16x32_bf16 v[12:15], v[172:175], v[216:219], v[12:15]
	v_mfma_f32_16x16x32_bf16 v[56:59], v[136:139], v[220:223], v[56:59]
	v_mfma_f32_16x16x32_bf16 v[56:59], v[140:143], v[224:227], v[56:59]
	v_mfma_f32_16x16x32_bf16 v[52:55], v[144:147], v[220:223], v[52:55]
	v_mfma_f32_16x16x32_bf16 v[52:55], v[172:175], v[224:227], v[52:55]
	v_mfma_f32_16x16x32_bf16 v[88:91], v[136:139], v[228:231], v[88:91]
	v_mfma_f32_16x16x32_bf16 v[88:91], v[140:143], v[232:235], v[88:91]
	v_mfma_f32_16x16x32_bf16 v[76:79], v[144:147], v[228:231], v[76:79]
	v_mfma_f32_16x16x32_bf16 v[76:79], v[172:175], v[232:235], v[76:79]
	v_mfma_f32_16x16x32_bf16 v[112:115], v[136:139], v[236:239], v[112:115]
	v_mfma_f32_16x16x32_bf16 v[112:115], v[140:143], v[240:243], v[112:115]
	v_mfma_f32_16x16x32_bf16 v[108:111], v[144:147], v[236:239], v[108:111]
	v_mfma_f32_16x16x32_bf16 v[108:111], v[172:175], v[240:243], v[108:111]
	s_setprio 0
	s_setprio 1
	v_mfma_f32_16x16x32_bf16 v[8:11], v[176:179], v[212:215], v[8:11]
	v_mfma_f32_16x16x32_bf16 v[8:11], v[180:183], v[216:219], v[8:11]
	v_mfma_f32_16x16x32_bf16 v[4:7], v[184:187], v[212:215], v[4:7]
	v_mfma_f32_16x16x32_bf16 v[4:7], v[208:211], v[216:219], v[4:7]
	v_mfma_f32_16x16x32_bf16 v[40:43], v[176:179], v[220:223], v[40:43]
	v_mfma_f32_16x16x32_bf16 v[40:43], v[180:183], v[224:227], v[40:43]
	v_mfma_f32_16x16x32_bf16 v[36:39], v[184:187], v[220:223], v[36:39]
	v_mfma_f32_16x16x32_bf16 v[36:39], v[208:211], v[224:227], v[36:39]
	v_mfma_f32_16x16x32_bf16 v[64:67], v[176:179], v[228:231], v[64:67]
	v_mfma_f32_16x16x32_bf16 v[64:67], v[180:183], v[232:235], v[64:67]
	v_mfma_f32_16x16x32_bf16 v[60:63], v[184:187], v[228:231], v[60:63]
	v_mfma_f32_16x16x32_bf16 v[60:63], v[208:211], v[232:235], v[60:63]
	v_mfma_f32_16x16x32_bf16 v[96:99], v[176:179], v[236:239], v[96:99]
	v_mfma_f32_16x16x32_bf16 v[96:99], v[180:183], v[240:243], v[96:99]
	v_mfma_f32_16x16x32_bf16 v[92:95], v[184:187], v[236:239], v[92:95]
	v_mfma_f32_16x16x32_bf16 v[92:95], v[208:211], v[240:243], v[92:95]
	s_setprio 0
	s_barrier
; #define PG8_STAGE(bufoff, gbase, voff) do { _Pragma("unroll") for (int _i = 0; _i < 2; ++_i) \
;         __builtin_amdgcn_global_load_lds((const unsigned*)((const char*)(gbase) + (voff)[_i]), (LAS unsigned*)(lds + (bufoff) + ldsw + _i * 8192), 16, 0, 0); } while (0)
; #define PG8_LDA(dst, b, h) do { _Pragma("unroll") for (int m = 0; m < 4; ++m) _Pragma("unroll") for (int k = 0; k < 2; ++k) dst[m][k] = *(const LAS bf16x8*)(lds + PG8_SA(b, h) + aoff + m * 2048 + k * 1024); } while (0)
; #define PG8_LDB(dst, b, h) do { _Pragma("unroll") for (int n = 0; n < 2; ++n) _Pragma("unroll") for (int k = 0; k < 2; ++k) dst[n][k] = *(const LAS bf16x8*)(lds + PG8_SB(b, h) + boff + n * 2048 + k * 1024); } while (0)
; #define PG8_MMA(ai, bj, At, Bt) do { __builtin_amdgcn_s_setprio(1); _Pragma("unroll") for (int m = 0; m < 4; ++m) _Pragma("unroll") for (int n = 0; n < 2; ++n) _Pragma("unroll") for (int k = 0; k < 2; ++k) \
;         acc[ai][bj][m][n] = __builtin_amdgcn_mfma_f32_16x16x32_bf16(Bt[n][k], At[m][k], acc[ai][bj][m][n], 0, 0, 0); __builtin_amdgcn_s_setprio(0); } while (0)
; #define PG8_WAIT_V(n) asm volatile("s_waitcnt vmcnt(" #n ")" ::: "memory")
; #define PG8_BAR __builtin_amdgcn_s_barrier()
; template <class Epi, class Sched, bool ALIGN_EPI = true>
; __device__ __forceinline__ void gemm_phase(LAS unsigned char* lds, const Gemm g, const Sched& S, const Epi& E) {
;     ...
;             PG8_LDB(B0, 0, 0); PG8_LDB(B1, 0, 1); PG8_SCHED; PG8_LDA(At, 0, 0); PG8_STAGE(PG8_SA(1, 1), a1 + hA, voffA);
;             PG8_WAIT_V(8); PG8_WAIT_L(0); PG8_BAR; PG8_MMA(0, 0, At, B0); PG8_MMA(0, 1, At, B1); PG8_BAR; PG8_SCHED;
;             PG8_LDA(At, 0, 1); PG8_STAGE(PG8_SB(0, 0), b2, voffB); PG8_STAGE(PG8_SB(0, 1), b2 + hB, voffB); PG8_STAGE(PG8_SA(0, 0), a2, voffA);
;             PG8_WAIT_V(8); PG8_WAIT_L(0); PG8_BAR; PG8_MMA(1, 0, At, B0); PG8_MMA(1, 1, At, B1); PG8_BAR; PG8_SCHED;
;             PG8_LDB(B0, 1, 0); PG8_LDB(B1, 1, 1); PG8_SCHED; PG8_LDA(At, 1, 0); PG8_STAGE(PG8_SA(0, 1), a2 + hA, voffA);
;             PG8_WAIT_V(8); PG8_WAIT_L(0); PG8_BAR; PG8_MMA(0, 0, At, B0); PG8_MMA(0, 1, At, B1); PG8_BAR; PG8_SCHED;
;             PG8_LDA(At, 1, 1); PG8_STAGE(PG8_SB(1, 0), b3, voffB); PG8_STAGE(PG8_SB(1, 1), b3 + hB, voffB); PG8_STAGE(PG8_SA(1, 0), a3, voffA);
;             PG8_WAIT_V(8); PG8_WAIT_L(0); PG8_BAR; PG8_MMA(1, 0, At, B0); PG8_MMA(1, 1, At, B1); PG8_BAR; PG8_SCHED;
	s_add_i32 s10, s19, s66
	v_lshl_add_u64 v[160:161], v[160:161], 0, s[86:87]
	s_mov_b32 m0, s10
	ds_read_b128 v[212:215], v197 offset:49152
	ds_read_b128 v[216:219], v197 offset:50176
	ds_read_b128 v[220:223], v197 offset:51200
	ds_read_b128 v[224:227], v197 offset:52224
	ds_read_b128 v[228:231], v197 offset:53248
	ds_read_b128 v[232:235], v197 offset:54272
	ds_read_b128 v[236:239], v197 offset:55296
	ds_read_b128 v[240:243], v197 offset:56320
	global_load_lds_dwordx4 v[160:161], off
	s_add_i32 m0, s10, 0x2000
	s_add_u32 s10, s62, 0x160080
	v_lshl_add_u64 v[160:161], v[162:163], 0, s[86:87]
	s_addc_u32 s11, s63, 0
	s_add_i32 s19, s24, s66
	global_load_lds_dwordx4 v[160:161], off
	v_lshl_add_u64 v[160:161], s[10:11], 0, v[2:3]
	s_mov_b32 m0, s19
	s_nop 0
	global_load_lds_dwordx4 v[160:161], off
	v_lshl_add_u64 v[160:161], s[10:11], 0, v[150:151]
	s_add_i32 m0, s19, 0x2000
	s_nop 0
	global_load_lds_dwordx4 v[160:161], off
	v_lshl_add_u64 v[160:161], v[244:245], 0, s[86:87]
	s_mov_b32 m0, s80
	s_nop 0
	global_load_lds_dwordx4 v[160:161], off
	v_lshl_add_u64 v[160:161], v[246:247], 0, s[86:87]
	s_mov_b32 m0, s81
	s_nop 0
	global_load_lds_dwordx4 v[160:161], off
	s_waitcnt vmcnt(8)
	s_waitcnt lgkmcnt(0)
	s_barrier
	s_setprio 1
	s_waitcnt lgkmcnt(0)
	v_mfma_f32_16x16x32_bf16 v[128:131], v[136:139], v[212:215], v[128:131]
	v_mfma_f32_16x16x32_bf16 v[128:131], v[140:143], v[216:219], v[128:131]
	v_mfma_f32_16x16x32_bf16 v[124:127], v[144:147], v[212:215], v[124:127]
	v_mfma_f32_16x16x32_bf16 v[124:127], v[172:175], v[216:219], v[124:127]
	v_mfma_f32_16x16x32_bf16 v[104:107], v[136:139], v[220:223], v[104:107]
	v_mfma_f32_16x16x32_bf16 v[104:107], v[140:143], v[224:227], v[104:107]
	v_mfma_f32_16x16x32_bf16 v[100:103], v[144:147], v[220:223], v[100:103]
	v_mfma_f32_16x16x32_bf16 v[100:103], v[172:175], v[224:227], v[100:103]
	v_mfma_f32_16x16x32_bf16 v[72:75], v[136:139], v[228:231], v[72:75]
	v_mfma_f32_16x16x32_bf16 v[72:75], v[140:143], v[232:235], v[72:75]
	v_mfma_f32_16x16x32_bf16 v[68:71], v[144:147], v[228:231], v[68:71]
	v_mfma_f32_16x16x32_bf16 v[68:71], v[172:175], v[232:235], v[68:71]
	v_mfma_f32_16x16x32_bf16 v[32:35], v[136:139], v[236:239], v[32:35]
	v_mfma_f32_16x16x32_bf16 v[32:35], v[140:143], v[240:243], v[32:35]
	v_mfma_f32_16x16x32_bf16 v[28:31], v[144:147], v[236:239], v[28:31]
	v_mfma_f32_16x16x32_bf16 v[28:31], v[172:175], v[240:243], v[28:31]
	s_setprio 0
	s_setprio 1
	v_mfma_f32_16x16x32_bf16 v[120:123], v[176:179], v[212:215], v[120:123]
	v_mfma_f32_16x16x32_bf16 v[120:123], v[180:183], v[216:219], v[120:123]
	v_mfma_f32_16x16x32_bf16 v[116:119], v[184:187], v[212:215], v[116:119]
	v_mfma_f32_16x16x32_bf16 v[116:119], v[208:211], v[216:219], v[116:119]
	v_mfma_f32_16x16x32_bf16 v[84:87], v[176:179], v[220:223], v[84:87]
	v_mfma_f32_16x16x32_bf16 v[84:87], v[180:183], v[224:227], v[84:87]
	v_mfma_f32_16x16x32_bf16 v[80:83], v[184:187], v[220:223], v[80:83]
	v_mfma_f32_16x16x32_bf16 v[80:83], v[208:211], v[224:227], v[80:83]
	v_mfma_f32_16x16x32_bf16 v[48:51], v[176:179], v[228:231], v[48:51]
	v_mfma_f32_16x16x32_bf16 v[48:51], v[180:183], v[232:235], v[48:51]
	v_mfma_f32_16x16x32_bf16 v[44:47], v[184:187], v[228:231], v[44:47]
	v_mfma_f32_16x16x32_bf16 v[44:47], v[208:211], v[232:235], v[44:47]
	v_mfma_f32_16x16x32_bf16 v[24:27], v[176:179], v[236:239], v[24:27]
	v_mfma_f32_16x16x32_bf16 v[24:27], v[180:183], v[240:243], v[24:27]
	v_mfma_f32_16x16x32_bf16 v[20:23], v[184:187], v[236:239], v[20:23]
	v_mfma_f32_16x16x32_bf16 v[20:23], v[208:211], v[240:243], v[20:23]
	s_setprio 0
	s_barrier
	s_add_i32 s18, s18, 2
	s_cmpk_gt_u32 s18, 0x55
	s_mov_b64 s[10:11], vcc
	s_cbranch_scc1 .Lpeel_exit_1111
.LBB0_1111:
	s_add_u32 vcc_lo, s10, 0x100
	s_addc_u32 vcc_hi, s11, 0
	s_add_u32 s19, s16, s10
	s_addc_u32 s24, s17, s11
	s_add_i32 s25, 0, 0x10000
	s_cmpk_eq_i32 s18, 0x54
	s_cselect_b32 s65, s61, s24
	s_cselect_b32 s24, 0, vcc_lo
	s_cselect_b32 s64, s60, s19
	s_cselect_b32 s19, 0, vcc_hi
	s_add_u32 s62, s2, s24
	v_add_u32_e32 v160, s25, v188
	s_addc_u32 s63, s3, s19
	s_add_i32 s19, 0, 0x14000
	ds_read_b128 v[136:139], v160
	ds_read_b128 v[140:143], v160 offset:1024
	ds_read_b128 v[144:147], v160 offset:2048
	ds_read_b128 v[172:175], v160 offset:3072
	v_add_u32_e32 v160, s19, v188
	ds_read_b128 v[176:179], v160
	ds_read_b128 v[180:183], v160 offset:1024
	ds_read_b128 v[184:187], v160 offset:2048
	ds_read_b128 v[208:211], v160 offset:3072
	v_lshl_add_u64 v[160:161], v[132:133], 0, s[10:11]
	s_add_i32 m0, s67, 0xc000
	ds_read_b128 v[212:215], v197
	ds_read_b128 v[216:219], v197 offset:1024
	ds_read_b128 v[220:223], v197 offset:2048
	ds_read_b128 v[224:227], v197 offset:3072
	ds_read_b128 v[228:231], v197 offset:4096
	ds_read_b128 v[232:235], v197 offset:5120
	ds_read_b128 v[236:239], v197 offset:6144
	ds_read_b128 v[240:243], v197 offset:7168
	global_load_lds_dwordx4 v[160:161], off
	v_lshl_add_u64 v[160:161], v[134:135], 0, s[10:11]
	s_add_i32 m0, s67, 0xe000
	s_nop 0
	global_load_lds_dwordx4 v[160:161], off
	s_waitcnt vmcnt(8)
	s_waitcnt lgkmcnt(0)
	s_barrier
; #define PG8_STAGE(bufoff, gbase, voff) do { _Pragma("unroll") for (int _i = 0; _i < 2; ++_i) \
;         __builtin_amdgcn_global_load_lds((const unsigned*)((const char*)(gbase) + (voff)[_i]), (LAS unsigned*)(lds + (bufoff) + ldsw + _i * 8192), 16, 0, 0); } while (0)
; #define PG8_LDA(dst, b, h) do { _Pragma("unroll") for (int m = 0; m < 4; ++m) _Pragma("unroll") for (int k = 0; k < 2; ++k) dst[m][k] = *(const LAS bf16x8*)(lds + PG8_SA(b, h) + aoff + m * 2048 + k * 1024); } while (0)
; #define PG8_MMA(ai, bj, At, Bt) do { __builtin_amdgcn_s_setprio(1); _Pragma("unroll") for (int m = 0; m < 4; ++m) _Pragma("unroll") for (int n = 0; n < 2; ++n) _Pragma("unroll") for (int k = 0; k < 2; ++k) \
;         acc[ai][bj][m][n] = __builtin_amdgcn_mfma_f32_16x16x32_bf16(Bt[n][k], At[m][k], acc[ai][bj][m][n], 0, 0, 0); __builtin_amdgcn_s_setprio(0); } while (0)
; #define PG8_WAIT_V(n) asm volatile("s_waitcnt vmcnt(" #n ")" ::: "memory")
; #define PG8_WAIT_L(n) asm volatile("s_waitcnt lgkmcnt(" #n ")" ::: "memory")
; #define PG8_BAR __builtin_amdgcn_s_barrier()
; #define PG8_SCHED __builtin_amdgcn_sched_barrier(0)
; template <class Epi, class Sched, bool ALIGN_EPI = true>
; __device__ __forceinline__ void gemm_phase(LAS unsigned char* lds, const Gemm g, const Sched& S, const Epi& E) {
;     ...
;             PG8_WAIT_V(8); PG8_WAIT_L(0); PG8_BAR; PG8_MMA(0, 0, At, B0); PG8_MMA(0, 1, At, B1); PG8_BAR; PG8_SCHED;
;             PG8_LDA(At, 0, 1); PG8_STAGE(PG8_SB(0, 0), b2, voffB); PG8_STAGE(PG8_SB(0, 1), b2 + hB, voffB); PG8_STAGE(PG8_SA(0, 0), a2, voffA);
;             PG8_WAIT_V(8); PG8_WAIT_L(0); PG8_BAR; PG8_MMA(1, 0, At, B0); PG8_MMA(1, 1, At, B1); PG8_BAR; PG8_SCHED;
	s_setprio 1
	s_waitcnt lgkmcnt(0)
	v_mfma_f32_16x16x32_bf16 v[16:19], v[136:139], v[212:215], v[16:19]
	v_mfma_f32_16x16x32_bf16 v[16:19], v[140:143], v[216:219], v[16:19]
	v_mfma_f32_16x16x32_bf16 v[12:15], v[144:147], v[212:215], v[12:15]
	v_mfma_f32_16x16x32_bf16 v[12:15], v[172:175], v[216:219], v[12:15]
	v_mfma_f32_16x16x32_bf16 v[56:59], v[136:139], v[220:223], v[56:59]
	v_mfma_f32_16x16x32_bf16 v[56:59], v[140:143], v[224:227], v[56:59]
	v_mfma_f32_16x16x32_bf16 v[52:55], v[144:147], v[220:223], v[52:55]
	v_mfma_f32_16x16x32_bf16 v[52:55], v[172:175], v[224:227], v[52:55]
	v_mfma_f32_16x16x32_bf16 v[88:91], v[136:139], v[228:231], v[88:91]
	v_mfma_f32_16x16x32_bf16 v[88:91], v[140:143], v[232:235], v[88:91]
	v_mfma_f32_16x16x32_bf16 v[76:79], v[144:147], v[228:231], v[76:79]
	v_mfma_f32_16x16x32_bf16 v[76:79], v[172:175], v[232:235], v[76:79]
	v_mfma_f32_16x16x32_bf16 v[112:115], v[136:139], v[236:239], v[112:115]
	v_mfma_f32_16x16x32_bf16 v[112:115], v[140:143], v[240:243], v[112:115]
	v_mfma_f32_16x16x32_bf16 v[108:111], v[144:147], v[236:239], v[108:111]
	v_mfma_f32_16x16x32_bf16 v[108:111], v[172:175], v[240:243], v[108:111]
	s_setprio 0
	s_setprio 1
	v_mfma_f32_16x16x32_bf16 v[8:11], v[176:179], v[212:215], v[8:11]
	v_mfma_f32_16x16x32_bf16 v[8:11], v[180:183], v[216:219], v[8:11]
	v_mfma_f32_16x16x32_bf16 v[4:7], v[184:187], v[212:215], v[4:7]
	v_mfma_f32_16x16x32_bf16 v[4:7], v[208:211], v[216:219], v[4:7]
	v_mfma_f32_16x16x32_bf16 v[40:43], v[176:179], v[220:223], v[40:43]
	v_mfma_f32_16x16x32_bf16 v[40:43], v[180:183], v[224:227], v[40:43]
	v_mfma_f32_16x16x32_bf16 v[36:39], v[184:187], v[220:223], v[36:39]
	v_mfma_f32_16x16x32_bf16 v[36:39], v[208:211], v[224:227], v[36:39]
	v_mfma_f32_16x16x32_bf16 v[64:67], v[176:179], v[228:231], v[64:67]
	v_mfma_f32_16x16x32_bf16 v[64:67], v[180:183], v[232:235], v[64:67]
	v_mfma_f32_16x16x32_bf16 v[60:63], v[184:187], v[228:231], v[60:63]
	v_mfma_f32_16x16x32_bf16 v[60:63], v[208:211], v[232:235], v[60:63]
	v_mfma_f32_16x16x32_bf16 v[96:99], v[176:179], v[236:239], v[96:99]
	v_mfma_f32_16x16x32_bf16 v[96:99], v[180:183], v[240:243], v[96:99]
	v_mfma_f32_16x16x32_bf16 v[92:95], v[184:187], v[236:239], v[92:95]
	v_mfma_f32_16x16x32_bf16 v[92:95], v[208:211], v[240:243], v[92:95]
	s_setprio 0
	s_barrier
	s_add_i32 s10, s25, s66
	v_lshl_add_u64 v[160:161], s[62:63], 0, v[2:3]
	s_mov_b32 m0, s10
	ds_read_b128 v[212:215], v197 offset:16384
	ds_read_b128 v[216:219], v197 offset:17408
	ds_read_b128 v[220:223], v197 offset:18432
	ds_read_b128 v[224:227], v197 offset:19456
	ds_read_b128 v[228:231], v197 offset:20480
	ds_read_b128 v[232:235], v197 offset:21504
	ds_read_b128 v[236:239], v197 offset:22528
	ds_read_b128 v[240:243], v197 offset:23552
	global_load_lds_dwordx4 v[160:161], off
	s_add_i32 m0, s10, 0x2000
	s_add_u32 s10, s62, 0x160000
	v_lshl_add_u64 v[162:163], s[62:63], 0, v[150:151]
	s_addc_u32 s11, s63, 0
	s_add_i32 s19, s19, s66
	global_load_lds_dwordx4 v[162:163], off
	v_lshl_add_u64 v[244:245], s[10:11], 0, v[2:3]
	s_mov_b32 m0, s19
	v_lshl_add_u64 v[246:247], s[64:65], 0, v[148:149]
	global_load_lds_dwordx4 v[244:245], off
	v_lshl_add_u64 v[244:245], s[10:11], 0, v[150:151]
	s_add_i32 m0, s19, 0x2000
	s_nop 0
	global_load_lds_dwordx4 v[244:245], off
	v_lshl_add_u64 v[244:245], s[64:65], 0, v[0:1]
	s_mov_b32 m0, s67
	s_nop 0
	global_load_lds_dwordx4 v[244:245], off
	s_mov_b32 m0, s75
	s_nop 0
	global_load_lds_dwordx4 v[246:247], off
	s_waitcnt vmcnt(8)
	s_waitcnt lgkmcnt(0)
	s_barrier
	s_setprio 1
	s_waitcnt lgkmcnt(0)
	v_mfma_f32_16x16x32_bf16 v[128:131], v[136:139], v[212:215], v[128:131]
	v_mfma_f32_16x16x32_bf16 v[128:131], v[140:143], v[216:219], v[128:131]
	v_mfma_f32_16x16x32_bf16 v[124:127], v[144:147], v[212:215], v[124:127]
	v_mfma_f32_16x16x32_bf16 v[124:127], v[172:175], v[216:219], v[124:127]
	v_mfma_f32_16x16x32_bf16 v[104:107], v[136:139], v[220:223], v[104:107]
	v_mfma_f32_16x16x32_bf16 v[104:107], v[140:143], v[224:227], v[104:107]
	v_mfma_f32_16x16x32_bf16 v[100:103], v[144:147], v[220:223], v[100:103]
	v_mfma_f32_16x16x32_bf16 v[100:103], v[172:175], v[224:227], v[100:103]
	v_mfma_f32_16x16x32_bf16 v[72:75], v[136:139], v[228:231], v[72:75]
	v_mfma_f32_16x16x32_bf16 v[72:75], v[140:143], v[232:235], v[72:75]
	v_mfma_f32_16x16x32_bf16 v[68:71], v[144:147], v[228:231], v[68:71]
	v_mfma_f32_16x16x32_bf16 v[68:71], v[172:175], v[232:235], v[68:71]
	v_mfma_f32_16x16x32_bf16 v[32:35], v[136:139], v[236:239], v[32:35]
	v_mfma_f32_16x16x32_bf16 v[32:35], v[140:143], v[240:243], v[32:35]
	v_mfma_f32_16x16x32_bf16 v[28:31], v[144:147], v[236:239], v[28:31]
	v_mfma_f32_16x16x32_bf16 v[28:31], v[172:175], v[240:243], v[28:31]
	s_setprio 0
	s_setprio 1
	v_mfma_f32_16x16x32_bf16 v[120:123], v[176:179], v[212:215], v[120:123]
	v_mfma_f32_16x16x32_bf16 v[120:123], v[180:183], v[216:219], v[120:123]
	v_mfma_f32_16x16x32_bf16 v[116:119], v[184:187], v[212:215], v[116:119]
	v_mfma_f32_16x16x32_bf16 v[116:119], v[208:211], v[216:219], v[116:119]
	v_mfma_f32_16x16x32_bf16 v[84:87], v[176:179], v[220:223], v[84:87]
	v_mfma_f32_16x16x32_bf16 v[84:87], v[180:183], v[224:227], v[84:87]
	v_mfma_f32_16x16x32_bf16 v[80:83], v[184:187], v[220:223], v[80:83]
	v_mfma_f32_16x16x32_bf16 v[80:83], v[208:211], v[224:227], v[80:83]
	v_mfma_f32_16x16x32_bf16 v[48:51], v[176:179], v[228:231], v[48:51]
	v_mfma_f32_16x16x32_bf16 v[48:51], v[180:183], v[232:235], v[48:51]
	v_mfma_f32_16x16x32_bf16 v[44:47], v[184:187], v[228:231], v[44:47]
	v_mfma_f32_16x16x32_bf16 v[44:47], v[208:211], v[232:235], v[44:47]
	v_mfma_f32_16x16x32_bf16 v[24:27], v[176:179], v[236:239], v[24:27]
	v_mfma_f32_16x16x32_bf16 v[24:27], v[180:183], v[240:243], v[24:27]
	v_mfma_f32_16x16x32_bf16 v[20:23], v[184:187], v[236:239], v[20:23]
	v_mfma_f32_16x16x32_bf16 v[20:23], v[208:211], v[240:243], v[20:23]
	s_setprio 0
	s_barrier
; #define PG8_STAGE(bufoff, gbase, voff) do { _Pragma("unroll") for (int _i = 0; _i < 2; ++_i) \
;         __builtin_amdgcn_global_load_lds((const unsigned*)((const char*)(gbase) + (voff)[_i]), (LAS unsigned*)(lds + (bufoff) + ldsw + _i * 8192), 16, 0, 0); } while (0)
; #define PG8_LDA(dst, b, h) do { _Pragma("unroll") for (int m = 0; m < 4; ++m) _Pragma("unroll") for (int k = 0; k < 2; ++k) dst[m][k] = *(const LAS bf16x8*)(lds + PG8_SA(b, h) + aoff + m * 2048 + k * 1024); } while (0)
; #define PG8_LDB(dst, b, h) do { _Pragma("unroll") for (int n = 0; n < 2; ++n) _Pragma("unroll") for (int k = 0; k < 2; ++k) dst[n][k] = *(const LAS bf16x8*)(lds + PG8_SB(b, h) + boff + n * 2048 + k * 1024); } while (0)
; #define PG8_MMA(ai, bj, At, Bt) do { __builtin_amdgcn_s_setprio(1); _Pragma("unroll") for (int m = 0; m < 4; ++m) _Pragma("unroll") for (int n = 0; n < 2; ++n) _Pragma("unroll") for (int k = 0; k < 2; ++k) \
;         acc[ai][bj][m][n] = __builtin_amdgcn_mfma_f32_16x16x32_bf16(Bt[n][k], At[m][k], acc[ai][bj][m][n], 0, 0, 0); __builtin_amdgcn_s_setprio(0); } while (0)
; #define PG8_WAIT_V(n) asm volatile("s_waitcnt vmcnt(" #n ")" ::: "memory")
; #define PG8_WAIT_L(n) asm volatile("s_waitcnt lgkmcnt(" #n ")" ::: "memory")
; #define PG8_BAR __builtin_amdgcn_s_barrier()
; #define PG8_SCHED __builtin_amdgcn_sched_barrier(0)
; template <class Epi, class Sched, bool ALIGN_EPI = true>
; __device__ __forceinline__ void gemm_phase(LAS unsigned char* lds, const Gemm g, const Sched& S, const Epi& E) {
;     ...
;             PG8_LDB(B0, 1, 0); PG8_LDB(B1, 1, 1); PG8_SCHED; PG8_LDA(At, 1, 0); PG8_STAGE(PG8_SA(0, 1), a2 + hA, voffA);
;             PG8_WAIT_V(8); PG8_WAIT_L(0); PG8_BAR; PG8_MMA(0, 0, At, B0); PG8_MMA(0, 1, At, B1); PG8_BAR; PG8_SCHED;
	s_add_i32 s19, 0, 0x18000
	s_add_i32 s24, 0, 0x1c000
	v_add_u32_e32 v172, s19, v188
	v_add_u32_e32 v207, s24, v188
	ds_read_b128 v[136:139], v172
	ds_read_b128 v[140:143], v172 offset:1024
	ds_read_b128 v[144:147], v172 offset:2048
	ds_read_b128 v[172:175], v172 offset:3072
	ds_read_b128 v[176:179], v207
	ds_read_b128 v[180:183], v207 offset:1024
	ds_read_b128 v[184:187], v207 offset:2048
	ds_read_b128 v[208:211], v207 offset:3072
	s_add_u32 s10, s64, 0x160000
	s_addc_u32 s11, s65, 0
	s_mov_b32 m0, s76
	v_lshl_add_u64 v[248:249], s[10:11], 0, v[0:1]
	ds_read_b128 v[212:215], v197 offset:32768
	ds_read_b128 v[216:219], v197 offset:33792
	ds_read_b128 v[220:223], v197 offset:34816
	ds_read_b128 v[224:227], v197 offset:35840
	ds_read_b128 v[228:231], v197 offset:36864
	ds_read_b128 v[232:235], v197 offset:37888
	ds_read_b128 v[236:239], v197 offset:38912
	ds_read_b128 v[240:243], v197 offset:39936
	global_load_lds_dwordx4 v[248:249], off
	v_lshl_add_u64 v[248:249], s[10:11], 0, v[148:149]
	s_mov_b32 m0, s77
	s_nop 0
	global_load_lds_dwordx4 v[248:249], off
	s_waitcnt vmcnt(8)
	s_waitcnt lgkmcnt(0)
	s_barrier
	s_setprio 1
	s_waitcnt lgkmcnt(0)
	v_mfma_f32_16x16x32_bf16 v[16:19], v[136:139], v[212:215], v[16:19]
	v_mfma_f32_16x16x32_bf16 v[16:19], v[140:143], v[216:219], v[16:19]
	v_mfma_f32_16x16x32_bf16 v[12:15], v[144:147], v[212:215], v[12:15]
	v_mfma_f32_16x16x32_bf16 v[12:15], v[172:175], v[216:219], v[12:15]
	v_mfma_f32_16x16x32_bf16 v[56:59], v[136:139], v[220:223], v[56:59]
	v_mfma_f32_16x16x32_bf16 v[56:59], v[140:143], v[224:227], v[56:59]
	v_mfma_f32_16x16x32_bf16 v[52:55], v[144:147], v[220:223], v[52:55]
	v_mfma_f32_16x16x32_bf16 v[52:55], v[172:175], v[224:227], v[52:55]
	v_mfma_f32_16x16x32_bf16 v[88:91], v[136:139], v[228:231], v[88:91]
	v_mfma_f32_16x16x32_bf16 v[88:91], v[140:143], v[232:235], v[88:91]
	v_mfma_f32_16x16x32_bf16 v[76:79], v[144:147], v[228:231], v[76:79]
	v_mfma_f32_16x16x32_bf16 v[76:79], v[172:175], v[232:235], v[76:79]
	v_mfma_f32_16x16x32_bf16 v[112:115], v[136:139], v[236:239], v[112:115]
	v_mfma_f32_16x16x32_bf16 v[112:115], v[140:143], v[240:243], v[112:115]
	v_mfma_f32_16x16x32_bf16 v[108:111], v[144:147], v[236:239], v[108:111]
	v_mfma_f32_16x16x32_bf16 v[108:111], v[172:175], v[240:243], v[108:111]
	s_setprio 0
	s_setprio 1
	v_mfma_f32_16x16x32_bf16 v[8:11], v[176:179], v[212:215], v[8:11]
	v_mfma_f32_16x16x32_bf16 v[8:11], v[180:183], v[216:219], v[8:11]
	v_mfma_f32_16x16x32_bf16 v[4:7], v[184:187], v[212:215], v[4:7]
	v_mfma_f32_16x16x32_bf16 v[4:7], v[208:211], v[216:219], v[4:7]
	v_mfma_f32_16x16x32_bf16 v[40:43], v[176:179], v[220:223], v[40:43]
	v_mfma_f32_16x16x32_bf16 v[40:43], v[180:183], v[224:227], v[40:43]
	v_mfma_f32_16x16x32_bf16 v[36:39], v[184:187], v[220:223], v[36:39]
	v_mfma_f32_16x16x32_bf16 v[36:39], v[208:211], v[224:227], v[36:39]
	v_mfma_f32_16x16x32_bf16 v[64:67], v[176:179], v[228:231], v[64:67]
	v_mfma_f32_16x16x32_bf16 v[64:67], v[180:183], v[232:235], v[64:67]
	v_mfma_f32_16x16x32_bf16 v[60:63], v[184:187], v[228:231], v[60:63]
	v_mfma_f32_16x16x32_bf16 v[60:63], v[208:211], v[232:235], v[60:63]
	v_mfma_f32_16x16x32_bf16 v[96:99], v[176:179], v[236:239], v[96:99]
	v_mfma_f32_16x16x32_bf16 v[96:99], v[180:183], v[240:243], v[96:99]
	v_mfma_f32_16x16x32_bf16 v[92:95], v[184:187], v[236:239], v[92:95]
	v_mfma_f32_16x16x32_bf16 v[92:95], v[208:211], v[240:243], v[92:95]
	s_setprio 0
	s_barrier
; #define PG8_STAGE(bufoff, gbase, voff) do { _Pragma("unroll") for (int _i = 0; _i < 2; ++_i) \
;         __builtin_amdgcn_global_load_lds((const unsigned*)((const char*)(gbase) + (voff)[_i]), (LAS unsigned*)(lds + (bufoff) + ldsw + _i * 8192), 16, 0, 0); } while (0)
; #define PG8_LDA(dst, b, h) do { _Pragma("unroll") for (int m = 0; m < 4; ++m) _Pragma("unroll") for (int k = 0; k < 2; ++k) dst[m][k] = *(const LAS bf16x8*)(lds + PG8_SA(b, h) + aoff + m * 2048 + k * 1024); } while (0)
; #define PG8_MMA(ai, bj, At, Bt) do { __builtin_amdgcn_s_setprio(1); _Pragma("unroll") for (int m = 0; m < 4; ++m) _Pragma("unroll") for (int n = 0; n < 2; ++n) _Pragma("unroll") for (int k = 0; k < 2; ++k) \
;         acc[ai][bj][m][n] = __builtin_amdgcn_mfma_f32_16x16x32_bf16(Bt[n][k], At[m][k], acc[ai][bj][m][n], 0, 0, 0); __builtin_amdgcn_s_setprio(0); } while (0)
; #define PG8_WAIT_V(n) asm volatile("s_waitcnt vmcnt(" #n ")" ::: "memory")
; #define PG8_WAIT_L(n) asm volatile("s_waitcnt lgkmcnt(" #n ")" ::: "memory")
; #define PG8_BAR __builtin_amdgcn_s_barrier()
; #define PG8_SCHED __builtin_amdgcn_sched_barrier(0)
; template <class Epi, class Sched, bool ALIGN_EPI = true>
; __device__ __forceinline__ void gemm_phase(LAS unsigned char* lds, const Gemm g, const Sched& S, const Epi& E) {
;     ...
;             PG8_LDA(At, 1, 1); PG8_STAGE(PG8_SB(1, 0), b3, voffB); PG8_STAGE(PG8_SB(1, 1), b3 + hB, voffB); PG8_STAGE(PG8_SA(1, 0), a3, voffA);
;             PG8_WAIT_V(8); PG8_WAIT_L(0); PG8_BAR; PG8_MMA(1, 0, At, B0); PG8_MMA(1, 1, At, B1); PG8_BAR; PG8_SCHED;
	s_add_i32 s10, s19, s66
	v_lshl_add_u64 v[160:161], v[160:161], 0, s[86:87]
	s_mov_b32 m0, s10
	ds_read_b128 v[212:215], v197 offset:49152
	ds_read_b128 v[216:219], v197 offset:50176
	ds_read_b128 v[220:223], v197 offset:51200
	ds_read_b128 v[224:227], v197 offset:52224
	ds_read_b128 v[228:231], v197 offset:53248
	ds_read_b128 v[232:235], v197 offset:54272
	ds_read_b128 v[236:239], v197 offset:55296
	ds_read_b128 v[240:243], v197 offset:56320
	global_load_lds_dwordx4 v[160:161], off
	s_add_i32 m0, s10, 0x2000
	s_add_u32 s10, s62, 0x160080
	v_lshl_add_u64 v[160:161], v[162:163], 0, s[86:87]
	s_addc_u32 s11, s63, 0
	s_add_i32 s19, s24, s66
	global_load_lds_dwordx4 v[160:161], off
	v_lshl_add_u64 v[160:161], s[10:11], 0, v[2:3]
	s_mov_b32 m0, s19
	s_nop 0
	global_load_lds_dwordx4 v[160:161], off
	v_lshl_add_u64 v[160:161], s[10:11], 0, v[150:151]
	s_add_i32 m0, s19, 0x2000
	s_nop 0
	global_load_lds_dwordx4 v[160:161], off
	v_lshl_add_u64 v[160:161], v[244:245], 0, s[86:87]
	s_mov_b32 m0, s80
	s_nop 0
	global_load_lds_dwordx4 v[160:161], off
	v_lshl_add_u64 v[160:161], v[246:247], 0, s[86:87]
	s_mov_b32 m0, s81
	s_nop 0
	global_load_lds_dwordx4 v[160:161], off
	s_waitcnt vmcnt(8)
	s_waitcnt lgkmcnt(0)
	s_barrier
	s_setprio 1
	s_waitcnt lgkmcnt(0)
	v_mfma_f32_16x16x32_bf16 v[128:131], v[136:139], v[212:215], v[128:131]
	v_mfma_f32_16x16x32_bf16 v[128:131], v[140:143], v[216:219], v[128:131]
	v_mfma_f32_16x16x32_bf16 v[124:127], v[144:147], v[212:215], v[124:127]
	v_mfma_f32_16x16x32_bf16 v[124:127], v[172:175], v[216:219], v[124:127]
	v_mfma_f32_16x16x32_bf16 v[104:107], v[136:139], v[220:223], v[104:107]
	v_mfma_f32_16x16x32_bf16 v[104:107], v[140:143], v[224:227], v[104:107]
	v_mfma_f32_16x16x32_bf16 v[100:103], v[144:147], v[220:223], v[100:103]
	v_mfma_f32_16x16x32_bf16 v[100:103], v[172:175], v[224:227], v[100:103]
	v_mfma_f32_16x16x32_bf16 v[72:75], v[136:139], v[228:231], v[72:75]
	v_mfma_f32_16x16x32_bf16 v[72:75], v[140:143], v[232:235], v[72:75]
	v_mfma_f32_16x16x32_bf16 v[68:71], v[144:147], v[228:231], v[68:71]
	v_mfma_f32_16x16x32_bf16 v[68:71], v[172:175], v[232:235], v[68:71]
	v_mfma_f32_16x16x32_bf16 v[32:35], v[136:139], v[236:239], v[32:35]
	v_mfma_f32_16x16x32_bf16 v[32:35], v[140:143], v[240:243], v[32:35]
	v_mfma_f32_16x16x32_bf16 v[28:31], v[144:147], v[236:239], v[28:31]
	v_mfma_f32_16x16x32_bf16 v[28:31], v[172:175], v[240:243], v[28:31]
	s_setprio 0
	s_setprio 1
	v_mfma_f32_16x16x32_bf16 v[120:123], v[176:179], v[212:215], v[120:123]
	v_mfma_f32_16x16x32_bf16 v[120:123], v[180:183], v[216:219], v[120:123]
	v_mfma_f32_16x16x32_bf16 v[116:119], v[184:187], v[212:215], v[116:119]
	v_mfma_f32_16x16x32_bf16 v[116:119], v[208:211], v[216:219], v[116:119]
	v_mfma_f32_16x16x32_bf16 v[84:87], v[176:179], v[220:223], v[84:87]
	v_mfma_f32_16x16x32_bf16 v[84:87], v[180:183], v[224:227], v[84:87]
	v_mfma_f32_16x16x32_bf16 v[80:83], v[184:187], v[220:223], v[80:83]
	v_mfma_f32_16x16x32_bf16 v[80:83], v[208:211], v[224:227], v[80:83]
	v_mfma_f32_16x16x32_bf16 v[48:51], v[176:179], v[228:231], v[48:51]
	v_mfma_f32_16x16x32_bf16 v[48:51], v[180:183], v[232:235], v[48:51]
	v_mfma_f32_16x16x32_bf16 v[44:47], v[184:187], v[228:231], v[44:47]
	v_mfma_f32_16x16x32_bf16 v[44:47], v[208:211], v[232:235], v[44:47]
	v_mfma_f32_16x16x32_bf16 v[24:27], v[176:179], v[236:239], v[24:27]
	v_mfma_f32_16x16x32_bf16 v[24:27], v[180:183], v[240:243], v[24:27]
	v_mfma_f32_16x16x32_bf16 v[20:23], v[184:187], v[236:239], v[20:23]
	v_mfma_f32_16x16x32_bf16 v[20:23], v[208:211], v[240:243], v[20:23]
	s_setprio 0
	s_barrier
	s_add_i32 s18, s18, 2
	s_cmpk_gt_u32 s18, 0x55
	s_mov_b64 s[10:11], vcc
	s_cbranch_scc0 .LBB0_1111
